# instruction selection: integer RNE f32->bf16 bit trick replaced by v_cvt_pk_bf16_f32 in prologue/conv/combine where no hazard-sensitive neighbour exists (159 sites)
# speedup vs baseline: 1.0052x; 1.0010x over previous
; #define GAS __attribute__((address_space(1)))
; #define LAS __attribute__((address_space(3)))
; __device__ __forceinline__ unsigned pk2(float lo, float hi) { return f2bf(lo) | (f2bf(hi) << 16); }
; __device__ __forceinline__ void transpose_item(const float* W, int K, int N, bf16* WT, int mode, const float* gain, LAS float* scr, int item, int lane) {
;     ...
;     const int c = lane & 7;
; #pragma unroll
;     for (int j = 0; j < 4; ++j) { const int n = (lane >> 3) + 8 * j; const LAS float* s = scr + (8 * c) * 33 + n;
;         v4u o; o.x = pk2(s[0 * 33], s[1 * 33]); o.y = pk2(s[2 * 33], s[3 * 33]); o.z = pk2(s[4 * 33], s[5 * 33]); o.w = pk2(s[6 * 33], s[7 * 33]);
;         const int p_ = dst_row(mode, n0 + n), pl_ = p_ & 127, x_ = pl_ & 31, R_ = (pl_ & ~31) + 16 * ((x_ >> 2) & 1) + 4 * (x_ >> 3) + (x_ & 3);
;         *(GAS v4u*)((GAS unsigned char*)WT + ((size_t)(p_ >> 7) * (K / 64) + (k0 >> 6)) * 16384 + pg8::lds_byte(R_, 8 * c)) = o; }
.LBB0_22:
	s_waitcnt vmcnt(0)
	ds_write_b32 v2, v32 offset:1848
	s_waitcnt lgkmcnt(0)
	ds_read2_b32 v[108:109], v67 offset1:8
	ds_read2_b32 v[110:111], v67 offset0:33 offset1:41
	ds_read2_b32 v[112:113], v67 offset0:66 offset1:74
	ds_read2_b32 v[114:115], v67 offset0:99 offset1:107
	ds_read2_b32 v[116:117], v67 offset0:132 offset1:140
	s_waitcnt lgkmcnt(4)
	s_waitcnt lgkmcnt(3)
	ds_read2_b32 v[118:119], v67 offset0:165 offset1:173
	v_cvt_pk_bf16_f32 v32, v108, v110
	s_waitcnt lgkmcnt(3)
	s_waitcnt lgkmcnt(2)
	ds_read2_b32 v[120:121], v67 offset0:198 offset1:206
	ds_read2_b32 v[122:123], v67 offset0:231 offset1:239
	v_cvt_pk_bf16_f32 v33, v112, v114
	s_waitcnt lgkmcnt(3)
	s_lshl_b32 s3, s60, 8
	s_waitcnt lgkmcnt(2)
	s_sub_i32 s3, s13, s3
	s_and_b32 s2, s96, 0x700
	s_and_b32 s3, s3, 0xffffff80
	v_cvt_pk_bf16_f32 v34, v116, v118
	s_waitcnt lgkmcnt(1)
	s_add_i32 s2, s2, s3
	s_waitcnt lgkmcnt(0)
	s_and_b32 s3, s74, 0x60
	s_ashr_i32 s2, s2, 7
	s_ashr_i32 s61, s60, 31
	v_cvt_pk_bf16_f32 v35, v120, v122
	v_and_or_b32 v2, v66, 16, s3
	s_ashr_i32 s3, s2, 31
	s_lshl_b64 s[2:3], s[2:3], 18
	s_lshl_b64 s[18:19], s[60:61], 14
	s_add_u32 s2, s94, s2
	v_lshrrev_b32_e32 v2, 3, v2
	s_addc_u32 s3, s95, s3
	v_or_b32_e32 v2, v2, v64
	s_add_u32 s2, s2, s18
	v_lshlrev_b32_e32 v2, 10, v2
	s_addc_u32 s3, s3, s19
	v_or_b32_e32 v124, v2, v68
	global_store_dwordx4 v124, v[32:35], s[2:3]
	v_bfe_u32 v108, v123, 16, 1
	v_add3_u32 v110, v123, v108, s33
	v_bfe_u32 v32, v109, 16, 1
	v_add3_u32 v32, v109, v32, s33
	v_bfe_u32 v33, v111, 16, 1
	v_lshrrev_b32_e32 v32, 16, v32
	v_add3_u32 v33, v111, v33, s33
	v_and_or_b32 v32, v33, s86, v32
	v_cvt_pk_bf16_f32 v33, v113, v115
	v_cvt_pk_bf16_f32 v34, v117, v119
	v_bfe_u32 v35, v121, 16, 1
	v_add3_u32 v35, v121, v35, s33
	v_lshrrev_b32_e32 v35, 16, v35
	ds_read2_b32 v[108:109], v67 offset0:16 offset1:24
	v_and_or_b32 v35, v110, s86, v35
	ds_read2_b32 v[110:111], v67 offset0:49 offset1:57
	ds_read2_b32 v[112:113], v67 offset0:82 offset1:90
	v_or_b32_e32 v2, v2, v69
	ds_read2_b32 v[114:115], v67 offset0:115 offset1:123
	global_store_dwordx4 v2, v[32:35], s[2:3]
	s_waitcnt lgkmcnt(3)
	v_bfe_u32 v2, v108, 16, 1
	v_add3_u32 v2, v108, v2, s33
	s_waitcnt lgkmcnt(2)
	v_bfe_u32 v32, v110, 16, 1
	ds_read2_b32 v[116:117], v67 offset0:148 offset1:156
	v_lshrrev_b32_e32 v2, 16, v2
	v_add3_u32 v32, v110, v32, s33
	ds_read2_b32 v[118:119], v67 offset0:181 offset1:189
	v_and_or_b32 v32, v32, s86, v2
	s_waitcnt lgkmcnt(3)
	s_waitcnt lgkmcnt(2)
	ds_read2_b32 v[120:121], v67 offset0:214 offset1:222
	ds_read2_b32 v[122:123], v67 offset0:247 offset1:255
	v_cvt_pk_bf16_f32 v33, v112, v114
	s_waitcnt lgkmcnt(3)
	s_waitcnt lgkmcnt(2)
	v_cvt_pk_bf16_f32 v34, v116, v118
	s_waitcnt lgkmcnt(1)
	v_bfe_u32 v2, v120, 16, 1
	v_add3_u32 v2, v120, v2, s33
	s_waitcnt lgkmcnt(0)
	v_bfe_u32 v35, v122, 16, 1
	v_lshrrev_b32_e32 v2, 16, v2
	v_add3_u32 v35, v122, v35, s33
	v_and_or_b32 v35, v35, s86, v2
	v_xor_b32_e32 v2, 32, v124
	v_lshl_add_u64 v[124:125], s[2:3], 0, v[2:3]
	global_store_dwordx4 v[124:125], v[32:35], off offset:512
	v_bfe_u32 v2, v111, 16, 1
	v_add3_u32 v2, v111, v2, s33
	v_bfe_u32 v32, v109, 16, 1
	v_add3_u32 v32, v109, v32, s33
	v_lshrrev_b32_e32 v32, 16, v32
	v_and_or_b32 v32, v2, s86, v32
	v_cvt_pk_bf16_f32 v33, v113, v115
	v_bfe_u32 v35, v121, 16, 1
	v_cvt_pk_bf16_f32 v34, v117, v119
	v_bfe_u32 v2, v123, 16, 1
	v_add3_u32 v35, v121, v35, s33
	v_add3_u32 v2, v123, v2, s33
	v_lshrrev_b32_e32 v35, 16, v35
	v_and_or_b32 v35, v2, s86, v35
	global_store_dwordx4 v[124:125], v[32:35], off offset:768
	s_waitcnt lgkmcnt(0)

; #define LAS __attribute__((address_space(3)))
; #define LDS_WAIT() asm volatile("s_waitcnt lgkmcnt(0)" ::: "memory")
; #define TR(cnt, W, K_, N_, DST, MODE, GAIN) if (r < (cnt)) { transpose_item((W), (K_), (N_), (bf16*)(ws + (DST)), (MODE), (GAIN), scr, r, lane); continue; } r -= (cnt);
; __device__ __forceinline__ void transpose_item(const float* W, int K, int N, bf16* WT, int mode, const float* gain, LAS float* scr, int item, int lane) {
;     const int nblk = N / 32, kb = item / nblk, nb = item % nblk, k0 = 64 * kb, n0 = 32 * nb;
; #pragma unroll
;     for (int i = 0; i < 32; ++i) { const int kk = 2 * i + (lane >> 5); float w = W[(size_t)(k0 + kk) * N + n0 + (lane & 31)]; if (gain) w *= gain[k0 + kk]; scr[kk * 33 + (lane & 31)] = w; }
;     LDS_WAIT(); asm volatile("" ::: "memory");
; __device__ __forceinline__ void p0_prologue(const Args& a, LAS unsigned char* lds, int vcu, int G, int wave, int lane) {
;     ...
;     for (int it = gw; it < NITEMS; it += NGW) {
;         int r = it;
;     ...
;         TR(T_PW1, a.in[I_CW1], D, 2 * D, WS_WPW1, 3, a.in[I_CNG])
;         TR(T_SQ, a.in[I_CW2], D, D, WS_WPW2, 0, (const float*)nullptr)
;         TR(T_QKV, a.in[I_AWQKV], D, 3 * D, WS_WQKV, 4, a.in[I_ANG])
;         TR(T_SQ, a.in[I_AWO], D, D, WS_WO, 0, (const float*)nullptr)
;         TR(T_GU, a.in[I_FWG], D, DFF, WS_WGU0, 1, a.in[I_FNG])
;         TR(T_GU, a.in[I_FWU], D, DFF, WS_WGU0, 2, a.in[I_FNG])
;         TR(T_GU, a.in[I_FWG] + (size_t)D * DFF, D, DFF, WS_WGU1, 1, a.in[I_FNG] + D)
;         TR(T_GU, a.in[I_FWU] + (size_t)D * DFF, D, DFF, WS_WGU1, 2, a.in[I_FNG] + D)
;         TR(T_DN, a.in[I_FWD], DFF, D, WS_WD0, 0, (const float*)nullptr)
;         TR(T_DN, a.in[I_FWD] + (size_t)D * DFF, DFF, D, WS_WD1, 0, (const float*)nullptr)
;         TR(T_SQ, a.in[I_PWG], D, D, WS_WPG0, 0, a.in[I_PNG])
;         TR(T_SQ, a.in[I_PWG] + (size_t)D * D, D, D, WS_WPG1, 0, a.in[I_PNG] + D)
;         TR(T_PP, a.in[I_PWP], PLE, D, WS_WPP0, 0, (const float*)nullptr)
;         TR(T_PP, a.in[I_PWP] + (size_t)PLE * D, PLE, D, WS_WPP1, 0, (const float*)nullptr)
.LBB0_24:
	s_cmpk_gt_i32 s88, 0x3ff
	s_mov_b64 s[2:3], -1
	s_cbranch_scc0 .LBB0_330
	s_cmpk_gt_u32 s88, 0x5ff
	s_cbranch_scc0 .LBB0_327
	s_cmpk_gt_u32 s88, 0xbff
	s_cbranch_scc0 .LBB0_260
	s_cmpk_gt_u32 s88, 0xdff
	s_cbranch_scc0 .LBB0_257
	s_cmpk_gt_u32 s88, 0x137f
	s_cbranch_scc0 .LBB0_190
	s_cmpk_gt_u32 s88, 0x18ff
	s_cbranch_scc0 .LBB0_123
	s_cmpk_gt_u32 s88, 0x1e7f
	s_cbranch_scc0 .LBB0_120
	s_cmpk_gt_u32 s88, 0x23ff
	s_cbranch_scc0 .LBB0_117
	s_cmpk_gt_u32 s88, 0x297f
	s_cbranch_scc0 .LBB0_114
	s_cmpk_gt_u32 s88, 0x2eff
	s_cbranch_scc0 .LBB0_111
	s_cmpk_gt_u32 s88, 0x30ff
	s_cbranch_scc0 .LBB0_44
	s_cmpk_gt_u32 s88, 0x32ff
	s_cbranch_scc0 .LBB0_41
	s_bfe_u32 s18, s88, 0x30005
	s_cmpk_gt_u32 s88, 0x337f
	s_cbranch_scc0 .LBB0_38
	s_xor_b32 s2, s18, 4
	s_lshl_b32 s3, s2, 6
	s_and_b32 s19, s10, 0x3e0
	s_lshl_b32 s56, s19, 2
	v_or_b32_e32 v2, s3, v0
	v_lshl_add_u64 v[32:33], v[14:15], 0, s[56:57]
	v_lshlrev_b32_e32 v2, 12, v2
	v_lshl_add_u64 v[34:35], v[32:33], 0, v[2:3]
	v_or_b32_e32 v2, s3, v38
	v_lshlrev_b32_e32 v2, 12, v2
	global_load_dword v108, v[34:35], off
	v_lshl_add_u64 v[34:35], v[32:33], 0, v[2:3]
	v_or_b32_e32 v2, s3, v70
	v_lshlrev_b32_e32 v2, 12, v2
	global_load_dword v109, v[34:35], off
	v_lshl_add_u64 v[34:35], v[32:33], 0, v[2:3]
	v_or_b32_e32 v2, s3, v71
	v_lshlrev_b32_e32 v2, 12, v2
	global_load_dword v110, v[34:35], off
	v_lshl_add_u64 v[34:35], v[32:33], 0, v[2:3]
	v_or_b32_e32 v2, s3, v72
	v_lshlrev_b32_e32 v2, 12, v2
	global_load_dword v111, v[34:35], off
	v_lshl_add_u64 v[34:35], v[32:33], 0, v[2:3]
	v_or_b32_e32 v2, s3, v73
	v_lshlrev_b32_e32 v2, 12, v2
	global_load_dword v112, v[34:35], off
	v_lshl_add_u64 v[34:35], v[32:33], 0, v[2:3]
	v_or_b32_e32 v2, s3, v74
	v_lshlrev_b32_e32 v2, 12, v2
	global_load_dword v113, v[34:35], off
	v_lshl_add_u64 v[34:35], v[32:33], 0, v[2:3]
	v_or_b32_e32 v2, s3, v75
	v_lshlrev_b32_e32 v2, 12, v2
	global_load_dword v114, v[34:35], off
	v_lshl_add_u64 v[34:35], v[32:33], 0, v[2:3]
	v_or_b32_e32 v2, s3, v76
	v_lshlrev_b32_e32 v2, 12, v2
	global_load_dword v115, v[34:35], off
	v_lshl_add_u64 v[34:35], v[32:33], 0, v[2:3]
	v_or_b32_e32 v2, s3, v77
	v_lshlrev_b32_e32 v2, 12, v2
	global_load_dword v116, v[34:35], off
	v_lshl_add_u64 v[34:35], v[32:33], 0, v[2:3]
	v_or_b32_e32 v2, s3, v78
	v_lshlrev_b32_e32 v2, 12, v2
	global_load_dword v117, v[34:35], off
	v_lshl_add_u64 v[34:35], v[32:33], 0, v[2:3]
	v_or_b32_e32 v2, s3, v79
	v_lshlrev_b32_e32 v2, 12, v2
	global_load_dword v118, v[34:35], off
	v_lshl_add_u64 v[34:35], v[32:33], 0, v[2:3]
	v_or_b32_e32 v2, s3, v80
	v_lshlrev_b32_e32 v2, 12, v2
	global_load_dword v119, v[34:35], off
	v_lshl_add_u64 v[34:35], v[32:33], 0, v[2:3]
	v_or_b32_e32 v2, s3, v81
	v_lshlrev_b32_e32 v2, 12, v2
	global_load_dword v120, v[34:35], off
	v_lshl_add_u64 v[34:35], v[32:33], 0, v[2:3]
	v_or_b32_e32 v2, s3, v82
	v_lshlrev_b32_e32 v2, 12, v2
	global_load_dword v121, v[34:35], off
	v_lshl_add_u64 v[34:35], v[32:33], 0, v[2:3]
	v_or_b32_e32 v2, s3, v83
	v_lshlrev_b32_e32 v2, 12, v2
	global_load_dword v122, v[34:35], off
	v_lshl_add_u64 v[34:35], v[32:33], 0, v[2:3]
	v_or_b32_e32 v2, s3, v84
	v_lshlrev_b32_e32 v2, 12, v2
	global_load_dword v123, v[34:35], off
	v_lshl_add_u64 v[34:35], v[32:33], 0, v[2:3]
	v_or_b32_e32 v2, s3, v85
	v_lshlrev_b32_e32 v2, 12, v2
	global_load_dword v124, v[34:35], off
	v_lshl_add_u64 v[34:35], v[32:33], 0, v[2:3]
	v_or_b32_e32 v2, s3, v86
	v_lshlrev_b32_e32 v2, 12, v2
	global_load_dword v125, v[34:35], off
	v_lshl_add_u64 v[34:35], v[32:33], 0, v[2:3]
	v_or_b32_e32 v2, s3, v87
	v_lshlrev_b32_e32 v2, 12, v2
	global_load_dword v126, v[34:35], off
	v_lshl_add_u64 v[34:35], v[32:33], 0, v[2:3]
	v_or_b32_e32 v2, s3, v88
	v_lshlrev_b32_e32 v2, 12, v2
	global_load_dword v127, v[34:35], off
	v_lshl_add_u64 v[34:35], v[32:33], 0, v[2:3]
	v_or_b32_e32 v2, s3, v89
	v_lshlrev_b32_e32 v2, 12, v2
	global_load_dword v128, v[34:35], off
	v_lshl_add_u64 v[34:35], v[32:33], 0, v[2:3]
	v_or_b32_e32 v2, s3, v90
	v_lshlrev_b32_e32 v2, 12, v2
	global_load_dword v129, v[34:35], off
	v_lshl_add_u64 v[34:35], v[32:33], 0, v[2:3]
	v_or_b32_e32 v2, s3, v91
	v_lshlrev_b32_e32 v2, 12, v2
	global_load_dword v130, v[34:35], off
	v_lshl_add_u64 v[34:35], v[32:33], 0, v[2:3]
	v_or_b32_e32 v2, s3, v92
	v_lshlrev_b32_e32 v2, 12, v2
	global_load_dword v131, v[34:35], off
	v_lshl_add_u64 v[34:35], v[32:33], 0, v[2:3]
	v_or_b32_e32 v2, s3, v93
	v_lshlrev_b32_e32 v2, 12, v2
	global_load_dword v132, v[34:35], off
	v_lshl_add_u64 v[34:35], v[32:33], 0, v[2:3]
	v_or_b32_e32 v2, s3, v94
	v_lshlrev_b32_e32 v2, 12, v2
	global_load_dword v133, v[34:35], off
	v_lshl_add_u64 v[34:35], v[32:33], 0, v[2:3]
	v_or_b32_e32 v2, s3, v95
	v_lshlrev_b32_e32 v2, 12, v2
	global_load_dword v134, v[34:35], off
	v_lshl_add_u64 v[34:35], v[32:33], 0, v[2:3]
	v_or_b32_e32 v2, s3, v96
	v_lshlrev_b32_e32 v2, 12, v2
	global_load_dword v135, v[34:35], off
	v_lshl_add_u64 v[34:35], v[32:33], 0, v[2:3]
	v_or_b32_e32 v2, s3, v97
	v_lshlrev_b32_e32 v2, 12, v2
	global_load_dword v136, v[34:35], off
	v_lshl_add_u64 v[34:35], v[32:33], 0, v[2:3]
	v_or_b32_e32 v2, s3, v98
	v_lshlrev_b32_e32 v2, 12, v2
	global_load_dword v137, v[34:35], off
	v_lshl_add_u64 v[34:35], v[32:33], 0, v[2:3]
	v_or_b32_e32 v2, s3, v99
	v_lshlrev_b32_e32 v2, 12, v2
	v_lshl_add_u64 v[32:33], v[32:33], 0, v[2:3]
	global_load_dword v34, v[34:35], off
	s_and_b32 s3, s10, 0x60
	global_load_dword v2, v[32:33], off
	v_add_u32_e32 v32, v36, v37
	s_waitcnt vmcnt(30)
	ds_write2_b32 v32, v108, v109 offset1:66
	s_waitcnt vmcnt(28)
	ds_write2_b32 v32, v110, v111 offset0:132 offset1:198
	v_add_u32_e32 v32, 0x400, v32
	s_waitcnt vmcnt(26)
; #define GAS __attribute__((address_space(1)))
; #define LAS __attribute__((address_space(3)))
; #define LDS_WAIT() asm volatile("s_waitcnt lgkmcnt(0)" ::: "memory")
; __device__ __forceinline__ unsigned pk2(float lo, float hi) { return f2bf(lo) | (f2bf(hi) << 16); }
; __device__ __forceinline__ void transpose_item(const float* W, int K, int N, bf16* WT, int mode, const float* gain, LAS float* scr, int item, int lane) {
;     ...
;     for (int i = 0; i < 32; ++i) { const int kk = 2 * i + (lane >> 5); float w = W[(size_t)(k0 + kk) * N + n0 + (lane & 31)]; if (gain) w *= gain[k0 + kk]; scr[kk * 33 + (lane & 31)] = w; }
;     LDS_WAIT(); asm volatile("" ::: "memory");
;     const int c = lane & 7;
; #pragma unroll
;     for (int j = 0; j < 4; ++j) { const int n = (lane >> 3) + 8 * j; const LAS float* s = scr + (8 * c) * 33 + n;
;         v4u o; o.x = pk2(s[0 * 33], s[1 * 33]); o.y = pk2(s[2 * 33], s[3 * 33]); o.z = pk2(s[4 * 33], s[5 * 33]); o.w = pk2(s[6 * 33], s[7 * 33]);
;         const int p_ = dst_row(mode, n0 + n), pl_ = p_ & 127, x_ = pl_ & 31, R_ = (pl_ & ~31) + 16 * ((x_ >> 2) & 1) + 4 * (x_ >> 3) + (x_ & 3);
;         *(GAS v4u*)((GAS unsigned char*)WT + ((size_t)(p_ >> 7) * (K / 64) + (k0 >> 6)) * 16384 + pg8::lds_byte(R_, 8 * c)) = o; }
	ds_write2_b32 v32, v112, v113 offset0:8 offset1:74
	v_add_u32_e32 v32, v36, v44
	s_waitcnt vmcnt(24)
	ds_write2_b32 v32, v114, v115 offset1:66
	s_waitcnt vmcnt(22)
	ds_write2_b32 v32, v116, v117 offset0:132 offset1:198
	v_add_u32_e32 v32, 0x400, v32
	s_waitcnt vmcnt(20)
	ds_write2_b32 v32, v118, v119 offset0:8 offset1:74
	v_add_u32_e32 v32, v36, v50
	s_waitcnt vmcnt(18)
	ds_write2_b32 v32, v120, v121 offset1:66
	s_waitcnt vmcnt(16)
	ds_write2_b32 v32, v122, v123 offset0:132 offset1:198
	v_add_u32_e32 v32, 0x400, v32
	s_waitcnt vmcnt(14)
	ds_write2_b32 v32, v124, v125 offset0:8 offset1:74
	v_add_u32_e32 v32, v36, v56
	s_waitcnt vmcnt(12)
	ds_write2_b32 v32, v126, v127 offset1:66
	s_waitcnt vmcnt(10)
	ds_write2_b32 v32, v128, v129 offset0:132 offset1:198
	v_add_u32_e32 v32, 0x400, v32
	s_waitcnt vmcnt(8)
	ds_write2_b32 v32, v130, v131 offset0:8 offset1:74
	v_add_u32_e32 v32, v36, v62
	s_waitcnt vmcnt(6)
	ds_write2_b32 v32, v132, v133 offset1:66
	s_waitcnt vmcnt(4)
	ds_write2_b32 v32, v134, v135 offset0:132 offset1:198
	v_add_u32_e32 v32, 0x400, v32
	s_waitcnt vmcnt(2)
	ds_write2_b32 v32, v136, v137 offset0:8 offset1:74
	s_waitcnt vmcnt(0)
	ds_write2_b32 v32, v34, v2 offset0:140 offset1:206
	s_waitcnt lgkmcnt(0)
	ds_read2_b32 v[108:109], v67 offset1:8
	ds_read2_b32 v[110:111], v67 offset0:33 offset1:41
	ds_read2_b32 v[112:113], v67 offset0:66 offset1:74
	ds_read2_b32 v[114:115], v67 offset0:99 offset1:107
	ds_read2_b32 v[116:117], v67 offset0:132 offset1:140
	s_waitcnt lgkmcnt(4)
	s_waitcnt lgkmcnt(3)
	ds_read2_b32 v[118:119], v67 offset0:165 offset1:173
	v_cvt_pk_bf16_f32 v32, v108, v110
	s_waitcnt lgkmcnt(3)
	s_waitcnt lgkmcnt(2)
	ds_read2_b32 v[120:121], v67 offset0:198 offset1:206
	ds_read2_b32 v[122:123], v67 offset0:231 offset1:239
	v_cvt_pk_bf16_f32 v33, v112, v114
	s_waitcnt lgkmcnt(3)
	s_waitcnt lgkmcnt(2)
	v_cvt_pk_bf16_f32 v34, v116, v118
	s_waitcnt lgkmcnt(1)
	s_waitcnt lgkmcnt(0)
	v_cvt_pk_bf16_f32 v35, v120, v122
	v_or_b32_e32 v2, s3, v100
	s_and_b32 s3, s88, 28
	s_add_i32 s2, s2, s3
	v_lshrrev_b32_e32 v2, 3, v2
	s_lshl_b32 s2, s2, 14
	v_readlane_b32 s3, v255, 60
	v_or_b32_e32 v2, v2, v64
	s_add_u32 s2, s3, s2
	v_readlane_b32 s3, v255, 61
	v_lshlrev_b32_e32 v2, 10, v2
	s_addc_u32 s3, s3, 0
	v_or_b32_e32 v124, v2, v68
	v_bfe_u32 v108, v123, 16, 1
	v_add3_u32 v110, v123, v108, s33
	global_store_dwordx4 v124, v[32:35], s[2:3]
	v_or_b32_e32 v2, v2, v69
	ds_read2_b32 v[122:123], v67 offset0:247 offset1:255
	v_bfe_u32 v32, v109, 16, 1
	v_add3_u32 v32, v109, v32, s33
	v_bfe_u32 v33, v111, 16, 1
	v_lshrrev_b32_e32 v32, 16, v32
	v_add3_u32 v33, v111, v33, s33
	v_and_or_b32 v32, v33, s86, v32
	v_cvt_pk_bf16_f32 v33, v113, v115
	v_cvt_pk_bf16_f32 v34, v117, v119
	v_bfe_u32 v35, v121, 16, 1
	v_add3_u32 v35, v121, v35, s33
	v_lshrrev_b32_e32 v35, 16, v35
	ds_read2_b32 v[108:109], v67 offset0:16 offset1:24
	v_and_or_b32 v35, v110, s86, v35
	ds_read2_b32 v[110:111], v67 offset0:49 offset1:57
	ds_read2_b32 v[112:113], v67 offset0:82 offset1:90
	ds_read2_b32 v[114:115], v67 offset0:115 offset1:123
	global_store_dwordx4 v2, v[32:35], s[2:3]
	s_waitcnt lgkmcnt(3)
	v_bfe_u32 v2, v108, 16, 1
	v_add3_u32 v2, v108, v2, s33
	s_waitcnt lgkmcnt(2)
	v_bfe_u32 v32, v110, 16, 1
	ds_read2_b32 v[116:117], v67 offset0:148 offset1:156
	v_lshrrev_b32_e32 v2, 16, v2
	v_add3_u32 v32, v110, v32, s33
	ds_read2_b32 v[118:119], v67 offset0:181 offset1:189
	v_and_or_b32 v32, v32, s86, v2
	s_waitcnt lgkmcnt(3)
	s_waitcnt lgkmcnt(2)
	ds_read2_b32 v[120:121], v67 offset0:214 offset1:222
	v_cvt_pk_bf16_f32 v33, v112, v114
	s_waitcnt lgkmcnt(2)
	s_waitcnt lgkmcnt(1)
	v_cvt_pk_bf16_f32 v34, v116, v118
	s_waitcnt lgkmcnt(0)
	v_bfe_u32 v2, v120, 16, 1
	v_add3_u32 v2, v120, v2, s33
	v_bfe_u32 v35, v122, 16, 1
	v_lshrrev_b32_e32 v2, 16, v2
	v_add3_u32 v35, v122, v35, s33
	v_and_or_b32 v35, v35, s86, v2
	v_xor_b32_e32 v2, 32, v124
	v_lshl_add_u64 v[124:125], s[2:3], 0, v[2:3]
	global_store_dwordx4 v[124:125], v[32:35], off offset:512
	v_bfe_u32 v2, v111, 16, 1
	v_add3_u32 v2, v111, v2, s33
	v_bfe_u32 v32, v109, 16, 1
	v_add3_u32 v32, v109, v32, s33
	v_lshrrev_b32_e32 v32, 16, v32
	v_and_or_b32 v32, v2, s86, v32
	v_cvt_pk_bf16_f32 v33, v113, v115
	v_bfe_u32 v35, v121, 16, 1
	v_cvt_pk_bf16_f32 v34, v117, v119
	v_bfe_u32 v2, v123, 16, 1
	v_add3_u32 v35, v121, v35, s33
	v_add3_u32 v2, v123, v2, s33
	v_lshrrev_b32_e32 v35, 16, v35
	v_and_or_b32 v35, v2, s86, v35
	global_store_dwordx4 v[124:125], v[32:35], off offset:768
	s_waitcnt lgkmcnt(0)
	s_mov_b64 s[2:3], 0
; #define LAS __attribute__((address_space(3)))
; #define LDS_WAIT() asm volatile("s_waitcnt lgkmcnt(0)" ::: "memory")
; __device__ __forceinline__ void transpose_item(const float* W, int K, int N, bf16* WT, int mode, const float* gain, LAS float* scr, int item, int lane) {
;     const int nblk = N / 32, kb = item / nblk, nb = item % nblk, k0 = 64 * kb, n0 = 32 * nb;
; #pragma unroll
;     for (int i = 0; i < 32; ++i) { const int kk = 2 * i + (lane >> 5); float w = W[(size_t)(k0 + kk) * N + n0 + (lane & 31)]; if (gain) w *= gain[k0 + kk]; scr[kk * 33 + (lane & 31)] = w; }
;     LDS_WAIT(); asm volatile("" ::: "memory");
.LBB0_38:
	s_andn2_b64 vcc, exec, s[2:3]
	s_cbranch_vccnz .LBB0_40
	s_lshl_b32 s2, s18, 6
	s_and_b32 s3, s10, 0x3e0
	s_lshl_b32 s56, s3, 2
	v_or_b32_e32 v2, s2, v0
	v_lshl_add_u64 v[32:33], v[4:5], 0, s[56:57]
	v_lshlrev_b32_e32 v2, 12, v2
	v_lshl_add_u64 v[34:35], v[32:33], 0, v[2:3]
	v_or_b32_e32 v2, s2, v38
	v_lshlrev_b32_e32 v2, 12, v2
	global_load_dword v108, v[34:35], off
	v_lshl_add_u64 v[34:35], v[32:33], 0, v[2:3]
	v_or_b32_e32 v2, s2, v70
	v_lshlrev_b32_e32 v2, 12, v2
	global_load_dword v109, v[34:35], off
	v_lshl_add_u64 v[34:35], v[32:33], 0, v[2:3]
	v_or_b32_e32 v2, s2, v71
	v_lshlrev_b32_e32 v2, 12, v2
	global_load_dword v110, v[34:35], off
	v_lshl_add_u64 v[34:35], v[32:33], 0, v[2:3]
	v_or_b32_e32 v2, s2, v72
	v_lshlrev_b32_e32 v2, 12, v2
	global_load_dword v111, v[34:35], off
	v_lshl_add_u64 v[34:35], v[32:33], 0, v[2:3]
	v_or_b32_e32 v2, s2, v73
	v_lshlrev_b32_e32 v2, 12, v2
	global_load_dword v112, v[34:35], off
	v_lshl_add_u64 v[34:35], v[32:33], 0, v[2:3]
	v_or_b32_e32 v2, s2, v74
	v_lshlrev_b32_e32 v2, 12, v2
	global_load_dword v113, v[34:35], off
	v_lshl_add_u64 v[34:35], v[32:33], 0, v[2:3]
	v_or_b32_e32 v2, s2, v75
	v_lshlrev_b32_e32 v2, 12, v2
	global_load_dword v114, v[34:35], off
	v_lshl_add_u64 v[34:35], v[32:33], 0, v[2:3]
	v_or_b32_e32 v2, s2, v76
	v_lshlrev_b32_e32 v2, 12, v2
	global_load_dword v115, v[34:35], off
	v_lshl_add_u64 v[34:35], v[32:33], 0, v[2:3]
	v_or_b32_e32 v2, s2, v77
	v_lshlrev_b32_e32 v2, 12, v2
	global_load_dword v116, v[34:35], off
	v_lshl_add_u64 v[34:35], v[32:33], 0, v[2:3]
	v_or_b32_e32 v2, s2, v78
	v_lshlrev_b32_e32 v2, 12, v2
	global_load_dword v117, v[34:35], off
	v_lshl_add_u64 v[34:35], v[32:33], 0, v[2:3]
	v_or_b32_e32 v2, s2, v79
	v_lshlrev_b32_e32 v2, 12, v2
	global_load_dword v118, v[34:35], off
	v_lshl_add_u64 v[34:35], v[32:33], 0, v[2:3]
	v_or_b32_e32 v2, s2, v80
	v_lshlrev_b32_e32 v2, 12, v2
	global_load_dword v119, v[34:35], off
	v_lshl_add_u64 v[34:35], v[32:33], 0, v[2:3]
	v_or_b32_e32 v2, s2, v81
	v_lshlrev_b32_e32 v2, 12, v2
	global_load_dword v120, v[34:35], off
	v_lshl_add_u64 v[34:35], v[32:33], 0, v[2:3]
	v_or_b32_e32 v2, s2, v82
	v_lshlrev_b32_e32 v2, 12, v2
	global_load_dword v121, v[34:35], off
	v_lshl_add_u64 v[34:35], v[32:33], 0, v[2:3]
	v_or_b32_e32 v2, s2, v83
	v_lshlrev_b32_e32 v2, 12, v2
	global_load_dword v122, v[34:35], off
	v_lshl_add_u64 v[34:35], v[32:33], 0, v[2:3]
	v_or_b32_e32 v2, s2, v84
	v_lshlrev_b32_e32 v2, 12, v2
	global_load_dword v123, v[34:35], off
	v_lshl_add_u64 v[34:35], v[32:33], 0, v[2:3]
	v_or_b32_e32 v2, s2, v85
	v_lshlrev_b32_e32 v2, 12, v2
	global_load_dword v124, v[34:35], off
	v_lshl_add_u64 v[34:35], v[32:33], 0, v[2:3]
	v_or_b32_e32 v2, s2, v86
	v_lshlrev_b32_e32 v2, 12, v2
	global_load_dword v125, v[34:35], off
	v_lshl_add_u64 v[34:35], v[32:33], 0, v[2:3]
	v_or_b32_e32 v2, s2, v87
	v_lshlrev_b32_e32 v2, 12, v2
	global_load_dword v126, v[34:35], off
	v_lshl_add_u64 v[34:35], v[32:33], 0, v[2:3]
	v_or_b32_e32 v2, s2, v88
	v_lshlrev_b32_e32 v2, 12, v2
	global_load_dword v127, v[34:35], off
	v_lshl_add_u64 v[34:35], v[32:33], 0, v[2:3]
	v_or_b32_e32 v2, s2, v89
	v_lshlrev_b32_e32 v2, 12, v2
	global_load_dword v128, v[34:35], off
	v_lshl_add_u64 v[34:35], v[32:33], 0, v[2:3]
	v_or_b32_e32 v2, s2, v90
	v_lshlrev_b32_e32 v2, 12, v2
	global_load_dword v129, v[34:35], off
	v_lshl_add_u64 v[34:35], v[32:33], 0, v[2:3]
	v_or_b32_e32 v2, s2, v91
	v_lshlrev_b32_e32 v2, 12, v2
	global_load_dword v130, v[34:35], off
	v_lshl_add_u64 v[34:35], v[32:33], 0, v[2:3]
	v_or_b32_e32 v2, s2, v92
	v_lshlrev_b32_e32 v2, 12, v2
	global_load_dword v131, v[34:35], off
	v_lshl_add_u64 v[34:35], v[32:33], 0, v[2:3]
	v_or_b32_e32 v2, s2, v93
	v_lshlrev_b32_e32 v2, 12, v2
	global_load_dword v132, v[34:35], off
	v_lshl_add_u64 v[34:35], v[32:33], 0, v[2:3]
	v_or_b32_e32 v2, s2, v94
	v_lshlrev_b32_e32 v2, 12, v2
	global_load_dword v133, v[34:35], off
	v_lshl_add_u64 v[34:35], v[32:33], 0, v[2:3]
	v_or_b32_e32 v2, s2, v95
	v_lshlrev_b32_e32 v2, 12, v2
	global_load_dword v134, v[34:35], off
	v_lshl_add_u64 v[34:35], v[32:33], 0, v[2:3]
	v_or_b32_e32 v2, s2, v96
	v_lshlrev_b32_e32 v2, 12, v2
	global_load_dword v135, v[34:35], off
	v_lshl_add_u64 v[34:35], v[32:33], 0, v[2:3]
	v_or_b32_e32 v2, s2, v97
	v_lshlrev_b32_e32 v2, 12, v2
	global_load_dword v136, v[34:35], off
	v_lshl_add_u64 v[34:35], v[32:33], 0, v[2:3]
	v_or_b32_e32 v2, s2, v98
	v_lshlrev_b32_e32 v2, 12, v2
	global_load_dword v137, v[34:35], off
	v_lshl_add_u64 v[34:35], v[32:33], 0, v[2:3]
	v_or_b32_e32 v2, s2, v99
	v_lshlrev_b32_e32 v2, 12, v2
	v_lshl_add_u64 v[32:33], v[32:33], 0, v[2:3]
	global_load_dword v34, v[34:35], off
	s_and_b32 s2, s10, 0x60
	global_load_dword v2, v[32:33], off
	v_add_u32_e32 v32, v36, v37
	s_waitcnt vmcnt(30)
; #define GAS __attribute__((address_space(1)))
; #define LAS __attribute__((address_space(3)))
; #define LDS_WAIT() asm volatile("s_waitcnt lgkmcnt(0)" ::: "memory")
; __device__ __forceinline__ unsigned pk2(float lo, float hi) { return f2bf(lo) | (f2bf(hi) << 16); }
; __device__ __forceinline__ void transpose_item(const float* W, int K, int N, bf16* WT, int mode, const float* gain, LAS float* scr, int item, int lane) {
;     ...
;     for (int i = 0; i < 32; ++i) { const int kk = 2 * i + (lane >> 5); float w = W[(size_t)(k0 + kk) * N + n0 + (lane & 31)]; if (gain) w *= gain[k0 + kk]; scr[kk * 33 + (lane & 31)] = w; }
;     LDS_WAIT(); asm volatile("" ::: "memory");
;     const int c = lane & 7;
; #pragma unroll
;     for (int j = 0; j < 4; ++j) { const int n = (lane >> 3) + 8 * j; const LAS float* s = scr + (8 * c) * 33 + n;
;         v4u o; o.x = pk2(s[0 * 33], s[1 * 33]); o.y = pk2(s[2 * 33], s[3 * 33]); o.z = pk2(s[4 * 33], s[5 * 33]); o.w = pk2(s[6 * 33], s[7 * 33]);
;         const int p_ = dst_row(mode, n0 + n), pl_ = p_ & 127, x_ = pl_ & 31, R_ = (pl_ & ~31) + 16 * ((x_ >> 2) & 1) + 4 * (x_ >> 3) + (x_ & 3);
;         *(GAS v4u*)((GAS unsigned char*)WT + ((size_t)(p_ >> 7) * (K / 64) + (k0 >> 6)) * 16384 + pg8::lds_byte(R_, 8 * c)) = o; }
	ds_write2_b32 v32, v108, v109 offset1:66
	s_waitcnt vmcnt(28)
	ds_write2_b32 v32, v110, v111 offset0:132 offset1:198
	v_add_u32_e32 v32, 0x400, v32
	s_waitcnt vmcnt(26)
	ds_write2_b32 v32, v112, v113 offset0:8 offset1:74
	v_add_u32_e32 v32, v36, v44
	s_waitcnt vmcnt(24)
	ds_write2_b32 v32, v114, v115 offset1:66
	s_waitcnt vmcnt(22)
	ds_write2_b32 v32, v116, v117 offset0:132 offset1:198
	v_add_u32_e32 v32, 0x400, v32
	s_waitcnt vmcnt(20)
	ds_write2_b32 v32, v118, v119 offset0:8 offset1:74
	v_add_u32_e32 v32, v36, v50
	s_waitcnt vmcnt(18)
	ds_write2_b32 v32, v120, v121 offset1:66
	s_waitcnt vmcnt(16)
	ds_write2_b32 v32, v122, v123 offset0:132 offset1:198
	v_add_u32_e32 v32, 0x400, v32
	s_waitcnt vmcnt(14)
	ds_write2_b32 v32, v124, v125 offset0:8 offset1:74
	v_add_u32_e32 v32, v36, v56
	s_waitcnt vmcnt(12)
	ds_write2_b32 v32, v126, v127 offset1:66
	s_waitcnt vmcnt(10)
	ds_write2_b32 v32, v128, v129 offset0:132 offset1:198
	v_add_u32_e32 v32, 0x400, v32
	s_waitcnt vmcnt(8)
	ds_write2_b32 v32, v130, v131 offset0:8 offset1:74
	v_add_u32_e32 v32, v36, v62
	s_waitcnt vmcnt(6)
	ds_write2_b32 v32, v132, v133 offset1:66
	s_waitcnt vmcnt(4)
	ds_write2_b32 v32, v134, v135 offset0:132 offset1:198
	v_add_u32_e32 v32, 0x400, v32
	s_waitcnt vmcnt(2)
	ds_write2_b32 v32, v136, v137 offset0:8 offset1:74
	s_waitcnt vmcnt(0)
	ds_write2_b32 v32, v34, v2 offset0:140 offset1:206
	s_waitcnt lgkmcnt(0)
	ds_read2_b32 v[108:109], v67 offset1:8
	ds_read2_b32 v[110:111], v67 offset0:33 offset1:41
	ds_read2_b32 v[112:113], v67 offset0:66 offset1:74
	ds_read2_b32 v[114:115], v67 offset0:99 offset1:107
	ds_read2_b32 v[116:117], v67 offset0:132 offset1:140
	s_waitcnt lgkmcnt(4)
	s_waitcnt lgkmcnt(3)
	ds_read2_b32 v[118:119], v67 offset0:165 offset1:173
	v_cvt_pk_bf16_f32 v32, v108, v110
	s_waitcnt lgkmcnt(3)
	s_waitcnt lgkmcnt(2)
	ds_read2_b32 v[120:121], v67 offset0:198 offset1:206
	ds_read2_b32 v[122:123], v67 offset0:231 offset1:239
	v_cvt_pk_bf16_f32 v33, v112, v114
	s_waitcnt lgkmcnt(3)
	s_waitcnt lgkmcnt(2)
	v_cvt_pk_bf16_f32 v34, v116, v118
	s_waitcnt lgkmcnt(1)
	s_waitcnt lgkmcnt(0)
	v_cvt_pk_bf16_f32 v35, v120, v122
	v_or_b32_e32 v2, s2, v100
	s_and_b32 s2, s88, 28
	s_add_i32 s18, s18, s2
	v_lshrrev_b32_e32 v2, 3, v2
	s_lshl_b32 s2, s18, 14
	v_or_b32_e32 v2, v2, v64
	s_add_u32 s2, s80, s2
	v_lshlrev_b32_e32 v2, 10, v2
	s_addc_u32 s3, s81, 0
	v_or_b32_e32 v124, v2, v68
	global_store_dwordx4 v124, v[32:35], s[2:3]
	v_bfe_u32 v108, v123, 16, 1
	v_add3_u32 v110, v123, v108, s33
	v_bfe_u32 v32, v109, 16, 1
	v_add3_u32 v32, v109, v32, s33
	v_bfe_u32 v33, v111, 16, 1
	v_lshrrev_b32_e32 v32, 16, v32
	v_add3_u32 v33, v111, v33, s33
	v_and_or_b32 v32, v33, s86, v32
	v_cvt_pk_bf16_f32 v33, v113, v115
	v_cvt_pk_bf16_f32 v34, v117, v119
	v_bfe_u32 v35, v121, 16, 1
	v_add3_u32 v35, v121, v35, s33
	v_lshrrev_b32_e32 v35, 16, v35
	ds_read2_b32 v[108:109], v67 offset0:16 offset1:24
	v_and_or_b32 v35, v110, s86, v35
	ds_read2_b32 v[110:111], v67 offset0:49 offset1:57
	ds_read2_b32 v[112:113], v67 offset0:82 offset1:90
	v_or_b32_e32 v2, v2, v69
	ds_read2_b32 v[114:115], v67 offset0:115 offset1:123
	global_store_dwordx4 v2, v[32:35], s[2:3]
	s_waitcnt lgkmcnt(3)
	v_bfe_u32 v2, v108, 16, 1
	v_add3_u32 v2, v108, v2, s33
	s_waitcnt lgkmcnt(2)
	v_bfe_u32 v32, v110, 16, 1
	ds_read2_b32 v[116:117], v67 offset0:148 offset1:156
	v_lshrrev_b32_e32 v2, 16, v2
	v_add3_u32 v32, v110, v32, s33
	ds_read2_b32 v[118:119], v67 offset0:181 offset1:189
	v_and_or_b32 v32, v32, s86, v2
	s_waitcnt lgkmcnt(3)
	s_waitcnt lgkmcnt(2)
	ds_read2_b32 v[120:121], v67 offset0:214 offset1:222
	ds_read2_b32 v[122:123], v67 offset0:247 offset1:255
	v_cvt_pk_bf16_f32 v33, v112, v114
	s_waitcnt lgkmcnt(3)
	s_waitcnt lgkmcnt(2)
	v_cvt_pk_bf16_f32 v34, v116, v118
	s_waitcnt lgkmcnt(1)
	v_bfe_u32 v2, v120, 16, 1
	v_add3_u32 v2, v120, v2, s33
	s_waitcnt lgkmcnt(0)
	v_bfe_u32 v35, v122, 16, 1
	v_lshrrev_b32_e32 v2, 16, v2
	v_add3_u32 v35, v122, v35, s33
	v_and_or_b32 v35, v35, s86, v2
	v_xor_b32_e32 v2, 32, v124
	v_lshl_add_u64 v[124:125], s[2:3], 0, v[2:3]
	global_store_dwordx4 v[124:125], v[32:35], off offset:512
	v_bfe_u32 v2, v111, 16, 1
	v_add3_u32 v2, v111, v2, s33
	v_bfe_u32 v32, v109, 16, 1
	v_add3_u32 v32, v109, v32, s33
	v_lshrrev_b32_e32 v32, 16, v32
	v_and_or_b32 v32, v2, s86, v32
	v_cvt_pk_bf16_f32 v33, v113, v115
	v_bfe_u32 v35, v121, 16, 1
	v_cvt_pk_bf16_f32 v34, v117, v119
	v_bfe_u32 v2, v123, 16, 1
	v_add3_u32 v35, v121, v35, s33
	v_add3_u32 v2, v123, v2, s33
	v_lshrrev_b32_e32 v35, 16, v35
	v_and_or_b32 v35, v2, s86, v35
	global_store_dwordx4 v[124:125], v[32:35], off offset:768
	s_waitcnt lgkmcnt(0)

; #define LAS __attribute__((address_space(3)))
; #define LDS_WAIT() asm volatile("s_waitcnt lgkmcnt(0)" ::: "memory")
; #define TR(cnt, W, K_, N_, DST, MODE, GAIN) if (r < (cnt)) { transpose_item((W), (K_), (N_), (bf16*)(ws + (DST)), (MODE), (GAIN), scr, r, lane); continue; } r -= (cnt);
; __device__ __forceinline__ void transpose_item(const float* W, int K, int N, bf16* WT, int mode, const float* gain, LAS float* scr, int item, int lane) {
;     const int nblk = N / 32, kb = item / nblk, nb = item % nblk, k0 = 64 * kb, n0 = 32 * nb;
; #pragma unroll
;     for (int i = 0; i < 32; ++i) { const int kk = 2 * i + (lane >> 5); float w = W[(size_t)(k0 + kk) * N + n0 + (lane & 31)]; if (gain) w *= gain[k0 + kk]; scr[kk * 33 + (lane & 31)] = w; }
;     LDS_WAIT(); asm volatile("" ::: "memory");
; __device__ __forceinline__ void p0_prologue(const Args& a, LAS unsigned char* lds, int vcu, int G, int wave, int lane) {
;     ...
;         TR(T_SQ, a.in[I_PWG], D, D, WS_WPG0, 0, a.in[I_PNG])
;         TR(T_SQ, a.in[I_PWG] + (size_t)D * D, D, D, WS_WPG1, 0, a.in[I_PNG] + D)
.LBB0_41:
	s_andn2_b64 vcc, exec, s[2:3]
	s_cbranch_vccnz .LBB0_43
	s_add_i32 s2, s88, 0xcf00
	s_bfe_u32 s2, s2, 0xb0005
	s_lshl_b32 s3, s2, 6
	s_and_b32 s18, s10, 0x3e0
	s_lshl_b32 s56, s18, 2
	v_or_b32_e32 v108, s3, v0
	v_lshl_add_u64 v[32:33], v[16:17], 0, s[56:57]
	v_lshlrev_b32_e32 v2, 12, v108
	v_lshl_add_u64 v[34:35], v[32:33], 0, v[2:3]
	global_load_dword v2, v[34:35], off
	v_lshlrev_b32_e32 v34, 2, v108
	global_load_dword v34, v34, s[6:7]
	v_or_b32_e32 v110, s3, v38
	v_add_u32_e32 v109, v36, v37
	s_waitcnt vmcnt(0)
	v_mul_f32_e32 v108, v2, v34
	v_lshlrev_b32_e32 v2, 12, v110
	v_lshl_add_u64 v[34:35], v[32:33], 0, v[2:3]
	global_load_dword v2, v[34:35], off
	v_lshlrev_b32_e32 v34, 2, v110
	global_load_dword v34, v34, s[6:7]
	v_or_b32_e32 v110, s3, v71
	s_waitcnt vmcnt(0)
	v_mul_f32_e32 v2, v2, v34
	ds_write2_b32 v109, v108, v2 offset1:66
	v_or_b32_e32 v108, s3, v70
	v_lshlrev_b32_e32 v2, 12, v108
	v_lshl_add_u64 v[34:35], v[32:33], 0, v[2:3]
	global_load_dword v2, v[34:35], off
	v_lshlrev_b32_e32 v34, 2, v108
	global_load_dword v34, v34, s[6:7]
	s_waitcnt vmcnt(0)
	v_mul_f32_e32 v108, v2, v34
	v_lshlrev_b32_e32 v2, 12, v110
	v_lshl_add_u64 v[34:35], v[32:33], 0, v[2:3]
	global_load_dword v2, v[34:35], off
	v_lshlrev_b32_e32 v34, 2, v110
	global_load_dword v34, v34, s[6:7]
	v_or_b32_e32 v110, s3, v73
	s_waitcnt vmcnt(0)
	v_mul_f32_e32 v2, v2, v34
	ds_write2_b32 v109, v108, v2 offset0:132 offset1:198
	v_or_b32_e32 v108, s3, v72
	v_lshlrev_b32_e32 v2, 12, v108
	v_lshl_add_u64 v[34:35], v[32:33], 0, v[2:3]
	global_load_dword v2, v[34:35], off
	v_lshlrev_b32_e32 v34, 2, v108
	global_load_dword v34, v34, s[6:7]
	s_waitcnt vmcnt(0)
	v_mul_f32_e32 v108, v2, v34
	v_lshlrev_b32_e32 v2, 12, v110
	v_lshl_add_u64 v[34:35], v[32:33], 0, v[2:3]
	global_load_dword v2, v[34:35], off
	v_lshlrev_b32_e32 v34, 2, v110
	global_load_dword v34, v34, s[6:7]
	v_or_b32_e32 v110, s3, v75
	s_waitcnt vmcnt(0)
	v_mul_f32_e32 v2, v2, v34
	v_add_u32_e32 v34, 0x400, v109
	ds_write2_b32 v34, v108, v2 offset0:8 offset1:74
	v_or_b32_e32 v108, s3, v74
	v_lshlrev_b32_e32 v2, 12, v108
	v_lshl_add_u64 v[34:35], v[32:33], 0, v[2:3]
	global_load_dword v2, v[34:35], off
	v_lshlrev_b32_e32 v34, 2, v108
	global_load_dword v34, v34, s[6:7]
	v_add_u32_e32 v109, v36, v44
	s_waitcnt vmcnt(0)
	v_mul_f32_e32 v108, v2, v34
	v_lshlrev_b32_e32 v2, 12, v110
	v_lshl_add_u64 v[34:35], v[32:33], 0, v[2:3]
	global_load_dword v2, v[34:35], off
	v_lshlrev_b32_e32 v34, 2, v110
	global_load_dword v34, v34, s[6:7]
	v_or_b32_e32 v110, s3, v77
	s_waitcnt vmcnt(0)
	v_mul_f32_e32 v2, v2, v34
	ds_write2_b32 v109, v108, v2 offset1:66
	v_or_b32_e32 v108, s3, v76
	v_lshlrev_b32_e32 v2, 12, v108
	v_lshl_add_u64 v[34:35], v[32:33], 0, v[2:3]
	global_load_dword v2, v[34:35], off
	v_lshlrev_b32_e32 v34, 2, v108
	global_load_dword v34, v34, s[6:7]
	s_waitcnt vmcnt(0)
	v_mul_f32_e32 v108, v2, v34
	v_lshlrev_b32_e32 v2, 12, v110
	v_lshl_add_u64 v[34:35], v[32:33], 0, v[2:3]
	global_load_dword v2, v[34:35], off
	v_lshlrev_b32_e32 v34, 2, v110
	global_load_dword v34, v34, s[6:7]
	v_or_b32_e32 v110, s3, v79
	s_waitcnt vmcnt(0)
	v_mul_f32_e32 v2, v2, v34
	ds_write2_b32 v109, v108, v2 offset0:132 offset1:198
	v_or_b32_e32 v108, s3, v78
	v_lshlrev_b32_e32 v2, 12, v108
	v_lshl_add_u64 v[34:35], v[32:33], 0, v[2:3]
	global_load_dword v2, v[34:35], off
	v_lshlrev_b32_e32 v34, 2, v108
	global_load_dword v34, v34, s[6:7]
	s_waitcnt vmcnt(0)
	v_mul_f32_e32 v108, v2, v34
	v_lshlrev_b32_e32 v2, 12, v110
	v_lshl_add_u64 v[34:35], v[32:33], 0, v[2:3]
	global_load_dword v2, v[34:35], off
	v_lshlrev_b32_e32 v34, 2, v110
	global_load_dword v34, v34, s[6:7]
	v_or_b32_e32 v110, s3, v81
	s_waitcnt vmcnt(0)
	v_mul_f32_e32 v2, v2, v34
	v_add_u32_e32 v34, 0x400, v109
	ds_write2_b32 v34, v108, v2 offset0:8 offset1:74
	v_or_b32_e32 v108, s3, v80
	v_lshlrev_b32_e32 v2, 12, v108
	v_lshl_add_u64 v[34:35], v[32:33], 0, v[2:3]
	global_load_dword v2, v[34:35], off
	v_lshlrev_b32_e32 v34, 2, v108
	global_load_dword v34, v34, s[6:7]
	v_add_u32_e32 v109, v36, v50
	s_waitcnt vmcnt(0)
	v_mul_f32_e32 v108, v2, v34
	v_lshlrev_b32_e32 v2, 12, v110
	v_lshl_add_u64 v[34:35], v[32:33], 0, v[2:3]
	global_load_dword v2, v[34:35], off
	v_lshlrev_b32_e32 v34, 2, v110
	global_load_dword v34, v34, s[6:7]
	v_or_b32_e32 v110, s3, v83
	s_waitcnt vmcnt(0)
	v_mul_f32_e32 v2, v2, v34
	ds_write2_b32 v109, v108, v2 offset1:66
	v_or_b32_e32 v108, s3, v82
	v_lshlrev_b32_e32 v2, 12, v108
	v_lshl_add_u64 v[34:35], v[32:33], 0, v[2:3]
	global_load_dword v2, v[34:35], off
	v_lshlrev_b32_e32 v34, 2, v108
	global_load_dword v34, v34, s[6:7]
	s_waitcnt vmcnt(0)
	v_mul_f32_e32 v108, v2, v34
	v_lshlrev_b32_e32 v2, 12, v110
	v_lshl_add_u64 v[34:35], v[32:33], 0, v[2:3]
	global_load_dword v2, v[34:35], off
	v_lshlrev_b32_e32 v34, 2, v110
	global_load_dword v34, v34, s[6:7]
	v_or_b32_e32 v110, s3, v85
	s_waitcnt vmcnt(0)
	v_mul_f32_e32 v2, v2, v34
	ds_write2_b32 v109, v108, v2 offset0:132 offset1:198
	v_or_b32_e32 v108, s3, v84
	v_lshlrev_b32_e32 v2, 12, v108
	v_lshl_add_u64 v[34:35], v[32:33], 0, v[2:3]
	global_load_dword v2, v[34:35], off
	v_lshlrev_b32_e32 v34, 2, v108
	global_load_dword v34, v34, s[6:7]
	s_waitcnt vmcnt(0)
	v_mul_f32_e32 v108, v2, v34
	v_lshlrev_b32_e32 v2, 12, v110
	v_lshl_add_u64 v[34:35], v[32:33], 0, v[2:3]
	global_load_dword v2, v[34:35], off
	v_lshlrev_b32_e32 v34, 2, v110
	global_load_dword v34, v34, s[6:7]
	v_or_b32_e32 v110, s3, v87
	s_waitcnt vmcnt(0)
	v_mul_f32_e32 v2, v2, v34
	v_add_u32_e32 v34, 0x400, v109
	ds_write2_b32 v34, v108, v2 offset0:8 offset1:74
	v_or_b32_e32 v108, s3, v86
	v_lshlrev_b32_e32 v2, 12, v108
	v_lshl_add_u64 v[34:35], v[32:33], 0, v[2:3]
	global_load_dword v2, v[34:35], off
	v_lshlrev_b32_e32 v34, 2, v108
	global_load_dword v34, v34, s[6:7]
	v_add_u32_e32 v109, v36, v56
	s_waitcnt vmcnt(0)
; #define GAS __attribute__((address_space(1)))
; #define LAS __attribute__((address_space(3)))
; #define LDS_WAIT() asm volatile("s_waitcnt lgkmcnt(0)" ::: "memory")
; __device__ __forceinline__ unsigned pk2(float lo, float hi) { return f2bf(lo) | (f2bf(hi) << 16); }
; __device__ __forceinline__ void transpose_item(const float* W, int K, int N, bf16* WT, int mode, const float* gain, LAS float* scr, int item, int lane) {
;     ...
;     for (int i = 0; i < 32; ++i) { const int kk = 2 * i + (lane >> 5); float w = W[(size_t)(k0 + kk) * N + n0 + (lane & 31)]; if (gain) w *= gain[k0 + kk]; scr[kk * 33 + (lane & 31)] = w; }
;     LDS_WAIT(); asm volatile("" ::: "memory");
;     const int c = lane & 7;
; #pragma unroll
;     for (int j = 0; j < 4; ++j) { const int n = (lane >> 3) + 8 * j; const LAS float* s = scr + (8 * c) * 33 + n;
;         v4u o; o.x = pk2(s[0 * 33], s[1 * 33]); o.y = pk2(s[2 * 33], s[3 * 33]); o.z = pk2(s[4 * 33], s[5 * 33]); o.w = pk2(s[6 * 33], s[7 * 33]);
;         const int p_ = dst_row(mode, n0 + n), pl_ = p_ & 127, x_ = pl_ & 31, R_ = (pl_ & ~31) + 16 * ((x_ >> 2) & 1) + 4 * (x_ >> 3) + (x_ & 3);
;         *(GAS v4u*)((GAS unsigned char*)WT + ((size_t)(p_ >> 7) * (K / 64) + (k0 >> 6)) * 16384 + pg8::lds_byte(R_, 8 * c)) = o; }
	v_mul_f32_e32 v108, v2, v34
	v_lshlrev_b32_e32 v2, 12, v110
	v_lshl_add_u64 v[34:35], v[32:33], 0, v[2:3]
	global_load_dword v2, v[34:35], off
	v_lshlrev_b32_e32 v34, 2, v110
	global_load_dword v34, v34, s[6:7]
	v_or_b32_e32 v110, s3, v89
	s_waitcnt vmcnt(0)
	v_mul_f32_e32 v2, v2, v34
	ds_write2_b32 v109, v108, v2 offset1:66
	v_or_b32_e32 v108, s3, v88
	v_lshlrev_b32_e32 v2, 12, v108
	v_lshl_add_u64 v[34:35], v[32:33], 0, v[2:3]
	global_load_dword v2, v[34:35], off
	v_lshlrev_b32_e32 v34, 2, v108
	global_load_dword v34, v34, s[6:7]
	s_waitcnt vmcnt(0)
	v_mul_f32_e32 v108, v2, v34
	v_lshlrev_b32_e32 v2, 12, v110
	v_lshl_add_u64 v[34:35], v[32:33], 0, v[2:3]
	global_load_dword v2, v[34:35], off
	v_lshlrev_b32_e32 v34, 2, v110
	global_load_dword v34, v34, s[6:7]
	v_or_b32_e32 v110, s3, v91
	s_waitcnt vmcnt(0)
	v_mul_f32_e32 v2, v2, v34
	ds_write2_b32 v109, v108, v2 offset0:132 offset1:198
	v_or_b32_e32 v108, s3, v90
	v_lshlrev_b32_e32 v2, 12, v108
	v_lshl_add_u64 v[34:35], v[32:33], 0, v[2:3]
	global_load_dword v2, v[34:35], off
	v_lshlrev_b32_e32 v34, 2, v108
	global_load_dword v34, v34, s[6:7]
	s_waitcnt vmcnt(0)
	v_mul_f32_e32 v108, v2, v34
	v_lshlrev_b32_e32 v2, 12, v110
	v_lshl_add_u64 v[34:35], v[32:33], 0, v[2:3]
	global_load_dword v2, v[34:35], off
	v_lshlrev_b32_e32 v34, 2, v110
	global_load_dword v34, v34, s[6:7]
	v_or_b32_e32 v110, s3, v93
	s_waitcnt vmcnt(0)
	v_mul_f32_e32 v2, v2, v34
	v_add_u32_e32 v34, 0x400, v109
	ds_write2_b32 v34, v108, v2 offset0:8 offset1:74
	v_or_b32_e32 v108, s3, v92
	v_lshlrev_b32_e32 v2, 12, v108
	v_lshl_add_u64 v[34:35], v[32:33], 0, v[2:3]
	global_load_dword v2, v[34:35], off
	v_lshlrev_b32_e32 v34, 2, v108
	global_load_dword v34, v34, s[6:7]
	v_add_u32_e32 v109, v36, v62
	s_waitcnt vmcnt(0)
	v_mul_f32_e32 v108, v2, v34
	v_lshlrev_b32_e32 v2, 12, v110
	v_lshl_add_u64 v[34:35], v[32:33], 0, v[2:3]
	global_load_dword v2, v[34:35], off
	v_lshlrev_b32_e32 v34, 2, v110
	global_load_dword v34, v34, s[6:7]
	v_or_b32_e32 v110, s3, v95
	s_waitcnt vmcnt(0)
	v_mul_f32_e32 v2, v2, v34
	ds_write2_b32 v109, v108, v2 offset1:66
	v_or_b32_e32 v108, s3, v94
	v_lshlrev_b32_e32 v2, 12, v108
	v_lshl_add_u64 v[34:35], v[32:33], 0, v[2:3]
	global_load_dword v2, v[34:35], off
	v_lshlrev_b32_e32 v34, 2, v108
	global_load_dword v34, v34, s[6:7]
	s_waitcnt vmcnt(0)
	v_mul_f32_e32 v108, v2, v34
	v_lshlrev_b32_e32 v2, 12, v110
	v_lshl_add_u64 v[34:35], v[32:33], 0, v[2:3]
	global_load_dword v2, v[34:35], off
	v_lshlrev_b32_e32 v34, 2, v110
	global_load_dword v34, v34, s[6:7]
	v_or_b32_e32 v110, s3, v97
	s_waitcnt vmcnt(0)
	v_mul_f32_e32 v2, v2, v34
	ds_write2_b32 v109, v108, v2 offset0:132 offset1:198
	v_or_b32_e32 v108, s3, v96
	v_lshlrev_b32_e32 v2, 12, v108
	v_lshl_add_u64 v[34:35], v[32:33], 0, v[2:3]
	global_load_dword v2, v[34:35], off
	v_lshlrev_b32_e32 v34, 2, v108
	global_load_dword v34, v34, s[6:7]
	v_add_u32_e32 v109, 0x400, v109
	s_waitcnt vmcnt(0)
	v_mul_f32_e32 v108, v2, v34
	v_lshlrev_b32_e32 v2, 12, v110
	v_lshl_add_u64 v[34:35], v[32:33], 0, v[2:3]
	global_load_dword v2, v[34:35], off
	v_lshlrev_b32_e32 v34, 2, v110
	global_load_dword v34, v34, s[6:7]
	s_waitcnt vmcnt(0)
	v_mul_f32_e32 v2, v2, v34
	ds_write2_b32 v109, v108, v2 offset0:8 offset1:74
	v_or_b32_e32 v108, s3, v98
	v_lshlrev_b32_e32 v2, 12, v108
	v_lshl_add_u64 v[34:35], v[32:33], 0, v[2:3]
	global_load_dword v2, v[34:35], off
	v_lshlrev_b32_e32 v34, 2, v108
	global_load_dword v34, v34, s[6:7]
	v_or_b32_e32 v35, s3, v99
	s_and_b32 s3, s10, 0x60
	s_waitcnt vmcnt(0)
	v_mul_f32_e32 v34, v2, v34
	v_lshlrev_b32_e32 v2, 12, v35
	v_lshl_add_u64 v[32:33], v[32:33], 0, v[2:3]
	global_load_dword v2, v[32:33], off
	v_lshlrev_b32_e32 v32, 2, v35
	global_load_dword v32, v32, s[6:7]
	s_waitcnt vmcnt(0)
	v_mul_f32_e32 v2, v2, v32
	ds_write2_b32 v109, v34, v2 offset0:140 offset1:206
	s_waitcnt lgkmcnt(0)
	ds_read2_b32 v[108:109], v67 offset0:33 offset1:41
	ds_read2_b32 v[110:111], v67 offset1:8
	ds_read2_b32 v[112:113], v67 offset0:66 offset1:74
	ds_read2_b32 v[114:115], v67 offset0:99 offset1:107
	ds_read2_b32 v[116:117], v67 offset0:132 offset1:140
	ds_read2_b32 v[118:119], v67 offset0:165 offset1:173
	ds_read2_b32 v[120:121], v67 offset0:198 offset1:206
	ds_read2_b32 v[122:123], v67 offset0:231 offset1:239
	s_waitcnt lgkmcnt(7)
	s_waitcnt lgkmcnt(6)
	v_cvt_pk_bf16_f32 v32, v110, v108
	s_waitcnt lgkmcnt(5)
	s_waitcnt lgkmcnt(4)
	v_cvt_pk_bf16_f32 v33, v112, v114
	s_waitcnt lgkmcnt(3)
	s_waitcnt lgkmcnt(2)
	v_cvt_pk_bf16_f32 v34, v116, v118
	s_waitcnt lgkmcnt(1)
	s_waitcnt lgkmcnt(0)
	v_cvt_pk_bf16_f32 v35, v120, v122
	v_or_b32_e32 v2, s3, v100
	s_and_b32 s3, s13, 0x70
	s_add_i32 s2, s2, s3
	v_lshrrev_b32_e32 v2, 3, v2
	s_lshl_b32 s2, s2, 14
	v_or_b32_e32 v2, v2, v64
	s_add_u32 s2, s82, s2
	v_lshlrev_b32_e32 v2, 10, v2
	s_addc_u32 s3, s83, 0
	v_or_b32_e32 v124, v2, v68
	global_store_dwordx4 v124, v[32:35], s[2:3]
	v_bfe_u32 v108, v123, 16, 1
	v_add3_u32 v108, v123, v108, s33
	v_bfe_u32 v32, v111, 16, 1
	v_add3_u32 v32, v111, v32, s33
	v_bfe_u32 v33, v109, 16, 1
	v_lshrrev_b32_e32 v32, 16, v32
	v_add3_u32 v33, v109, v33, s33
	v_and_or_b32 v32, v33, s86, v32
	v_cvt_pk_bf16_f32 v33, v113, v115
	v_cvt_pk_bf16_f32 v34, v117, v119
	v_bfe_u32 v35, v121, 16, 1
	v_add3_u32 v35, v121, v35, s33
	v_lshrrev_b32_e32 v35, 16, v35
	v_and_or_b32 v35, v108, s86, v35
	v_or_b32_e32 v2, v2, v69
	global_store_dwordx4 v2, v[32:35], s[2:3]
	ds_read2_b32 v[108:109], v67 offset0:16 offset1:24
	ds_read2_b32 v[110:111], v67 offset0:49 offset1:57
	ds_read2_b32 v[112:113], v67 offset0:82 offset1:90
	ds_read2_b32 v[114:115], v67 offset0:115 offset1:123
	ds_read2_b32 v[116:117], v67 offset0:148 offset1:156
	ds_read2_b32 v[118:119], v67 offset0:181 offset1:189
	ds_read2_b32 v[120:121], v67 offset0:214 offset1:222
	ds_read2_b32 v[122:123], v67 offset0:247 offset1:255
	s_waitcnt lgkmcnt(7)
	s_waitcnt lgkmcnt(6)
	v_cvt_pk_bf16_f32 v32, v108, v110
	s_waitcnt lgkmcnt(5)
	s_waitcnt lgkmcnt(4)
	v_cvt_pk_bf16_f32 v33, v112, v114
	s_waitcnt lgkmcnt(3)
	s_waitcnt lgkmcnt(2)
	v_cvt_pk_bf16_f32 v34, v116, v118
	s_waitcnt lgkmcnt(1)
	v_bfe_u32 v2, v120, 16, 1
	v_add3_u32 v2, v120, v2, s33
	s_waitcnt lgkmcnt(0)
	v_bfe_u32 v35, v122, 16, 1
	v_lshrrev_b32_e32 v2, 16, v2
	v_add3_u32 v35, v122, v35, s33
	v_and_or_b32 v35, v35, s86, v2
	v_xor_b32_e32 v2, 32, v124
	v_lshl_add_u64 v[124:125], s[2:3], 0, v[2:3]
	global_store_dwordx4 v[124:125], v[32:35], off offset:512
	v_bfe_u32 v2, v111, 16, 1
	v_add3_u32 v2, v111, v2, s33
	v_bfe_u32 v32, v109, 16, 1
	v_add3_u32 v32, v109, v32, s33
	v_lshrrev_b32_e32 v32, 16, v32
	v_and_or_b32 v32, v2, s86, v32
	v_cvt_pk_bf16_f32 v33, v113, v115
	v_bfe_u32 v35, v121, 16, 1
	v_cvt_pk_bf16_f32 v34, v117, v119
	v_bfe_u32 v2, v123, 16, 1
	v_add3_u32 v35, v121, v35, s33
	v_add3_u32 v2, v123, v2, s33
	v_lshrrev_b32_e32 v35, 16, v35
	v_and_or_b32 v35, v2, s86, v35
	global_store_dwordx4 v[124:125], v[32:35], off offset:768
	s_waitcnt lgkmcnt(0)

; #define GAS __attribute__((address_space(1)))
; #define LAS __attribute__((address_space(3)))
; __device__ __forceinline__ unsigned pk2(float lo, float hi) { return f2bf(lo) | (f2bf(hi) << 16); }
; __device__ __forceinline__ void transpose_item(const float* W, int K, int N, bf16* WT, int mode, const float* gain, LAS float* scr, int item, int lane) {
;     ...
;     const int c = lane & 7;
; #pragma unroll
;     for (int j = 0; j < 4; ++j) { const int n = (lane >> 3) + 8 * j; const LAS float* s = scr + (8 * c) * 33 + n;
;         v4u o; o.x = pk2(s[0 * 33], s[1 * 33]); o.y = pk2(s[2 * 33], s[3 * 33]); o.z = pk2(s[4 * 33], s[5 * 33]); o.w = pk2(s[6 * 33], s[7 * 33]);
;         const int p_ = dst_row(mode, n0 + n), pl_ = p_ & 127, x_ = pl_ & 31, R_ = (pl_ & ~31) + 16 * ((x_ >> 2) & 1) + 4 * (x_ >> 3) + (x_ & 3);
;         *(GAS v4u*)((GAS unsigned char*)WT + ((size_t)(p_ >> 7) * (K / 64) + (k0 >> 6)) * 16384 + pg8::lds_byte(R_, 8 * c)) = o; }
.LBB0_109:
	s_waitcnt vmcnt(0)
	ds_write_b32 v35, v2 offset:1848
	s_waitcnt lgkmcnt(0)
	ds_read2_b32 v[108:109], v67 offset1:8
	ds_read2_b32 v[110:111], v67 offset0:33 offset1:41
	ds_read2_b32 v[112:113], v67 offset0:66 offset1:74
	ds_read2_b32 v[114:115], v67 offset0:99 offset1:107
	ds_read2_b32 v[116:117], v67 offset0:132 offset1:140
	s_waitcnt lgkmcnt(4)
	s_waitcnt lgkmcnt(3)
	ds_read2_b32 v[118:119], v67 offset0:165 offset1:173
	v_cvt_pk_bf16_f32 v32, v108, v110
	s_waitcnt lgkmcnt(3)
	s_waitcnt lgkmcnt(2)
	ds_read2_b32 v[120:121], v67 offset0:198 offset1:206
	ds_read2_b32 v[122:123], v67 offset0:231 offset1:239
	v_cvt_pk_bf16_f32 v33, v112, v114
	s_waitcnt lgkmcnt(3)
	s_waitcnt lgkmcnt(2)
	v_cvt_pk_bf16_f32 v34, v116, v118
	s_waitcnt lgkmcnt(1)
	s_waitcnt lgkmcnt(0)
	s_and_b32 s2, s10, 0x60
	v_cvt_pk_bf16_f32 v35, v120, v122
	v_or_b32_e32 v2, s2, v100
	s_and_b32 s2, s13, 0x70
	s_add_i32 s18, s18, s2
	v_lshrrev_b32_e32 v2, 3, v2
	s_lshl_b32 s2, s18, 14
	v_or_b32_e32 v2, v2, v64
	s_add_u32 s2, s92, s2
	v_readlane_b32 s3, v255, 62
	v_lshlrev_b32_e32 v2, 10, v2
	s_addc_u32 s3, s3, 0
	v_or_b32_e32 v124, v2, v68
	v_bfe_u32 v108, v123, 16, 1
	v_add3_u32 v110, v123, v108, s33
	global_store_dwordx4 v124, v[32:35], s[2:3]
	v_or_b32_e32 v2, v2, v69
	ds_read2_b32 v[122:123], v67 offset0:247 offset1:255
	v_bfe_u32 v32, v109, 16, 1
	v_add3_u32 v32, v109, v32, s33
	v_bfe_u32 v33, v111, 16, 1
	v_lshrrev_b32_e32 v32, 16, v32
	v_add3_u32 v33, v111, v33, s33
	v_and_or_b32 v32, v33, s86, v32
	v_cvt_pk_bf16_f32 v33, v113, v115
	v_cvt_pk_bf16_f32 v34, v117, v119
	v_bfe_u32 v35, v121, 16, 1
	v_add3_u32 v35, v121, v35, s33
	v_lshrrev_b32_e32 v35, 16, v35
	ds_read2_b32 v[108:109], v67 offset0:16 offset1:24
	v_and_or_b32 v35, v110, s86, v35
	ds_read2_b32 v[110:111], v67 offset0:49 offset1:57
	ds_read2_b32 v[112:113], v67 offset0:82 offset1:90
	ds_read2_b32 v[114:115], v67 offset0:115 offset1:123
	global_store_dwordx4 v2, v[32:35], s[2:3]
	s_waitcnt lgkmcnt(3)
	v_bfe_u32 v2, v108, 16, 1
	v_add3_u32 v2, v108, v2, s33
	s_waitcnt lgkmcnt(2)
	v_bfe_u32 v32, v110, 16, 1
	ds_read2_b32 v[116:117], v67 offset0:148 offset1:156
	v_lshrrev_b32_e32 v2, 16, v2
	v_add3_u32 v32, v110, v32, s33
	ds_read2_b32 v[118:119], v67 offset0:181 offset1:189
	v_and_or_b32 v32, v32, s86, v2
	s_waitcnt lgkmcnt(3)
	s_waitcnt lgkmcnt(2)
	ds_read2_b32 v[120:121], v67 offset0:214 offset1:222
	v_cvt_pk_bf16_f32 v33, v112, v114
	s_waitcnt lgkmcnt(2)
	s_waitcnt lgkmcnt(1)
	v_cvt_pk_bf16_f32 v34, v116, v118
	s_waitcnt lgkmcnt(0)
	v_bfe_u32 v2, v120, 16, 1
	v_add3_u32 v2, v120, v2, s33
	v_bfe_u32 v35, v122, 16, 1
	v_lshrrev_b32_e32 v2, 16, v2
	v_add3_u32 v35, v122, v35, s33
	v_and_or_b32 v35, v35, s86, v2
	v_xor_b32_e32 v2, 32, v124
	v_lshl_add_u64 v[124:125], s[2:3], 0, v[2:3]
	global_store_dwordx4 v[124:125], v[32:35], off offset:512
	v_bfe_u32 v2, v111, 16, 1
	v_add3_u32 v2, v111, v2, s33
	v_bfe_u32 v32, v109, 16, 1
	v_add3_u32 v32, v109, v32, s33
	v_lshrrev_b32_e32 v32, 16, v32
	v_and_or_b32 v32, v2, s86, v32
	v_cvt_pk_bf16_f32 v33, v113, v115
	v_bfe_u32 v35, v121, 16, 1
	v_cvt_pk_bf16_f32 v34, v117, v119
	v_bfe_u32 v2, v123, 16, 1
	v_add3_u32 v35, v121, v35, s33
	v_add3_u32 v2, v123, v2, s33
	v_lshrrev_b32_e32 v35, 16, v35
	v_and_or_b32 v35, v2, s86, v35
	global_store_dwordx4 v[124:125], v[32:35], off offset:768
	s_waitcnt lgkmcnt(0)

; #define LAS __attribute__((address_space(3)))
; #define LDS_WAIT() asm volatile("s_waitcnt lgkmcnt(0)" ::: "memory")
; __device__ __forceinline__ void transpose_item(const float* W, int K, int N, bf16* WT, int mode, const float* gain, LAS float* scr, int item, int lane) {
;     const int nblk = N / 32, kb = item / nblk, nb = item % nblk, k0 = 64 * kb, n0 = 32 * nb;
; #pragma unroll
;     for (int i = 0; i < 32; ++i) { const int kk = 2 * i + (lane >> 5); float w = W[(size_t)(k0 + kk) * N + n0 + (lane & 31)]; if (gain) w *= gain[k0 + kk]; scr[kk * 33 + (lane & 31)] = w; }
;     LDS_WAIT(); asm volatile("" ::: "memory");
.LBB0_111:
	s_andn2_b64 vcc, exec, s[2:3]
	s_cbranch_vccnz .LBB0_113
	s_add_i32 s2, s88, 0xd680
	s_bfe_u32 s2, s2, 0xb0005
	s_lshl_b32 s3, s2, 6
	s_and_b32 s18, s10, 0x3e0
	s_lshl_b32 s56, s18, 2
	v_or_b32_e32 v2, s3, v0
	v_lshl_add_u64 v[32:33], v[18:19], 0, s[56:57]
	v_lshlrev_b32_e32 v2, 12, v2
	v_lshl_add_u64 v[34:35], v[32:33], 0, v[2:3]
	v_or_b32_e32 v2, s3, v38
	v_lshlrev_b32_e32 v2, 12, v2
	global_load_dword v108, v[34:35], off
	v_lshl_add_u64 v[34:35], v[32:33], 0, v[2:3]
	v_or_b32_e32 v2, s3, v70
	v_lshlrev_b32_e32 v2, 12, v2
	global_load_dword v109, v[34:35], off
	v_lshl_add_u64 v[34:35], v[32:33], 0, v[2:3]
	v_or_b32_e32 v2, s3, v71
	v_lshlrev_b32_e32 v2, 12, v2
	global_load_dword v110, v[34:35], off
	v_lshl_add_u64 v[34:35], v[32:33], 0, v[2:3]
	v_or_b32_e32 v2, s3, v72
	v_lshlrev_b32_e32 v2, 12, v2
	global_load_dword v111, v[34:35], off
	v_lshl_add_u64 v[34:35], v[32:33], 0, v[2:3]
	v_or_b32_e32 v2, s3, v73
	v_lshlrev_b32_e32 v2, 12, v2
	global_load_dword v112, v[34:35], off
	v_lshl_add_u64 v[34:35], v[32:33], 0, v[2:3]
	v_or_b32_e32 v2, s3, v74
	v_lshlrev_b32_e32 v2, 12, v2
	global_load_dword v113, v[34:35], off
	v_lshl_add_u64 v[34:35], v[32:33], 0, v[2:3]
	v_or_b32_e32 v2, s3, v75
	v_lshlrev_b32_e32 v2, 12, v2
	global_load_dword v114, v[34:35], off
	v_lshl_add_u64 v[34:35], v[32:33], 0, v[2:3]
	v_or_b32_e32 v2, s3, v76
	v_lshlrev_b32_e32 v2, 12, v2
	global_load_dword v115, v[34:35], off
	v_lshl_add_u64 v[34:35], v[32:33], 0, v[2:3]
	v_or_b32_e32 v2, s3, v77
	v_lshlrev_b32_e32 v2, 12, v2
	global_load_dword v116, v[34:35], off
	v_lshl_add_u64 v[34:35], v[32:33], 0, v[2:3]
	v_or_b32_e32 v2, s3, v78
	v_lshlrev_b32_e32 v2, 12, v2
	global_load_dword v117, v[34:35], off
	v_lshl_add_u64 v[34:35], v[32:33], 0, v[2:3]
	v_or_b32_e32 v2, s3, v79
	v_lshlrev_b32_e32 v2, 12, v2
	global_load_dword v118, v[34:35], off
	v_lshl_add_u64 v[34:35], v[32:33], 0, v[2:3]
	v_or_b32_e32 v2, s3, v80
	v_lshlrev_b32_e32 v2, 12, v2
	global_load_dword v119, v[34:35], off
	v_lshl_add_u64 v[34:35], v[32:33], 0, v[2:3]
	v_or_b32_e32 v2, s3, v81
	v_lshlrev_b32_e32 v2, 12, v2
	global_load_dword v120, v[34:35], off
	v_lshl_add_u64 v[34:35], v[32:33], 0, v[2:3]
	v_or_b32_e32 v2, s3, v82
	v_lshlrev_b32_e32 v2, 12, v2
	global_load_dword v121, v[34:35], off
	v_lshl_add_u64 v[34:35], v[32:33], 0, v[2:3]
	v_or_b32_e32 v2, s3, v83
	v_lshlrev_b32_e32 v2, 12, v2
	global_load_dword v122, v[34:35], off
	v_lshl_add_u64 v[34:35], v[32:33], 0, v[2:3]
	v_or_b32_e32 v2, s3, v84
	v_lshlrev_b32_e32 v2, 12, v2
	global_load_dword v123, v[34:35], off
	v_lshl_add_u64 v[34:35], v[32:33], 0, v[2:3]
	v_or_b32_e32 v2, s3, v85
	v_lshlrev_b32_e32 v2, 12, v2
	global_load_dword v124, v[34:35], off
	v_lshl_add_u64 v[34:35], v[32:33], 0, v[2:3]
	v_or_b32_e32 v2, s3, v86
	v_lshlrev_b32_e32 v2, 12, v2
	global_load_dword v125, v[34:35], off
	v_lshl_add_u64 v[34:35], v[32:33], 0, v[2:3]
	v_or_b32_e32 v2, s3, v87
	v_lshlrev_b32_e32 v2, 12, v2
	global_load_dword v126, v[34:35], off
	v_lshl_add_u64 v[34:35], v[32:33], 0, v[2:3]
	v_or_b32_e32 v2, s3, v88
	v_lshlrev_b32_e32 v2, 12, v2
	global_load_dword v127, v[34:35], off
	v_lshl_add_u64 v[34:35], v[32:33], 0, v[2:3]
	v_or_b32_e32 v2, s3, v89
	v_lshlrev_b32_e32 v2, 12, v2
	global_load_dword v128, v[34:35], off
	v_lshl_add_u64 v[34:35], v[32:33], 0, v[2:3]
	v_or_b32_e32 v2, s3, v90
	v_lshlrev_b32_e32 v2, 12, v2
	global_load_dword v129, v[34:35], off
	v_lshl_add_u64 v[34:35], v[32:33], 0, v[2:3]
	v_or_b32_e32 v2, s3, v91
	v_lshlrev_b32_e32 v2, 12, v2
	global_load_dword v130, v[34:35], off
	v_lshl_add_u64 v[34:35], v[32:33], 0, v[2:3]
	v_or_b32_e32 v2, s3, v92
	v_lshlrev_b32_e32 v2, 12, v2
	global_load_dword v131, v[34:35], off
	v_lshl_add_u64 v[34:35], v[32:33], 0, v[2:3]
	v_or_b32_e32 v2, s3, v93
	v_lshlrev_b32_e32 v2, 12, v2
	global_load_dword v132, v[34:35], off
	v_lshl_add_u64 v[34:35], v[32:33], 0, v[2:3]
	v_or_b32_e32 v2, s3, v94
	v_lshlrev_b32_e32 v2, 12, v2
	global_load_dword v133, v[34:35], off
	v_lshl_add_u64 v[34:35], v[32:33], 0, v[2:3]
	v_or_b32_e32 v2, s3, v95
	v_lshlrev_b32_e32 v2, 12, v2
	global_load_dword v134, v[34:35], off
	v_lshl_add_u64 v[34:35], v[32:33], 0, v[2:3]
	v_or_b32_e32 v2, s3, v96
	v_lshlrev_b32_e32 v2, 12, v2
	global_load_dword v135, v[34:35], off
	v_lshl_add_u64 v[34:35], v[32:33], 0, v[2:3]
	v_or_b32_e32 v2, s3, v97
	v_lshlrev_b32_e32 v2, 12, v2
	global_load_dword v136, v[34:35], off
	v_lshl_add_u64 v[34:35], v[32:33], 0, v[2:3]
	v_or_b32_e32 v2, s3, v98
	v_lshlrev_b32_e32 v2, 12, v2
	global_load_dword v137, v[34:35], off
	v_lshl_add_u64 v[34:35], v[32:33], 0, v[2:3]
	v_or_b32_e32 v2, s3, v99
	v_lshlrev_b32_e32 v2, 12, v2
	v_lshl_add_u64 v[32:33], v[32:33], 0, v[2:3]
	global_load_dword v34, v[34:35], off
	s_and_b32 s3, s10, 0x60
	global_load_dword v2, v[32:33], off
	v_add_u32_e32 v32, v36, v37
	s_waitcnt vmcnt(30)
; #define GAS __attribute__((address_space(1)))
; #define LAS __attribute__((address_space(3)))
; #define LDS_WAIT() asm volatile("s_waitcnt lgkmcnt(0)" ::: "memory")
; __device__ __forceinline__ unsigned pk2(float lo, float hi) { return f2bf(lo) | (f2bf(hi) << 16); }
; __device__ __forceinline__ void transpose_item(const float* W, int K, int N, bf16* WT, int mode, const float* gain, LAS float* scr, int item, int lane) {
;     ...
;     for (int i = 0; i < 32; ++i) { const int kk = 2 * i + (lane >> 5); float w = W[(size_t)(k0 + kk) * N + n0 + (lane & 31)]; if (gain) w *= gain[k0 + kk]; scr[kk * 33 + (lane & 31)] = w; }
;     LDS_WAIT(); asm volatile("" ::: "memory");
;     const int c = lane & 7;
; #pragma unroll
;     for (int j = 0; j < 4; ++j) { const int n = (lane >> 3) + 8 * j; const LAS float* s = scr + (8 * c) * 33 + n;
;         v4u o; o.x = pk2(s[0 * 33], s[1 * 33]); o.y = pk2(s[2 * 33], s[3 * 33]); o.z = pk2(s[4 * 33], s[5 * 33]); o.w = pk2(s[6 * 33], s[7 * 33]);
;         const int p_ = dst_row(mode, n0 + n), pl_ = p_ & 127, x_ = pl_ & 31, R_ = (pl_ & ~31) + 16 * ((x_ >> 2) & 1) + 4 * (x_ >> 3) + (x_ & 3);
;         *(GAS v4u*)((GAS unsigned char*)WT + ((size_t)(p_ >> 7) * (K / 64) + (k0 >> 6)) * 16384 + pg8::lds_byte(R_, 8 * c)) = o; }
	ds_write2_b32 v32, v108, v109 offset1:66
	s_waitcnt vmcnt(28)
	ds_write2_b32 v32, v110, v111 offset0:132 offset1:198
	v_add_u32_e32 v32, 0x400, v32
	s_waitcnt vmcnt(26)
	ds_write2_b32 v32, v112, v113 offset0:8 offset1:74
	v_add_u32_e32 v32, v36, v44
	s_waitcnt vmcnt(24)
	ds_write2_b32 v32, v114, v115 offset1:66
	s_waitcnt vmcnt(22)
	ds_write2_b32 v32, v116, v117 offset0:132 offset1:198
	v_add_u32_e32 v32, 0x400, v32
	s_waitcnt vmcnt(20)
	ds_write2_b32 v32, v118, v119 offset0:8 offset1:74
	v_add_u32_e32 v32, v36, v50
	s_waitcnt vmcnt(18)
	ds_write2_b32 v32, v120, v121 offset1:66
	s_waitcnt vmcnt(16)
	ds_write2_b32 v32, v122, v123 offset0:132 offset1:198
	v_add_u32_e32 v32, 0x400, v32
	s_waitcnt vmcnt(14)
	ds_write2_b32 v32, v124, v125 offset0:8 offset1:74
	v_add_u32_e32 v32, v36, v56
	s_waitcnt vmcnt(12)
	ds_write2_b32 v32, v126, v127 offset1:66
	s_waitcnt vmcnt(10)
	ds_write2_b32 v32, v128, v129 offset0:132 offset1:198
	v_add_u32_e32 v32, 0x400, v32
	s_waitcnt vmcnt(8)
	ds_write2_b32 v32, v130, v131 offset0:8 offset1:74
	v_add_u32_e32 v32, v36, v62
	s_waitcnt vmcnt(6)
	ds_write2_b32 v32, v132, v133 offset1:66
	s_waitcnt vmcnt(4)
	ds_write2_b32 v32, v134, v135 offset0:132 offset1:198
	v_add_u32_e32 v32, 0x400, v32
	s_waitcnt vmcnt(2)
	ds_write2_b32 v32, v136, v137 offset0:8 offset1:74
	s_waitcnt vmcnt(0)
	ds_write2_b32 v32, v34, v2 offset0:140 offset1:206
	s_waitcnt lgkmcnt(0)
	ds_read2_b32 v[108:109], v67 offset1:8
	ds_read2_b32 v[110:111], v67 offset0:33 offset1:41
	ds_read2_b32 v[112:113], v67 offset0:66 offset1:74
	ds_read2_b32 v[114:115], v67 offset0:99 offset1:107
	ds_read2_b32 v[116:117], v67 offset0:132 offset1:140
	s_waitcnt lgkmcnt(4)
	s_waitcnt lgkmcnt(3)
	ds_read2_b32 v[118:119], v67 offset0:165 offset1:173
	v_cvt_pk_bf16_f32 v32, v108, v110
	s_waitcnt lgkmcnt(3)
	s_waitcnt lgkmcnt(2)
	ds_read2_b32 v[120:121], v67 offset0:198 offset1:206
	ds_read2_b32 v[122:123], v67 offset0:231 offset1:239
	v_cvt_pk_bf16_f32 v33, v112, v114
	s_waitcnt lgkmcnt(3)
	s_waitcnt lgkmcnt(2)
	v_cvt_pk_bf16_f32 v34, v116, v118
	s_waitcnt lgkmcnt(1)
	s_waitcnt lgkmcnt(0)
	v_cvt_pk_bf16_f32 v35, v120, v122
	v_or_b32_e32 v2, s3, v100
	s_bfe_u32 s3, s10, 0x30007
	s_mul_i32 s3, s3, 44
	s_add_i32 s3, s3, s2
	v_lshrrev_b32_e32 v2, 3, v2
	s_lshl_b32 s2, s3, 14
	v_readlane_b32 s3, v255, 63
	v_or_b32_e32 v2, v2, v64
	s_add_u32 s2, s3, s2
	v_readlane_b32 s3, v254, 0
	v_lshlrev_b32_e32 v2, 10, v2
	s_addc_u32 s3, s3, 0
	v_or_b32_e32 v124, v2, v68
	v_bfe_u32 v108, v123, 16, 1
	v_add3_u32 v110, v123, v108, s33
	global_store_dwordx4 v124, v[32:35], s[2:3]
	v_or_b32_e32 v2, v2, v69
	ds_read2_b32 v[122:123], v67 offset0:247 offset1:255
	v_bfe_u32 v32, v109, 16, 1
	v_add3_u32 v32, v109, v32, s33
	v_bfe_u32 v33, v111, 16, 1
	v_lshrrev_b32_e32 v32, 16, v32
	v_add3_u32 v33, v111, v33, s33
	v_and_or_b32 v32, v33, s86, v32
	v_cvt_pk_bf16_f32 v33, v113, v115
	v_cvt_pk_bf16_f32 v34, v117, v119
	v_bfe_u32 v35, v121, 16, 1
	v_add3_u32 v35, v121, v35, s33
	v_lshrrev_b32_e32 v35, 16, v35
	ds_read2_b32 v[108:109], v67 offset0:16 offset1:24
	v_and_or_b32 v35, v110, s86, v35
	ds_read2_b32 v[110:111], v67 offset0:49 offset1:57
	ds_read2_b32 v[112:113], v67 offset0:82 offset1:90
	ds_read2_b32 v[114:115], v67 offset0:115 offset1:123
	global_store_dwordx4 v2, v[32:35], s[2:3]
	s_waitcnt lgkmcnt(3)
	v_bfe_u32 v2, v108, 16, 1
	v_add3_u32 v2, v108, v2, s33
	s_waitcnt lgkmcnt(2)
	v_bfe_u32 v32, v110, 16, 1
	ds_read2_b32 v[116:117], v67 offset0:148 offset1:156
	v_lshrrev_b32_e32 v2, 16, v2
	v_add3_u32 v32, v110, v32, s33
	ds_read2_b32 v[118:119], v67 offset0:181 offset1:189
	v_and_or_b32 v32, v32, s86, v2
	s_waitcnt lgkmcnt(3)
	s_waitcnt lgkmcnt(2)
	ds_read2_b32 v[120:121], v67 offset0:214 offset1:222
	v_cvt_pk_bf16_f32 v33, v112, v114
	s_waitcnt lgkmcnt(2)
	s_waitcnt lgkmcnt(1)
	v_cvt_pk_bf16_f32 v34, v116, v118
	s_waitcnt lgkmcnt(0)
	v_bfe_u32 v2, v120, 16, 1
	v_add3_u32 v2, v120, v2, s33
	v_bfe_u32 v35, v122, 16, 1
	v_lshrrev_b32_e32 v2, 16, v2
	v_add3_u32 v35, v122, v35, s33
	v_and_or_b32 v35, v35, s86, v2
	v_xor_b32_e32 v2, 32, v124
	v_lshl_add_u64 v[124:125], s[2:3], 0, v[2:3]
	global_store_dwordx4 v[124:125], v[32:35], off offset:512
	v_bfe_u32 v2, v111, 16, 1
	v_add3_u32 v2, v111, v2, s33
	v_bfe_u32 v32, v109, 16, 1
	v_add3_u32 v32, v109, v32, s33
	v_lshrrev_b32_e32 v32, 16, v32
	v_and_or_b32 v32, v2, s86, v32
	v_cvt_pk_bf16_f32 v33, v113, v115
	v_bfe_u32 v35, v121, 16, 1
	v_cvt_pk_bf16_f32 v34, v117, v119
	v_bfe_u32 v2, v123, 16, 1
	v_add3_u32 v35, v121, v35, s33
	v_add3_u32 v2, v123, v2, s33
	v_lshrrev_b32_e32 v35, 16, v35
	v_and_or_b32 v35, v2, s86, v35
	global_store_dwordx4 v[124:125], v[32:35], off offset:768
	s_waitcnt lgkmcnt(0)

; #define LAS __attribute__((address_space(3)))
; #define LDS_WAIT() asm volatile("s_waitcnt lgkmcnt(0)" ::: "memory")
; __device__ __forceinline__ void transpose_item(const float* W, int K, int N, bf16* WT, int mode, const float* gain, LAS float* scr, int item, int lane) {
;     const int nblk = N / 32, kb = item / nblk, nb = item % nblk, k0 = 64 * kb, n0 = 32 * nb;
; #pragma unroll
;     for (int i = 0; i < 32; ++i) { const int kk = 2 * i + (lane >> 5); float w = W[(size_t)(k0 + kk) * N + n0 + (lane & 31)]; if (gain) w *= gain[k0 + kk]; scr[kk * 33 + (lane & 31)] = w; }
;     LDS_WAIT(); asm volatile("" ::: "memory");
.LBB0_114:
	s_andn2_b64 vcc, exec, s[2:3]
	s_cbranch_vccnz .LBB0_116
	s_add_i32 s2, s88, 0xdc00
	s_bfe_u32 s2, s2, 0xb0005
	s_lshl_b32 s3, s2, 6
	s_and_b32 s18, s10, 0x3e0
	s_lshl_b32 s56, s18, 2
	v_or_b32_e32 v2, s3, v0
	v_lshl_add_u64 v[32:33], v[8:9], 0, s[56:57]
	v_lshlrev_b32_e32 v2, 12, v2
	v_lshl_add_u64 v[34:35], v[32:33], 0, v[2:3]
	v_or_b32_e32 v2, s3, v38
	v_lshlrev_b32_e32 v2, 12, v2
	global_load_dword v108, v[34:35], off
	v_lshl_add_u64 v[34:35], v[32:33], 0, v[2:3]
	v_or_b32_e32 v2, s3, v70
	v_lshlrev_b32_e32 v2, 12, v2
	global_load_dword v109, v[34:35], off
	v_lshl_add_u64 v[34:35], v[32:33], 0, v[2:3]
	v_or_b32_e32 v2, s3, v71
	v_lshlrev_b32_e32 v2, 12, v2
	global_load_dword v110, v[34:35], off
	v_lshl_add_u64 v[34:35], v[32:33], 0, v[2:3]
	v_or_b32_e32 v2, s3, v72
	v_lshlrev_b32_e32 v2, 12, v2
	global_load_dword v111, v[34:35], off
	v_lshl_add_u64 v[34:35], v[32:33], 0, v[2:3]
	v_or_b32_e32 v2, s3, v73
	v_lshlrev_b32_e32 v2, 12, v2
	global_load_dword v112, v[34:35], off
	v_lshl_add_u64 v[34:35], v[32:33], 0, v[2:3]
	v_or_b32_e32 v2, s3, v74
	v_lshlrev_b32_e32 v2, 12, v2
	global_load_dword v113, v[34:35], off
	v_lshl_add_u64 v[34:35], v[32:33], 0, v[2:3]
	v_or_b32_e32 v2, s3, v75
	v_lshlrev_b32_e32 v2, 12, v2
	global_load_dword v114, v[34:35], off
	v_lshl_add_u64 v[34:35], v[32:33], 0, v[2:3]
	v_or_b32_e32 v2, s3, v76
	v_lshlrev_b32_e32 v2, 12, v2
	global_load_dword v115, v[34:35], off
	v_lshl_add_u64 v[34:35], v[32:33], 0, v[2:3]
	v_or_b32_e32 v2, s3, v77
	v_lshlrev_b32_e32 v2, 12, v2
	global_load_dword v116, v[34:35], off
	v_lshl_add_u64 v[34:35], v[32:33], 0, v[2:3]
	v_or_b32_e32 v2, s3, v78
	v_lshlrev_b32_e32 v2, 12, v2
	global_load_dword v117, v[34:35], off
	v_lshl_add_u64 v[34:35], v[32:33], 0, v[2:3]
	v_or_b32_e32 v2, s3, v79
	v_lshlrev_b32_e32 v2, 12, v2
	global_load_dword v118, v[34:35], off
	v_lshl_add_u64 v[34:35], v[32:33], 0, v[2:3]
	v_or_b32_e32 v2, s3, v80
	v_lshlrev_b32_e32 v2, 12, v2
	global_load_dword v119, v[34:35], off
	v_lshl_add_u64 v[34:35], v[32:33], 0, v[2:3]
	v_or_b32_e32 v2, s3, v81
	v_lshlrev_b32_e32 v2, 12, v2
	global_load_dword v120, v[34:35], off
	v_lshl_add_u64 v[34:35], v[32:33], 0, v[2:3]
	v_or_b32_e32 v2, s3, v82
	v_lshlrev_b32_e32 v2, 12, v2
	global_load_dword v121, v[34:35], off
	v_lshl_add_u64 v[34:35], v[32:33], 0, v[2:3]
	v_or_b32_e32 v2, s3, v83
	v_lshlrev_b32_e32 v2, 12, v2
	global_load_dword v122, v[34:35], off
	v_lshl_add_u64 v[34:35], v[32:33], 0, v[2:3]
	v_or_b32_e32 v2, s3, v84
	v_lshlrev_b32_e32 v2, 12, v2
	global_load_dword v123, v[34:35], off
	v_lshl_add_u64 v[34:35], v[32:33], 0, v[2:3]
	v_or_b32_e32 v2, s3, v85
	v_lshlrev_b32_e32 v2, 12, v2
	global_load_dword v124, v[34:35], off
	v_lshl_add_u64 v[34:35], v[32:33], 0, v[2:3]
	v_or_b32_e32 v2, s3, v86
	v_lshlrev_b32_e32 v2, 12, v2
	global_load_dword v125, v[34:35], off
	v_lshl_add_u64 v[34:35], v[32:33], 0, v[2:3]
	v_or_b32_e32 v2, s3, v87
	v_lshlrev_b32_e32 v2, 12, v2
	global_load_dword v126, v[34:35], off
	v_lshl_add_u64 v[34:35], v[32:33], 0, v[2:3]
	v_or_b32_e32 v2, s3, v88
	v_lshlrev_b32_e32 v2, 12, v2
	global_load_dword v127, v[34:35], off
	v_lshl_add_u64 v[34:35], v[32:33], 0, v[2:3]
	v_or_b32_e32 v2, s3, v89
	v_lshlrev_b32_e32 v2, 12, v2
	global_load_dword v128, v[34:35], off
	v_lshl_add_u64 v[34:35], v[32:33], 0, v[2:3]
	v_or_b32_e32 v2, s3, v90
	v_lshlrev_b32_e32 v2, 12, v2
	global_load_dword v129, v[34:35], off
	v_lshl_add_u64 v[34:35], v[32:33], 0, v[2:3]
	v_or_b32_e32 v2, s3, v91
	v_lshlrev_b32_e32 v2, 12, v2
	global_load_dword v130, v[34:35], off
	v_lshl_add_u64 v[34:35], v[32:33], 0, v[2:3]
	v_or_b32_e32 v2, s3, v92
	v_lshlrev_b32_e32 v2, 12, v2
	global_load_dword v131, v[34:35], off
	v_lshl_add_u64 v[34:35], v[32:33], 0, v[2:3]
	v_or_b32_e32 v2, s3, v93
	v_lshlrev_b32_e32 v2, 12, v2
	global_load_dword v132, v[34:35], off
	v_lshl_add_u64 v[34:35], v[32:33], 0, v[2:3]
	v_or_b32_e32 v2, s3, v94
	v_lshlrev_b32_e32 v2, 12, v2
	global_load_dword v133, v[34:35], off
	v_lshl_add_u64 v[34:35], v[32:33], 0, v[2:3]
	v_or_b32_e32 v2, s3, v95
	v_lshlrev_b32_e32 v2, 12, v2
	global_load_dword v134, v[34:35], off
	v_lshl_add_u64 v[34:35], v[32:33], 0, v[2:3]
	v_or_b32_e32 v2, s3, v96
	v_lshlrev_b32_e32 v2, 12, v2
	global_load_dword v135, v[34:35], off
	v_lshl_add_u64 v[34:35], v[32:33], 0, v[2:3]
	v_or_b32_e32 v2, s3, v97
	v_lshlrev_b32_e32 v2, 12, v2
	global_load_dword v136, v[34:35], off
	v_lshl_add_u64 v[34:35], v[32:33], 0, v[2:3]
	v_or_b32_e32 v2, s3, v98
	v_lshlrev_b32_e32 v2, 12, v2
	global_load_dword v137, v[34:35], off
	v_lshl_add_u64 v[34:35], v[32:33], 0, v[2:3]
	v_or_b32_e32 v2, s3, v99
	v_lshlrev_b32_e32 v2, 12, v2
	v_lshl_add_u64 v[32:33], v[32:33], 0, v[2:3]
	global_load_dword v34, v[34:35], off
	s_and_b32 s3, s10, 0x60
	global_load_dword v2, v[32:33], off
	v_add_u32_e32 v32, v36, v37
	s_waitcnt vmcnt(30)
; #define GAS __attribute__((address_space(1)))
; #define LAS __attribute__((address_space(3)))
; #define LDS_WAIT() asm volatile("s_waitcnt lgkmcnt(0)" ::: "memory")
; __device__ __forceinline__ unsigned pk2(float lo, float hi) { return f2bf(lo) | (f2bf(hi) << 16); }
; __device__ __forceinline__ void transpose_item(const float* W, int K, int N, bf16* WT, int mode, const float* gain, LAS float* scr, int item, int lane) {
;     ...
;     for (int i = 0; i < 32; ++i) { const int kk = 2 * i + (lane >> 5); float w = W[(size_t)(k0 + kk) * N + n0 + (lane & 31)]; if (gain) w *= gain[k0 + kk]; scr[kk * 33 + (lane & 31)] = w; }
;     LDS_WAIT(); asm volatile("" ::: "memory");
;     const int c = lane & 7;
; #pragma unroll
;     for (int j = 0; j < 4; ++j) { const int n = (lane >> 3) + 8 * j; const LAS float* s = scr + (8 * c) * 33 + n;
;         v4u o; o.x = pk2(s[0 * 33], s[1 * 33]); o.y = pk2(s[2 * 33], s[3 * 33]); o.z = pk2(s[4 * 33], s[5 * 33]); o.w = pk2(s[6 * 33], s[7 * 33]);
;         const int p_ = dst_row(mode, n0 + n), pl_ = p_ & 127, x_ = pl_ & 31, R_ = (pl_ & ~31) + 16 * ((x_ >> 2) & 1) + 4 * (x_ >> 3) + (x_ & 3);
;         *(GAS v4u*)((GAS unsigned char*)WT + ((size_t)(p_ >> 7) * (K / 64) + (k0 >> 6)) * 16384 + pg8::lds_byte(R_, 8 * c)) = o; }
	ds_write2_b32 v32, v108, v109 offset1:66
	s_waitcnt vmcnt(28)
	ds_write2_b32 v32, v110, v111 offset0:132 offset1:198
	v_add_u32_e32 v32, 0x400, v32
	s_waitcnt vmcnt(26)
	ds_write2_b32 v32, v112, v113 offset0:8 offset1:74
	v_add_u32_e32 v32, v36, v44
	s_waitcnt vmcnt(24)
	ds_write2_b32 v32, v114, v115 offset1:66
	s_waitcnt vmcnt(22)
	ds_write2_b32 v32, v116, v117 offset0:132 offset1:198
	v_add_u32_e32 v32, 0x400, v32
	s_waitcnt vmcnt(20)
	ds_write2_b32 v32, v118, v119 offset0:8 offset1:74
	v_add_u32_e32 v32, v36, v50
	s_waitcnt vmcnt(18)
	ds_write2_b32 v32, v120, v121 offset1:66
	s_waitcnt vmcnt(16)
	ds_write2_b32 v32, v122, v123 offset0:132 offset1:198
	v_add_u32_e32 v32, 0x400, v32
	s_waitcnt vmcnt(14)
	ds_write2_b32 v32, v124, v125 offset0:8 offset1:74
	v_add_u32_e32 v32, v36, v56
	s_waitcnt vmcnt(12)
	ds_write2_b32 v32, v126, v127 offset1:66
	s_waitcnt vmcnt(10)
	ds_write2_b32 v32, v128, v129 offset0:132 offset1:198
	v_add_u32_e32 v32, 0x400, v32
	s_waitcnt vmcnt(8)
	ds_write2_b32 v32, v130, v131 offset0:8 offset1:74
	v_add_u32_e32 v32, v36, v62
	s_waitcnt vmcnt(6)
	ds_write2_b32 v32, v132, v133 offset1:66
	s_waitcnt vmcnt(4)
	ds_write2_b32 v32, v134, v135 offset0:132 offset1:198
	v_add_u32_e32 v32, 0x400, v32
	s_waitcnt vmcnt(2)
	ds_write2_b32 v32, v136, v137 offset0:8 offset1:74
	s_waitcnt vmcnt(0)
	ds_write2_b32 v32, v34, v2 offset0:140 offset1:206
	s_waitcnt lgkmcnt(0)
	ds_read2_b32 v[108:109], v67 offset1:8
	ds_read2_b32 v[110:111], v67 offset0:33 offset1:41
	ds_read2_b32 v[112:113], v67 offset0:66 offset1:74
	ds_read2_b32 v[114:115], v67 offset0:99 offset1:107
	ds_read2_b32 v[116:117], v67 offset0:132 offset1:140
	s_waitcnt lgkmcnt(4)
	s_waitcnt lgkmcnt(3)
	ds_read2_b32 v[118:119], v67 offset0:165 offset1:173
	v_cvt_pk_bf16_f32 v32, v108, v110
	s_waitcnt lgkmcnt(3)
	s_waitcnt lgkmcnt(2)
	ds_read2_b32 v[120:121], v67 offset0:198 offset1:206
	ds_read2_b32 v[122:123], v67 offset0:231 offset1:239
	v_cvt_pk_bf16_f32 v33, v112, v114
	s_waitcnt lgkmcnt(3)
	s_waitcnt lgkmcnt(2)
	v_cvt_pk_bf16_f32 v34, v116, v118
	s_waitcnt lgkmcnt(1)
	s_waitcnt lgkmcnt(0)
	v_cvt_pk_bf16_f32 v35, v120, v122
	v_or_b32_e32 v2, s3, v100
	s_bfe_u32 s3, s10, 0x30007
	s_mul_i32 s3, s3, 44
	s_add_i32 s3, s3, s2
	v_lshrrev_b32_e32 v2, 3, v2
	s_lshl_b32 s2, s3, 14
	v_readlane_b32 s3, v254, 1
	v_or_b32_e32 v2, v2, v64
	s_add_u32 s2, s3, s2
	v_readlane_b32 s3, v254, 3
	v_lshlrev_b32_e32 v2, 10, v2
	s_addc_u32 s3, s3, 0
	v_or_b32_e32 v124, v2, v68
	v_bfe_u32 v108, v123, 16, 1
	v_add3_u32 v110, v123, v108, s33
	global_store_dwordx4 v124, v[32:35], s[2:3]
	v_or_b32_e32 v2, v2, v69
	ds_read2_b32 v[122:123], v67 offset0:247 offset1:255
	v_bfe_u32 v32, v109, 16, 1
	v_add3_u32 v32, v109, v32, s33
	v_bfe_u32 v33, v111, 16, 1
	v_lshrrev_b32_e32 v32, 16, v32
	v_add3_u32 v33, v111, v33, s33
	v_and_or_b32 v32, v33, s86, v32
	v_cvt_pk_bf16_f32 v33, v113, v115
	v_cvt_pk_bf16_f32 v34, v117, v119
	v_bfe_u32 v35, v121, 16, 1
	v_add3_u32 v35, v121, v35, s33
	v_lshrrev_b32_e32 v35, 16, v35
	ds_read2_b32 v[108:109], v67 offset0:16 offset1:24
	v_and_or_b32 v35, v110, s86, v35
	ds_read2_b32 v[110:111], v67 offset0:49 offset1:57
	ds_read2_b32 v[112:113], v67 offset0:82 offset1:90
	ds_read2_b32 v[114:115], v67 offset0:115 offset1:123
	global_store_dwordx4 v2, v[32:35], s[2:3]
	s_waitcnt lgkmcnt(3)
	v_bfe_u32 v2, v108, 16, 1
	v_add3_u32 v2, v108, v2, s33
	s_waitcnt lgkmcnt(2)
	v_bfe_u32 v32, v110, 16, 1
	ds_read2_b32 v[116:117], v67 offset0:148 offset1:156
	v_lshrrev_b32_e32 v2, 16, v2
	v_add3_u32 v32, v110, v32, s33
	ds_read2_b32 v[118:119], v67 offset0:181 offset1:189
	v_and_or_b32 v32, v32, s86, v2
	s_waitcnt lgkmcnt(3)
	s_waitcnt lgkmcnt(2)
	ds_read2_b32 v[120:121], v67 offset0:214 offset1:222
	v_cvt_pk_bf16_f32 v33, v112, v114
	s_waitcnt lgkmcnt(2)
	s_waitcnt lgkmcnt(1)
	v_cvt_pk_bf16_f32 v34, v116, v118
	s_waitcnt lgkmcnt(0)
	v_bfe_u32 v2, v120, 16, 1
	v_add3_u32 v2, v120, v2, s33
	v_bfe_u32 v35, v122, 16, 1
	v_lshrrev_b32_e32 v2, 16, v2
	v_add3_u32 v35, v122, v35, s33
	v_and_or_b32 v35, v35, s86, v2
	v_xor_b32_e32 v2, 32, v124
	v_lshl_add_u64 v[124:125], s[2:3], 0, v[2:3]
	global_store_dwordx4 v[124:125], v[32:35], off offset:512
	v_bfe_u32 v2, v111, 16, 1
	v_add3_u32 v2, v111, v2, s33
	v_bfe_u32 v32, v109, 16, 1
	v_add3_u32 v32, v109, v32, s33
	v_lshrrev_b32_e32 v32, 16, v32
	v_and_or_b32 v32, v2, s86, v32
	v_cvt_pk_bf16_f32 v33, v113, v115
	v_bfe_u32 v35, v121, 16, 1
	v_cvt_pk_bf16_f32 v34, v117, v119
	v_bfe_u32 v2, v123, 16, 1
	v_add3_u32 v35, v121, v35, s33
	v_add3_u32 v2, v123, v2, s33
	v_lshrrev_b32_e32 v35, 16, v35
	v_and_or_b32 v35, v2, s86, v35
	global_store_dwordx4 v[124:125], v[32:35], off offset:768
	s_waitcnt lgkmcnt(0)

; #define LAS __attribute__((address_space(3)))
; #define LDS_WAIT() asm volatile("s_waitcnt lgkmcnt(0)" ::: "memory")
; __device__ __forceinline__ void transpose_item(const float* W, int K, int N, bf16* WT, int mode, const float* gain, LAS float* scr, int item, int lane) {
;     const int nblk = N / 32, kb = item / nblk, nb = item % nblk, k0 = 64 * kb, n0 = 32 * nb;
; #pragma unroll
;     for (int i = 0; i < 32; ++i) { const int kk = 2 * i + (lane >> 5); float w = W[(size_t)(k0 + kk) * N + n0 + (lane & 31)]; if (gain) w *= gain[k0 + kk]; scr[kk * 33 + (lane & 31)] = w; }
;     LDS_WAIT(); asm volatile("" ::: "memory");
.LBB0_117:
	s_andn2_b64 vcc, exec, s[2:3]
	s_cbranch_vccnz .LBB0_119
	s_add_i32 s3, s88, 0xe180
	s_and_b32 s2, s3, 0xffff
	s_mul_i32 s2, s2, 0xba2f
	s_lshr_b32 s18, s2, 16
	s_lshr_b32 s2, s2, 22
	s_mul_i32 s19, s2, 0x58
	s_sub_i32 s3, s3, s19
	s_and_b32 s3, s3, 0xffff
	s_and_b32 s19, s18, 0xffc0
	s_lshl_b32 s56, s3, 7
	v_lshl_add_u64 v[32:33], v[20:21], 0, s[56:57]
	v_or_b32_e32 v2, s19, v0
	v_mad_u64_u32 v[34:35], s[22:23], v2, s87, v[32:33]
	v_lshlrev_b32_e32 v2, 2, v2
	global_load_dword v34, v[34:35], off
	v_or_b32_e32 v109, s19, v38
	global_load_dword v2, v2, s[16:17]
	v_add_u32_e32 v108, v36, v37
	s_lshl_b32 s18, s3, 5
	s_lshl_b32 s3, s3, 3
	s_and_b32 s18, s18, 0x60
	s_and_b32 s3, s3, 0x3e0
	s_add_i32 s2, s2, s3
	s_lshl_b32 s2, s2, 14
	s_add_i32 s2, s2, 0x40000
	v_readlane_b32 s3, v254, 4
	s_add_u32 s2, s3, s2
	v_readlane_b32 s3, v254, 6
	s_addc_u32 s3, s3, 0
	s_waitcnt vmcnt(0)
	v_mul_f32_e32 v2, v34, v2
	v_mad_u64_u32 v[34:35], s[22:23], v109, s87, v[32:33]
	global_load_dword v34, v[34:35], off
	v_lshlrev_b32_e32 v35, 2, v109
	global_load_dword v35, v35, s[16:17]
	v_or_b32_e32 v109, s19, v71
	s_waitcnt vmcnt(0)
	v_mul_f32_e32 v34, v34, v35
	ds_write2_b32 v108, v2, v34 offset1:66
	v_or_b32_e32 v2, s19, v70
	v_mad_u64_u32 v[34:35], s[22:23], v2, s87, v[32:33]
	v_lshlrev_b32_e32 v2, 2, v2
	global_load_dword v34, v[34:35], off
	s_nop 0
	global_load_dword v2, v2, s[16:17]
	s_waitcnt vmcnt(0)
	v_mul_f32_e32 v2, v34, v2
	v_mad_u64_u32 v[34:35], s[22:23], v109, s87, v[32:33]
	global_load_dword v34, v[34:35], off
	v_lshlrev_b32_e32 v35, 2, v109
	global_load_dword v35, v35, s[16:17]
	v_or_b32_e32 v109, s19, v73
	s_waitcnt vmcnt(0)
	v_mul_f32_e32 v34, v34, v35
	ds_write2_b32 v108, v2, v34 offset0:132 offset1:198
	v_or_b32_e32 v2, s19, v72
	v_mad_u64_u32 v[34:35], s[22:23], v2, s87, v[32:33]
	v_lshlrev_b32_e32 v2, 2, v2
	global_load_dword v34, v[34:35], off
	s_nop 0
	global_load_dword v2, v2, s[16:17]
	s_waitcnt vmcnt(0)
	v_mul_f32_e32 v2, v34, v2
	v_mad_u64_u32 v[34:35], s[22:23], v109, s87, v[32:33]
	global_load_dword v34, v[34:35], off
	v_lshlrev_b32_e32 v35, 2, v109
	global_load_dword v35, v35, s[16:17]
	v_or_b32_e32 v109, s19, v75
	s_waitcnt vmcnt(0)
	v_mul_f32_e32 v34, v34, v35
	v_add_u32_e32 v35, 0x400, v108
	ds_write2_b32 v35, v2, v34 offset0:8 offset1:74
	v_or_b32_e32 v2, s19, v74
	v_mad_u64_u32 v[34:35], s[22:23], v2, s87, v[32:33]
	v_lshlrev_b32_e32 v2, 2, v2
	global_load_dword v34, v[34:35], off
	v_add_u32_e32 v108, v36, v44
	global_load_dword v2, v2, s[16:17]
	s_waitcnt vmcnt(0)
	v_mul_f32_e32 v2, v34, v2
	v_mad_u64_u32 v[34:35], s[22:23], v109, s87, v[32:33]
	global_load_dword v34, v[34:35], off
	v_lshlrev_b32_e32 v35, 2, v109
	global_load_dword v35, v35, s[16:17]
	v_or_b32_e32 v109, s19, v77
	s_waitcnt vmcnt(0)
	v_mul_f32_e32 v34, v34, v35
	ds_write2_b32 v108, v2, v34 offset1:66
	v_or_b32_e32 v2, s19, v76
	v_mad_u64_u32 v[34:35], s[22:23], v2, s87, v[32:33]
	v_lshlrev_b32_e32 v2, 2, v2
	global_load_dword v34, v[34:35], off
	s_nop 0
	global_load_dword v2, v2, s[16:17]
	s_waitcnt vmcnt(0)
	v_mul_f32_e32 v2, v34, v2
	v_mad_u64_u32 v[34:35], s[22:23], v109, s87, v[32:33]
	global_load_dword v34, v[34:35], off
	v_lshlrev_b32_e32 v35, 2, v109
	global_load_dword v35, v35, s[16:17]
	v_or_b32_e32 v109, s19, v79
	s_waitcnt vmcnt(0)
	v_mul_f32_e32 v34, v34, v35
	ds_write2_b32 v108, v2, v34 offset0:132 offset1:198
	v_or_b32_e32 v2, s19, v78
	v_mad_u64_u32 v[34:35], s[22:23], v2, s87, v[32:33]
	v_lshlrev_b32_e32 v2, 2, v2
	global_load_dword v34, v[34:35], off
	s_nop 0
	global_load_dword v2, v2, s[16:17]
	s_waitcnt vmcnt(0)
	v_mul_f32_e32 v2, v34, v2
	v_mad_u64_u32 v[34:35], s[22:23], v109, s87, v[32:33]
	global_load_dword v34, v[34:35], off
	v_lshlrev_b32_e32 v35, 2, v109
	global_load_dword v35, v35, s[16:17]
	v_or_b32_e32 v109, s19, v81
	s_waitcnt vmcnt(0)
	v_mul_f32_e32 v34, v34, v35
	v_add_u32_e32 v35, 0x400, v108
	ds_write2_b32 v35, v2, v34 offset0:8 offset1:74
	v_or_b32_e32 v2, s19, v80
	v_mad_u64_u32 v[34:35], s[22:23], v2, s87, v[32:33]
	v_lshlrev_b32_e32 v2, 2, v2
	global_load_dword v34, v[34:35], off
	v_add_u32_e32 v108, v36, v50
	global_load_dword v2, v2, s[16:17]
	s_waitcnt vmcnt(0)
	v_mul_f32_e32 v2, v34, v2
	v_mad_u64_u32 v[34:35], s[22:23], v109, s87, v[32:33]
	global_load_dword v34, v[34:35], off
	v_lshlrev_b32_e32 v35, 2, v109
	global_load_dword v35, v35, s[16:17]
	v_or_b32_e32 v109, s19, v83
	s_waitcnt vmcnt(0)
	v_mul_f32_e32 v34, v34, v35
	ds_write2_b32 v108, v2, v34 offset1:66
	v_or_b32_e32 v2, s19, v82
	v_mad_u64_u32 v[34:35], s[22:23], v2, s87, v[32:33]
	v_lshlrev_b32_e32 v2, 2, v2
	global_load_dword v34, v[34:35], off
	s_nop 0
	global_load_dword v2, v2, s[16:17]
	s_waitcnt vmcnt(0)
	v_mul_f32_e32 v2, v34, v2
	v_mad_u64_u32 v[34:35], s[22:23], v109, s87, v[32:33]
	global_load_dword v34, v[34:35], off
	v_lshlrev_b32_e32 v35, 2, v109
	global_load_dword v35, v35, s[16:17]
	v_or_b32_e32 v109, s19, v85
	s_waitcnt vmcnt(0)
	v_mul_f32_e32 v34, v34, v35
	ds_write2_b32 v108, v2, v34 offset0:132 offset1:198
	v_or_b32_e32 v2, s19, v84
	v_mad_u64_u32 v[34:35], s[22:23], v2, s87, v[32:33]
	v_lshlrev_b32_e32 v2, 2, v2
	global_load_dword v34, v[34:35], off
	s_nop 0
	global_load_dword v2, v2, s[16:17]
	s_waitcnt vmcnt(0)
	v_mul_f32_e32 v2, v34, v2
	v_mad_u64_u32 v[34:35], s[22:23], v109, s87, v[32:33]
	global_load_dword v34, v[34:35], off
	v_lshlrev_b32_e32 v35, 2, v109
	global_load_dword v35, v35, s[16:17]
	v_or_b32_e32 v109, s19, v87
	s_waitcnt vmcnt(0)
	v_mul_f32_e32 v34, v34, v35
	v_add_u32_e32 v35, 0x400, v108
	ds_write2_b32 v35, v2, v34 offset0:8 offset1:74
	v_or_b32_e32 v2, s19, v86
	v_mad_u64_u32 v[34:35], s[22:23], v2, s87, v[32:33]
	v_lshlrev_b32_e32 v2, 2, v2
	global_load_dword v34, v[34:35], off
	v_add_u32_e32 v108, v36, v56
	global_load_dword v2, v2, s[16:17]
	s_waitcnt vmcnt(0)
; #define GAS __attribute__((address_space(1)))
; #define LAS __attribute__((address_space(3)))
; #define LDS_WAIT() asm volatile("s_waitcnt lgkmcnt(0)" ::: "memory")
; __device__ __forceinline__ unsigned pk2(float lo, float hi) { return f2bf(lo) | (f2bf(hi) << 16); }
; __device__ __forceinline__ void transpose_item(const float* W, int K, int N, bf16* WT, int mode, const float* gain, LAS float* scr, int item, int lane) {
;     ...
;     for (int i = 0; i < 32; ++i) { const int kk = 2 * i + (lane >> 5); float w = W[(size_t)(k0 + kk) * N + n0 + (lane & 31)]; if (gain) w *= gain[k0 + kk]; scr[kk * 33 + (lane & 31)] = w; }
;     LDS_WAIT(); asm volatile("" ::: "memory");
;     const int c = lane & 7;
; #pragma unroll
;     for (int j = 0; j < 4; ++j) { const int n = (lane >> 3) + 8 * j; const LAS float* s = scr + (8 * c) * 33 + n;
;         v4u o; o.x = pk2(s[0 * 33], s[1 * 33]); o.y = pk2(s[2 * 33], s[3 * 33]); o.z = pk2(s[4 * 33], s[5 * 33]); o.w = pk2(s[6 * 33], s[7 * 33]);
;         const int p_ = dst_row(mode, n0 + n), pl_ = p_ & 127, x_ = pl_ & 31, R_ = (pl_ & ~31) + 16 * ((x_ >> 2) & 1) + 4 * (x_ >> 3) + (x_ & 3);
;         *(GAS v4u*)((GAS unsigned char*)WT + ((size_t)(p_ >> 7) * (K / 64) + (k0 >> 6)) * 16384 + pg8::lds_byte(R_, 8 * c)) = o; }
	v_mul_f32_e32 v2, v34, v2
	v_mad_u64_u32 v[34:35], s[22:23], v109, s87, v[32:33]
	global_load_dword v34, v[34:35], off
	v_lshlrev_b32_e32 v35, 2, v109
	global_load_dword v35, v35, s[16:17]
	v_or_b32_e32 v109, s19, v89
	s_waitcnt vmcnt(0)
	v_mul_f32_e32 v34, v34, v35
	ds_write2_b32 v108, v2, v34 offset1:66
	v_or_b32_e32 v2, s19, v88
	v_mad_u64_u32 v[34:35], s[22:23], v2, s87, v[32:33]
	v_lshlrev_b32_e32 v2, 2, v2
	global_load_dword v34, v[34:35], off
	s_nop 0
	global_load_dword v2, v2, s[16:17]
	s_waitcnt vmcnt(0)
	v_mul_f32_e32 v2, v34, v2
	v_mad_u64_u32 v[34:35], s[22:23], v109, s87, v[32:33]
	global_load_dword v34, v[34:35], off
	v_lshlrev_b32_e32 v35, 2, v109
	global_load_dword v35, v35, s[16:17]
	v_or_b32_e32 v109, s19, v91
	s_waitcnt vmcnt(0)
	v_mul_f32_e32 v34, v34, v35
	ds_write2_b32 v108, v2, v34 offset0:132 offset1:198
	v_or_b32_e32 v2, s19, v90
	v_mad_u64_u32 v[34:35], s[22:23], v2, s87, v[32:33]
	v_lshlrev_b32_e32 v2, 2, v2
	global_load_dword v34, v[34:35], off
	s_nop 0
	global_load_dword v2, v2, s[16:17]
	s_waitcnt vmcnt(0)
	v_mul_f32_e32 v2, v34, v2
	v_mad_u64_u32 v[34:35], s[22:23], v109, s87, v[32:33]
	global_load_dword v34, v[34:35], off
	v_lshlrev_b32_e32 v35, 2, v109
	global_load_dword v35, v35, s[16:17]
	v_or_b32_e32 v109, s19, v93
	s_waitcnt vmcnt(0)
	v_mul_f32_e32 v34, v34, v35
	v_add_u32_e32 v35, 0x400, v108
	ds_write2_b32 v35, v2, v34 offset0:8 offset1:74
	v_or_b32_e32 v2, s19, v92
	v_mad_u64_u32 v[34:35], s[22:23], v2, s87, v[32:33]
	v_lshlrev_b32_e32 v2, 2, v2
	global_load_dword v34, v[34:35], off
	v_add_u32_e32 v108, v36, v62
	global_load_dword v2, v2, s[16:17]
	s_waitcnt vmcnt(0)
	v_mul_f32_e32 v2, v34, v2
	v_mad_u64_u32 v[34:35], s[22:23], v109, s87, v[32:33]
	global_load_dword v34, v[34:35], off
	v_lshlrev_b32_e32 v35, 2, v109
	global_load_dword v35, v35, s[16:17]
	v_or_b32_e32 v109, s19, v95
	s_waitcnt vmcnt(0)
	v_mul_f32_e32 v34, v34, v35
	ds_write2_b32 v108, v2, v34 offset1:66
	v_or_b32_e32 v2, s19, v94
	v_mad_u64_u32 v[34:35], s[22:23], v2, s87, v[32:33]
	v_lshlrev_b32_e32 v2, 2, v2
	global_load_dword v34, v[34:35], off
	s_nop 0
	global_load_dword v2, v2, s[16:17]
	s_waitcnt vmcnt(0)
	v_mul_f32_e32 v2, v34, v2
	v_mad_u64_u32 v[34:35], s[22:23], v109, s87, v[32:33]
	global_load_dword v34, v[34:35], off
	v_lshlrev_b32_e32 v35, 2, v109
	global_load_dword v35, v35, s[16:17]
	v_or_b32_e32 v109, s19, v97
	s_waitcnt vmcnt(0)
	v_mul_f32_e32 v34, v34, v35
	ds_write2_b32 v108, v2, v34 offset0:132 offset1:198
	v_or_b32_e32 v2, s19, v96
	v_mad_u64_u32 v[34:35], s[22:23], v2, s87, v[32:33]
	v_lshlrev_b32_e32 v2, 2, v2
	global_load_dword v34, v[34:35], off
	v_add_u32_e32 v108, 0x400, v108
	global_load_dword v2, v2, s[16:17]
	s_waitcnt vmcnt(0)
	v_mul_f32_e32 v2, v34, v2
	v_mad_u64_u32 v[34:35], s[22:23], v109, s87, v[32:33]
	global_load_dword v34, v[34:35], off
	v_lshlrev_b32_e32 v35, 2, v109
	global_load_dword v35, v35, s[16:17]
	s_waitcnt vmcnt(0)
	v_mul_f32_e32 v34, v34, v35
	ds_write2_b32 v108, v2, v34 offset0:8 offset1:74
	v_or_b32_e32 v2, s19, v98
	v_mad_u64_u32 v[34:35], s[22:23], v2, s87, v[32:33]
	v_lshlrev_b32_e32 v2, 2, v2
	global_load_dword v34, v[34:35], off
	s_nop 0
	global_load_dword v2, v2, s[16:17]
	s_waitcnt vmcnt(0)
	v_mul_f32_e32 v2, v34, v2
	v_or_b32_e32 v34, s19, v99
	v_mad_u64_u32 v[32:33], s[22:23], v34, s87, v[32:33]
	global_load_dword v32, v[32:33], off
	v_lshlrev_b32_e32 v33, 2, v34
	global_load_dword v33, v33, s[16:17]
	s_waitcnt vmcnt(0)
	v_mul_f32_e32 v32, v32, v33
	ds_write2_b32 v108, v2, v32 offset0:140 offset1:206
	s_waitcnt lgkmcnt(0)
	ds_read2_b32 v[108:109], v67 offset0:33 offset1:41
	ds_read2_b32 v[110:111], v67 offset1:8
	ds_read2_b32 v[112:113], v67 offset0:66 offset1:74
	ds_read2_b32 v[114:115], v67 offset0:99 offset1:107
	ds_read2_b32 v[116:117], v67 offset0:132 offset1:140
	ds_read2_b32 v[118:119], v67 offset0:165 offset1:173
	ds_read2_b32 v[120:121], v67 offset0:198 offset1:206
	ds_read2_b32 v[122:123], v67 offset0:231 offset1:239
	s_waitcnt lgkmcnt(7)
	s_waitcnt lgkmcnt(6)
	v_cvt_pk_bf16_f32 v32, v110, v108
	s_waitcnt lgkmcnt(5)
	s_waitcnt lgkmcnt(4)
	v_cvt_pk_bf16_f32 v33, v112, v114
	s_waitcnt lgkmcnt(3)
	s_waitcnt lgkmcnt(2)
	v_cvt_pk_bf16_f32 v34, v116, v118
	s_waitcnt lgkmcnt(1)
	s_waitcnt lgkmcnt(0)
	v_cvt_pk_bf16_f32 v35, v120, v122
	v_or_b32_e32 v2, s18, v100
	v_lshrrev_b32_e32 v2, 3, v2
	v_or_b32_e32 v2, v2, v64
	v_lshlrev_b32_e32 v2, 10, v2
	v_or_b32_e32 v124, v2, v68
	global_store_dwordx4 v124, v[32:35], s[2:3]
	v_bfe_u32 v108, v123, 16, 1
	v_add3_u32 v108, v123, v108, s33
	v_bfe_u32 v32, v111, 16, 1
	v_add3_u32 v32, v111, v32, s33
	v_bfe_u32 v33, v109, 16, 1
	v_lshrrev_b32_e32 v32, 16, v32
	v_add3_u32 v33, v109, v33, s33
	v_and_or_b32 v32, v33, s86, v32
	v_cvt_pk_bf16_f32 v33, v113, v115
	v_cvt_pk_bf16_f32 v34, v117, v119
	v_bfe_u32 v35, v121, 16, 1
	v_add3_u32 v35, v121, v35, s33
	v_lshrrev_b32_e32 v35, 16, v35
	v_and_or_b32 v35, v108, s86, v35
	v_or_b32_e32 v2, v2, v69
	global_store_dwordx4 v2, v[32:35], s[2:3]
	ds_read2_b32 v[108:109], v67 offset0:16 offset1:24
	ds_read2_b32 v[110:111], v67 offset0:49 offset1:57
	ds_read2_b32 v[112:113], v67 offset0:82 offset1:90
	ds_read2_b32 v[114:115], v67 offset0:115 offset1:123
	ds_read2_b32 v[116:117], v67 offset0:148 offset1:156
	ds_read2_b32 v[118:119], v67 offset0:181 offset1:189
	ds_read2_b32 v[120:121], v67 offset0:214 offset1:222
	ds_read2_b32 v[122:123], v67 offset0:247 offset1:255
	s_waitcnt lgkmcnt(7)
	s_waitcnt lgkmcnt(6)
	v_cvt_pk_bf16_f32 v32, v108, v110
	s_waitcnt lgkmcnt(5)
	s_waitcnt lgkmcnt(4)
	v_cvt_pk_bf16_f32 v33, v112, v114
	s_waitcnt lgkmcnt(3)
	s_waitcnt lgkmcnt(2)
	v_cvt_pk_bf16_f32 v34, v116, v118
	s_waitcnt lgkmcnt(1)
	v_bfe_u32 v2, v120, 16, 1
	v_add3_u32 v2, v120, v2, s33
	s_waitcnt lgkmcnt(0)
	v_bfe_u32 v35, v122, 16, 1
	v_lshrrev_b32_e32 v2, 16, v2
	v_add3_u32 v35, v122, v35, s33
	v_and_or_b32 v35, v35, s86, v2
	v_xor_b32_e32 v2, 32, v124
	v_lshl_add_u64 v[124:125], s[2:3], 0, v[2:3]
	global_store_dwordx4 v[124:125], v[32:35], off offset:512
	v_bfe_u32 v2, v111, 16, 1
	v_add3_u32 v2, v111, v2, s33
	v_bfe_u32 v32, v109, 16, 1
	v_add3_u32 v32, v109, v32, s33
	v_lshrrev_b32_e32 v32, 16, v32
	v_and_or_b32 v32, v2, s86, v32
	v_cvt_pk_bf16_f32 v33, v113, v115
	v_bfe_u32 v35, v121, 16, 1
	v_cvt_pk_bf16_f32 v34, v117, v119
	v_bfe_u32 v2, v123, 16, 1
	v_add3_u32 v35, v121, v35, s33
	v_add3_u32 v2, v123, v2, s33
	v_lshrrev_b32_e32 v35, 16, v35
	v_and_or_b32 v35, v2, s86, v35
	global_store_dwordx4 v[124:125], v[32:35], off offset:768
	s_waitcnt lgkmcnt(0)

; __device__ __forceinline__ void transpose_item(const float* W, int K, int N, bf16* WT, int mode, const float* gain, LAS float* scr, int item, int lane) {
;     const int nblk = N / 32, kb = item / nblk, nb = item % nblk, k0 = 64 * kb, n0 = 32 * nb;
; #pragma unroll
;     for (int i = 0; i < 32; ++i) { const int kk = 2 * i + (lane >> 5); float w = W[(size_t)(k0 + kk) * N + n0 + (lane & 31)]; if (gain) w *= gain[k0 + kk]; scr[kk * 33 + (lane & 31)] = w; }
.LBB0_120:
	s_andn2_b64 vcc, exec, s[2:3]
	s_cbranch_vccnz .LBB0_122
	s_add_i32 s3, s88, 0xe700
	s_and_b32 s2, s3, 0xffff
	s_mul_i32 s2, s2, 0xba2f
	s_lshr_b32 s19, s2, 16
	s_lshr_b32 s2, s2, 22
	s_mul_i32 s18, s2, 0x58
	s_sub_i32 s3, s3, s18
	s_and_b32 s18, s3, 0xffff
	s_and_b32 s19, s19, 0xffc0
	s_lshl_b32 s56, s18, 7
	v_lshl_add_u64 v[32:33], v[22:23], 0, s[56:57]
	v_or_b32_e32 v2, s19, v0
	v_mad_u64_u32 v[34:35], s[22:23], v2, s87, v[32:33]
	v_lshlrev_b32_e32 v2, 2, v2
	global_load_dword v34, v[34:35], off
	v_or_b32_e32 v109, s19, v38
	global_load_dword v2, v2, s[16:17]
	v_add_u32_e32 v108, v36, v37
	s_lshl_b32 s3, s18, 5
	s_lshl_b32 s18, s18, 3
	s_and_b32 s3, s3, 0x60
	s_and_b32 s18, s18, 0x3e0
	s_add_i32 s18, s18, s2
	s_lshl_b32 s2, s18, 14
	s_waitcnt vmcnt(0)
	v_mul_f32_e32 v2, v34, v2
	v_mad_u64_u32 v[34:35], s[22:23], v109, s87, v[32:33]
	global_load_dword v34, v[34:35], off
	v_lshlrev_b32_e32 v35, 2, v109
	global_load_dword v35, v35, s[16:17]
	v_or_b32_e32 v109, s19, v71
	s_waitcnt vmcnt(0)
	v_mul_f32_e32 v34, v34, v35
	ds_write2_b32 v108, v2, v34 offset1:66
	v_or_b32_e32 v2, s19, v70
	v_mad_u64_u32 v[34:35], s[22:23], v2, s87, v[32:33]
	v_lshlrev_b32_e32 v2, 2, v2
	global_load_dword v34, v[34:35], off
	s_nop 0
	global_load_dword v2, v2, s[16:17]
	s_waitcnt vmcnt(0)
	v_mul_f32_e32 v2, v34, v2
	v_mad_u64_u32 v[34:35], s[22:23], v109, s87, v[32:33]
	global_load_dword v34, v[34:35], off
	v_lshlrev_b32_e32 v35, 2, v109
	global_load_dword v35, v35, s[16:17]
	v_or_b32_e32 v109, s19, v73
	s_waitcnt vmcnt(0)
	v_mul_f32_e32 v34, v34, v35
	ds_write2_b32 v108, v2, v34 offset0:132 offset1:198
	v_or_b32_e32 v2, s19, v72
	v_mad_u64_u32 v[34:35], s[22:23], v2, s87, v[32:33]
	v_lshlrev_b32_e32 v2, 2, v2
	global_load_dword v34, v[34:35], off
	s_nop 0
	global_load_dword v2, v2, s[16:17]
	s_waitcnt vmcnt(0)
	v_mul_f32_e32 v2, v34, v2
	v_mad_u64_u32 v[34:35], s[22:23], v109, s87, v[32:33]
	global_load_dword v34, v[34:35], off
	v_lshlrev_b32_e32 v35, 2, v109
	global_load_dword v35, v35, s[16:17]
	v_or_b32_e32 v109, s19, v75
	s_waitcnt vmcnt(0)
	v_mul_f32_e32 v34, v34, v35
	v_add_u32_e32 v35, 0x400, v108
	ds_write2_b32 v35, v2, v34 offset0:8 offset1:74
	v_or_b32_e32 v2, s19, v74
	v_mad_u64_u32 v[34:35], s[22:23], v2, s87, v[32:33]
	v_lshlrev_b32_e32 v2, 2, v2
	global_load_dword v34, v[34:35], off
	v_add_u32_e32 v108, v36, v44
	global_load_dword v2, v2, s[16:17]
	s_waitcnt vmcnt(0)
	v_mul_f32_e32 v2, v34, v2
	v_mad_u64_u32 v[34:35], s[22:23], v109, s87, v[32:33]
	global_load_dword v34, v[34:35], off
	v_lshlrev_b32_e32 v35, 2, v109
	global_load_dword v35, v35, s[16:17]
	v_or_b32_e32 v109, s19, v77
	s_waitcnt vmcnt(0)
	v_mul_f32_e32 v34, v34, v35
	ds_write2_b32 v108, v2, v34 offset1:66
	v_or_b32_e32 v2, s19, v76
	v_mad_u64_u32 v[34:35], s[22:23], v2, s87, v[32:33]
	v_lshlrev_b32_e32 v2, 2, v2
	global_load_dword v34, v[34:35], off
	s_nop 0
	global_load_dword v2, v2, s[16:17]
	s_waitcnt vmcnt(0)
	v_mul_f32_e32 v2, v34, v2
	v_mad_u64_u32 v[34:35], s[22:23], v109, s87, v[32:33]
	global_load_dword v34, v[34:35], off
	v_lshlrev_b32_e32 v35, 2, v109
	global_load_dword v35, v35, s[16:17]
	v_or_b32_e32 v109, s19, v79
	s_waitcnt vmcnt(0)
	v_mul_f32_e32 v34, v34, v35
	ds_write2_b32 v108, v2, v34 offset0:132 offset1:198
	v_or_b32_e32 v2, s19, v78
	v_mad_u64_u32 v[34:35], s[22:23], v2, s87, v[32:33]
	v_lshlrev_b32_e32 v2, 2, v2
	global_load_dword v34, v[34:35], off
	s_nop 0
	global_load_dword v2, v2, s[16:17]
	s_waitcnt vmcnt(0)
	v_mul_f32_e32 v2, v34, v2
	v_mad_u64_u32 v[34:35], s[22:23], v109, s87, v[32:33]
	global_load_dword v34, v[34:35], off
	v_lshlrev_b32_e32 v35, 2, v109
	global_load_dword v35, v35, s[16:17]
	v_or_b32_e32 v109, s19, v81
	s_waitcnt vmcnt(0)
	v_mul_f32_e32 v34, v34, v35
	v_add_u32_e32 v35, 0x400, v108
	ds_write2_b32 v35, v2, v34 offset0:8 offset1:74
	v_or_b32_e32 v2, s19, v80
	v_mad_u64_u32 v[34:35], s[22:23], v2, s87, v[32:33]
	v_lshlrev_b32_e32 v2, 2, v2
	global_load_dword v34, v[34:35], off
	v_add_u32_e32 v108, v36, v50
	global_load_dword v2, v2, s[16:17]
	s_waitcnt vmcnt(0)
	v_mul_f32_e32 v2, v34, v2
	v_mad_u64_u32 v[34:35], s[22:23], v109, s87, v[32:33]
	global_load_dword v34, v[34:35], off
	v_lshlrev_b32_e32 v35, 2, v109
	global_load_dword v35, v35, s[16:17]
	v_or_b32_e32 v109, s19, v83
	s_waitcnt vmcnt(0)
	v_mul_f32_e32 v34, v34, v35
	ds_write2_b32 v108, v2, v34 offset1:66
	v_or_b32_e32 v2, s19, v82
	v_mad_u64_u32 v[34:35], s[22:23], v2, s87, v[32:33]
	v_lshlrev_b32_e32 v2, 2, v2
	global_load_dword v34, v[34:35], off
	s_nop 0
	global_load_dword v2, v2, s[16:17]
	s_waitcnt vmcnt(0)
	v_mul_f32_e32 v2, v34, v2
	v_mad_u64_u32 v[34:35], s[22:23], v109, s87, v[32:33]
	global_load_dword v34, v[34:35], off
	v_lshlrev_b32_e32 v35, 2, v109
	global_load_dword v35, v35, s[16:17]
	v_or_b32_e32 v109, s19, v85
	s_waitcnt vmcnt(0)
	v_mul_f32_e32 v34, v34, v35
	ds_write2_b32 v108, v2, v34 offset0:132 offset1:198
	v_or_b32_e32 v2, s19, v84
	v_mad_u64_u32 v[34:35], s[22:23], v2, s87, v[32:33]
	v_lshlrev_b32_e32 v2, 2, v2
	global_load_dword v34, v[34:35], off
	s_nop 0
	global_load_dword v2, v2, s[16:17]
	s_waitcnt vmcnt(0)
	v_mul_f32_e32 v2, v34, v2
	v_mad_u64_u32 v[34:35], s[22:23], v109, s87, v[32:33]
	global_load_dword v34, v[34:35], off
	v_lshlrev_b32_e32 v35, 2, v109
	global_load_dword v35, v35, s[16:17]
	v_or_b32_e32 v109, s19, v87
	s_waitcnt vmcnt(0)
	v_mul_f32_e32 v34, v34, v35
	v_add_u32_e32 v35, 0x400, v108
	ds_write2_b32 v35, v2, v34 offset0:8 offset1:74
	v_or_b32_e32 v2, s19, v86
	v_mad_u64_u32 v[34:35], s[22:23], v2, s87, v[32:33]
	v_lshlrev_b32_e32 v2, 2, v2
	global_load_dword v34, v[34:35], off
	v_add_u32_e32 v108, v36, v56
	global_load_dword v2, v2, s[16:17]
	s_waitcnt vmcnt(0)
; #define GAS __attribute__((address_space(1)))
; #define LAS __attribute__((address_space(3)))
; #define LDS_WAIT() asm volatile("s_waitcnt lgkmcnt(0)" ::: "memory")
; __device__ __forceinline__ unsigned pk2(float lo, float hi) { return f2bf(lo) | (f2bf(hi) << 16); }
; __device__ __forceinline__ void transpose_item(const float* W, int K, int N, bf16* WT, int mode, const float* gain, LAS float* scr, int item, int lane) {
;     ...
;     for (int i = 0; i < 32; ++i) { const int kk = 2 * i + (lane >> 5); float w = W[(size_t)(k0 + kk) * N + n0 + (lane & 31)]; if (gain) w *= gain[k0 + kk]; scr[kk * 33 + (lane & 31)] = w; }
;     LDS_WAIT(); asm volatile("" ::: "memory");
;     const int c = lane & 7;
; #pragma unroll
;     for (int j = 0; j < 4; ++j) { const int n = (lane >> 3) + 8 * j; const LAS float* s = scr + (8 * c) * 33 + n;
;         v4u o; o.x = pk2(s[0 * 33], s[1 * 33]); o.y = pk2(s[2 * 33], s[3 * 33]); o.z = pk2(s[4 * 33], s[5 * 33]); o.w = pk2(s[6 * 33], s[7 * 33]);
;         const int p_ = dst_row(mode, n0 + n), pl_ = p_ & 127, x_ = pl_ & 31, R_ = (pl_ & ~31) + 16 * ((x_ >> 2) & 1) + 4 * (x_ >> 3) + (x_ & 3);
;         *(GAS v4u*)((GAS unsigned char*)WT + ((size_t)(p_ >> 7) * (K / 64) + (k0 >> 6)) * 16384 + pg8::lds_byte(R_, 8 * c)) = o; }
	v_mul_f32_e32 v2, v34, v2
	v_mad_u64_u32 v[34:35], s[22:23], v109, s87, v[32:33]
	global_load_dword v34, v[34:35], off
	v_lshlrev_b32_e32 v35, 2, v109
	global_load_dword v35, v35, s[16:17]
	v_or_b32_e32 v109, s19, v89
	s_waitcnt vmcnt(0)
	v_mul_f32_e32 v34, v34, v35
	ds_write2_b32 v108, v2, v34 offset1:66
	v_or_b32_e32 v2, s19, v88
	v_mad_u64_u32 v[34:35], s[22:23], v2, s87, v[32:33]
	v_lshlrev_b32_e32 v2, 2, v2
	global_load_dword v34, v[34:35], off
	s_nop 0
	global_load_dword v2, v2, s[16:17]
	s_waitcnt vmcnt(0)
	v_mul_f32_e32 v2, v34, v2
	v_mad_u64_u32 v[34:35], s[22:23], v109, s87, v[32:33]
	global_load_dword v34, v[34:35], off
	v_lshlrev_b32_e32 v35, 2, v109
	global_load_dword v35, v35, s[16:17]
	v_or_b32_e32 v109, s19, v91
	s_waitcnt vmcnt(0)
	v_mul_f32_e32 v34, v34, v35
	ds_write2_b32 v108, v2, v34 offset0:132 offset1:198
	v_or_b32_e32 v2, s19, v90
	v_mad_u64_u32 v[34:35], s[22:23], v2, s87, v[32:33]
	v_lshlrev_b32_e32 v2, 2, v2
	global_load_dword v34, v[34:35], off
	s_nop 0
	global_load_dword v2, v2, s[16:17]
	s_waitcnt vmcnt(0)
	v_mul_f32_e32 v2, v34, v2
	v_mad_u64_u32 v[34:35], s[22:23], v109, s87, v[32:33]
	global_load_dword v34, v[34:35], off
	v_lshlrev_b32_e32 v35, 2, v109
	global_load_dword v35, v35, s[16:17]
	v_or_b32_e32 v109, s19, v93
	s_waitcnt vmcnt(0)
	v_mul_f32_e32 v34, v34, v35
	v_add_u32_e32 v35, 0x400, v108
	ds_write2_b32 v35, v2, v34 offset0:8 offset1:74
	v_or_b32_e32 v2, s19, v92
	v_mad_u64_u32 v[34:35], s[22:23], v2, s87, v[32:33]
	v_lshlrev_b32_e32 v2, 2, v2
	global_load_dword v34, v[34:35], off
	v_add_u32_e32 v108, v36, v62
	global_load_dword v2, v2, s[16:17]
	s_waitcnt vmcnt(0)
	v_mul_f32_e32 v2, v34, v2
	v_mad_u64_u32 v[34:35], s[22:23], v109, s87, v[32:33]
	global_load_dword v34, v[34:35], off
	v_lshlrev_b32_e32 v35, 2, v109
	global_load_dword v35, v35, s[16:17]
	v_or_b32_e32 v109, s19, v95
	s_waitcnt vmcnt(0)
	v_mul_f32_e32 v34, v34, v35
	ds_write2_b32 v108, v2, v34 offset1:66
	v_or_b32_e32 v2, s19, v94
	v_mad_u64_u32 v[34:35], s[22:23], v2, s87, v[32:33]
	v_lshlrev_b32_e32 v2, 2, v2
	global_load_dword v34, v[34:35], off
	s_nop 0
	global_load_dword v2, v2, s[16:17]
	s_waitcnt vmcnt(0)
	v_mul_f32_e32 v2, v34, v2
	v_mad_u64_u32 v[34:35], s[22:23], v109, s87, v[32:33]
	global_load_dword v34, v[34:35], off
	v_lshlrev_b32_e32 v35, 2, v109
	global_load_dword v35, v35, s[16:17]
	v_or_b32_e32 v109, s19, v97
	s_waitcnt vmcnt(0)
	v_mul_f32_e32 v34, v34, v35
	ds_write2_b32 v108, v2, v34 offset0:132 offset1:198
	v_or_b32_e32 v2, s19, v96
	v_mad_u64_u32 v[34:35], s[22:23], v2, s87, v[32:33]
	v_lshlrev_b32_e32 v2, 2, v2
	global_load_dword v34, v[34:35], off
	v_add_u32_e32 v108, 0x400, v108
	global_load_dword v2, v2, s[16:17]
	s_waitcnt vmcnt(0)
	v_mul_f32_e32 v2, v34, v2
	v_mad_u64_u32 v[34:35], s[22:23], v109, s87, v[32:33]
	global_load_dword v34, v[34:35], off
	v_lshlrev_b32_e32 v35, 2, v109
	global_load_dword v35, v35, s[16:17]
	s_waitcnt vmcnt(0)
	v_mul_f32_e32 v34, v34, v35
	ds_write2_b32 v108, v2, v34 offset0:8 offset1:74
	v_or_b32_e32 v2, s19, v98
	v_mad_u64_u32 v[34:35], s[22:23], v2, s87, v[32:33]
	v_lshlrev_b32_e32 v2, 2, v2
	global_load_dword v34, v[34:35], off
	s_nop 0
	global_load_dword v2, v2, s[16:17]
	s_waitcnt vmcnt(0)
	v_mul_f32_e32 v2, v34, v2
	v_or_b32_e32 v34, s19, v99
	v_mad_u64_u32 v[32:33], s[22:23], v34, s87, v[32:33]
	global_load_dword v32, v[32:33], off
	v_lshlrev_b32_e32 v33, 2, v34
	global_load_dword v33, v33, s[16:17]
	s_waitcnt vmcnt(0)
	v_mul_f32_e32 v32, v32, v33
	ds_write2_b32 v108, v2, v32 offset0:140 offset1:206
	s_waitcnt lgkmcnt(0)
	ds_read2_b32 v[108:109], v67 offset0:33 offset1:41
	ds_read2_b32 v[110:111], v67 offset1:8
	ds_read2_b32 v[112:113], v67 offset0:66 offset1:74
	ds_read2_b32 v[114:115], v67 offset0:99 offset1:107
	ds_read2_b32 v[116:117], v67 offset0:132 offset1:140
	ds_read2_b32 v[118:119], v67 offset0:165 offset1:173
	ds_read2_b32 v[120:121], v67 offset0:198 offset1:206
	ds_read2_b32 v[122:123], v67 offset0:231 offset1:239
	s_waitcnt lgkmcnt(7)
	s_waitcnt lgkmcnt(6)
	v_cvt_pk_bf16_f32 v32, v110, v108
	s_waitcnt lgkmcnt(5)
	s_waitcnt lgkmcnt(4)
	v_cvt_pk_bf16_f32 v33, v112, v114
	s_waitcnt lgkmcnt(3)
	s_waitcnt lgkmcnt(2)
	v_cvt_pk_bf16_f32 v34, v116, v118
	s_waitcnt lgkmcnt(1)
	v_bfe_u32 v2, v120, 16, 1
	v_add3_u32 v2, v120, v2, s33
	s_waitcnt lgkmcnt(0)
	v_bfe_u32 v35, v122, 16, 1
	v_lshrrev_b32_e32 v2, 16, v2
	v_add3_u32 v35, v122, v35, s33
	v_and_or_b32 v35, v35, s86, v2
	v_or_b32_e32 v2, s3, v100
	v_lshrrev_b32_e32 v2, 3, v2
	v_readlane_b32 s3, v254, 4
	v_or_b32_e32 v2, v2, v64
	s_add_u32 s2, s3, s2
	v_readlane_b32 s3, v254, 6
	v_lshlrev_b32_e32 v2, 10, v2
	s_addc_u32 s3, s3, 0
	v_or_b32_e32 v124, v2, v68
	v_bfe_u32 v108, v123, 16, 1
	v_add3_u32 v108, v123, v108, s33
	global_store_dwordx4 v124, v[32:35], s[2:3]
	v_or_b32_e32 v2, v2, v69
	s_nop 0
	v_bfe_u32 v32, v111, 16, 1
	v_add3_u32 v32, v111, v32, s33
	v_bfe_u32 v33, v109, 16, 1
	v_lshrrev_b32_e32 v32, 16, v32
	v_add3_u32 v33, v109, v33, s33
	v_and_or_b32 v32, v33, s86, v32
	v_cvt_pk_bf16_f32 v33, v113, v115
	v_bfe_u32 v34, v117, 16, 1
	v_add3_u32 v34, v117, v34, s33
	v_bfe_u32 v35, v119, 16, 1
	v_lshrrev_b32_e32 v34, 16, v34
	v_add3_u32 v35, v119, v35, s33
	v_and_or_b32 v34, v35, s86, v34
	v_bfe_u32 v35, v121, 16, 1
	v_add3_u32 v35, v121, v35, s33
	v_lshrrev_b32_e32 v35, 16, v35
	v_and_or_b32 v35, v108, s86, v35
	global_store_dwordx4 v2, v[32:35], s[2:3]
	ds_read2_b32 v[108:109], v67 offset0:16 offset1:24
	ds_read2_b32 v[110:111], v67 offset0:49 offset1:57
	ds_read2_b32 v[112:113], v67 offset0:82 offset1:90
	ds_read2_b32 v[114:115], v67 offset0:115 offset1:123
	ds_read2_b32 v[116:117], v67 offset0:148 offset1:156
	ds_read2_b32 v[118:119], v67 offset0:181 offset1:189
	ds_read2_b32 v[120:121], v67 offset0:214 offset1:222
	ds_read2_b32 v[122:123], v67 offset0:247 offset1:255
	s_waitcnt lgkmcnt(7)
	s_waitcnt lgkmcnt(6)
	v_cvt_pk_bf16_f32 v32, v108, v110
	s_waitcnt lgkmcnt(5)
	s_waitcnt lgkmcnt(4)
	v_cvt_pk_bf16_f32 v33, v112, v114
	s_waitcnt lgkmcnt(3)
	s_waitcnt lgkmcnt(2)
	v_cvt_pk_bf16_f32 v34, v116, v118
	s_waitcnt lgkmcnt(1)
	v_bfe_u32 v2, v120, 16, 1
	v_add3_u32 v2, v120, v2, s33
	s_waitcnt lgkmcnt(0)
	v_bfe_u32 v35, v122, 16, 1
	v_lshrrev_b32_e32 v2, 16, v2
	v_add3_u32 v35, v122, v35, s33
	v_and_or_b32 v35, v35, s86, v2
	v_xor_b32_e32 v2, 32, v124
	v_lshl_add_u64 v[124:125], s[2:3], 0, v[2:3]
	global_store_dwordx4 v[124:125], v[32:35], off offset:512
	v_bfe_u32 v2, v111, 16, 1
	v_add3_u32 v2, v111, v2, s33
	v_bfe_u32 v32, v109, 16, 1
	v_add3_u32 v32, v109, v32, s33
	v_lshrrev_b32_e32 v32, 16, v32
	v_and_or_b32 v32, v2, s86, v32
	v_cvt_pk_bf16_f32 v33, v113, v115
	v_bfe_u32 v35, v121, 16, 1
	v_cvt_pk_bf16_f32 v34, v117, v119
	v_bfe_u32 v2, v123, 16, 1
	v_add3_u32 v35, v121, v35, s33
	v_add3_u32 v2, v123, v2, s33
	v_lshrrev_b32_e32 v35, 16, v35
	v_and_or_b32 v35, v2, s86, v35
	global_store_dwordx4 v[124:125], v[32:35], off offset:768
	s_waitcnt lgkmcnt(0)

; #define GAS __attribute__((address_space(1)))
; #define LAS __attribute__((address_space(3)))
; #define LDS_WAIT() asm volatile("s_waitcnt lgkmcnt(0)" ::: "memory")
; __device__ __forceinline__ unsigned pk2(float lo, float hi) { return f2bf(lo) | (f2bf(hi) << 16); }
; __device__ __forceinline__ void transpose_item(const float* W, int K, int N, bf16* WT, int mode, const float* gain, LAS float* scr, int item, int lane) {
;     ...
;     LDS_WAIT(); asm volatile("" ::: "memory");
;     const int c = lane & 7;
; #pragma unroll
;     for (int j = 0; j < 4; ++j) { const int n = (lane >> 3) + 8 * j; const LAS float* s = scr + (8 * c) * 33 + n;
;         v4u o; o.x = pk2(s[0 * 33], s[1 * 33]); o.y = pk2(s[2 * 33], s[3 * 33]); o.z = pk2(s[4 * 33], s[5 * 33]); o.w = pk2(s[6 * 33], s[7 * 33]);
;         const int p_ = dst_row(mode, n0 + n), pl_ = p_ & 127, x_ = pl_ & 31, R_ = (pl_ & ~31) + 16 * ((x_ >> 2) & 1) + 4 * (x_ >> 3) + (x_ & 3);
;         *(GAS v4u*)((GAS unsigned char*)WT + ((size_t)(p_ >> 7) * (K / 64) + (k0 >> 6)) * 16384 + pg8::lds_byte(R_, 8 * c)) = o; }
.LBB0_188:
	s_waitcnt vmcnt(0)
	ds_write_b32 v34, v32 offset:1848
	s_waitcnt lgkmcnt(0)
	ds_read2_b32 v[108:109], v67 offset1:8
	ds_read2_b32 v[110:111], v67 offset0:33 offset1:41
	ds_read2_b32 v[112:113], v67 offset0:66 offset1:74
	ds_read2_b32 v[114:115], v67 offset0:99 offset1:107
	ds_read2_b32 v[116:117], v67 offset0:132 offset1:140
	s_waitcnt lgkmcnt(4)
	s_waitcnt lgkmcnt(3)
	ds_read2_b32 v[118:119], v67 offset0:165 offset1:173
	v_cvt_pk_bf16_f32 v32, v108, v110
	s_waitcnt lgkmcnt(3)
	s_waitcnt lgkmcnt(2)
	ds_read2_b32 v[120:121], v67 offset0:198 offset1:206
	ds_read2_b32 v[122:123], v67 offset0:231 offset1:239
	v_cvt_pk_bf16_f32 v33, v112, v114
	s_waitcnt lgkmcnt(3)
	s_waitcnt lgkmcnt(2)
	v_cvt_pk_bf16_f32 v34, v116, v118
	s_waitcnt lgkmcnt(1)
	s_lshl_b32 s2, s19, 5
	s_waitcnt lgkmcnt(0)
	s_and_b32 s2, s2, 0x60
	v_cvt_pk_bf16_f32 v35, v120, v122
	v_or_b32_e32 v2, s2, v100
	s_lshl_b32 s2, s19, 3
	s_and_b32 s2, s2, 0x3e0
	s_and_b32 s3, 0xffff, s18
	s_add_i32 s3, s3, s2
	s_lshl_b32 s2, s3, 14
	v_lshrrev_b32_e32 v2, 3, v2
	s_add_i32 s2, s2, 0x40000
	v_or_b32_e32 v2, v2, v64
	s_add_u32 s2, s58, s2
	v_lshlrev_b32_e32 v2, 10, v2
	s_addc_u32 s3, s59, 0
	v_or_b32_e32 v124, v2, v68
	global_store_dwordx4 v124, v[32:35], s[2:3]
	v_bfe_u32 v108, v123, 16, 1
	v_add3_u32 v110, v123, v108, s33
	v_bfe_u32 v32, v109, 16, 1
	v_add3_u32 v32, v109, v32, s33
	v_bfe_u32 v33, v111, 16, 1
	v_lshrrev_b32_e32 v32, 16, v32
	v_add3_u32 v33, v111, v33, s33
	v_and_or_b32 v32, v33, s86, v32
	v_cvt_pk_bf16_f32 v33, v113, v115
	v_cvt_pk_bf16_f32 v34, v117, v119
	v_bfe_u32 v35, v121, 16, 1
	v_add3_u32 v35, v121, v35, s33
	v_lshrrev_b32_e32 v35, 16, v35
	ds_read2_b32 v[108:109], v67 offset0:16 offset1:24
	v_and_or_b32 v35, v110, s86, v35
	ds_read2_b32 v[110:111], v67 offset0:49 offset1:57
	ds_read2_b32 v[112:113], v67 offset0:82 offset1:90
	v_or_b32_e32 v2, v2, v69
	ds_read2_b32 v[114:115], v67 offset0:115 offset1:123
	global_store_dwordx4 v2, v[32:35], s[2:3]
	s_waitcnt lgkmcnt(3)
	v_bfe_u32 v2, v108, 16, 1
	v_add3_u32 v2, v108, v2, s33
	s_waitcnt lgkmcnt(2)
	v_bfe_u32 v32, v110, 16, 1
	ds_read2_b32 v[116:117], v67 offset0:148 offset1:156
	v_lshrrev_b32_e32 v2, 16, v2
	v_add3_u32 v32, v110, v32, s33
	ds_read2_b32 v[118:119], v67 offset0:181 offset1:189
	v_and_or_b32 v32, v32, s86, v2
	s_waitcnt lgkmcnt(3)
	s_waitcnt lgkmcnt(2)
	ds_read2_b32 v[120:121], v67 offset0:214 offset1:222
	ds_read2_b32 v[122:123], v67 offset0:247 offset1:255
	v_cvt_pk_bf16_f32 v33, v112, v114
	s_waitcnt lgkmcnt(3)
	s_waitcnt lgkmcnt(2)
	v_cvt_pk_bf16_f32 v34, v116, v118
	s_waitcnt lgkmcnt(1)
	v_bfe_u32 v2, v120, 16, 1
	v_add3_u32 v2, v120, v2, s33
	s_waitcnt lgkmcnt(0)
	v_bfe_u32 v35, v122, 16, 1
	v_lshrrev_b32_e32 v2, 16, v2
	v_add3_u32 v35, v122, v35, s33
	v_and_or_b32 v35, v35, s86, v2
	v_xor_b32_e32 v2, 32, v124
	v_lshl_add_u64 v[124:125], s[2:3], 0, v[2:3]
	global_store_dwordx4 v[124:125], v[32:35], off offset:512
	v_bfe_u32 v2, v111, 16, 1
	v_add3_u32 v2, v111, v2, s33
	v_bfe_u32 v32, v109, 16, 1
	v_add3_u32 v32, v109, v32, s33
	v_lshrrev_b32_e32 v32, 16, v32
	v_and_or_b32 v32, v2, s86, v32
	v_cvt_pk_bf16_f32 v33, v113, v115
	v_bfe_u32 v35, v121, 16, 1
	v_cvt_pk_bf16_f32 v34, v117, v119
	v_bfe_u32 v2, v123, 16, 1
	v_add3_u32 v35, v121, v35, s33
	v_add3_u32 v2, v123, v2, s33
	v_lshrrev_b32_e32 v35, 16, v35
	v_and_or_b32 v35, v2, s86, v35
	global_store_dwordx4 v[124:125], v[32:35], off offset:768
	s_waitcnt lgkmcnt(0)

; #define GAS __attribute__((address_space(1)))
; #define LAS __attribute__((address_space(3)))
; #define LDS_WAIT() asm volatile("s_waitcnt lgkmcnt(0)" ::: "memory")
; __device__ __forceinline__ unsigned pk2(float lo, float hi) { return f2bf(lo) | (f2bf(hi) << 16); }
; __device__ __forceinline__ void transpose_item(const float* W, int K, int N, bf16* WT, int mode, const float* gain, LAS float* scr, int item, int lane) {
;     ...
;     LDS_WAIT(); asm volatile("" ::: "memory");
;     const int c = lane & 7;
; #pragma unroll
;     for (int j = 0; j < 4; ++j) { const int n = (lane >> 3) + 8 * j; const LAS float* s = scr + (8 * c) * 33 + n;
;         v4u o; o.x = pk2(s[0 * 33], s[1 * 33]); o.y = pk2(s[2 * 33], s[3 * 33]); o.z = pk2(s[4 * 33], s[5 * 33]); o.w = pk2(s[6 * 33], s[7 * 33]);
;         const int p_ = dst_row(mode, n0 + n), pl_ = p_ & 127, x_ = pl_ & 31, R_ = (pl_ & ~31) + 16 * ((x_ >> 2) & 1) + 4 * (x_ >> 3) + (x_ & 3);
;         *(GAS v4u*)((GAS unsigned char*)WT + ((size_t)(p_ >> 7) * (K / 64) + (k0 >> 6)) * 16384 + pg8::lds_byte(R_, 8 * c)) = o; }
.LBB0_255:
	s_waitcnt vmcnt(0)
	ds_write_b32 v34, v32 offset:1848
	s_waitcnt lgkmcnt(0)
	ds_read2_b32 v[108:109], v67 offset1:8
	ds_read2_b32 v[110:111], v67 offset0:33 offset1:41
	ds_read2_b32 v[112:113], v67 offset0:66 offset1:74
	ds_read2_b32 v[114:115], v67 offset0:99 offset1:107
	ds_read2_b32 v[116:117], v67 offset0:132 offset1:140
	s_waitcnt lgkmcnt(4)
	s_waitcnt lgkmcnt(3)
	ds_read2_b32 v[118:119], v67 offset0:165 offset1:173
	v_cvt_pk_bf16_f32 v32, v108, v110
	s_waitcnt lgkmcnt(3)
	s_waitcnt lgkmcnt(2)
	ds_read2_b32 v[120:121], v67 offset0:198 offset1:206
	ds_read2_b32 v[122:123], v67 offset0:231 offset1:239
	v_cvt_pk_bf16_f32 v33, v112, v114
	s_waitcnt lgkmcnt(3)
	s_waitcnt lgkmcnt(2)
	v_cvt_pk_bf16_f32 v34, v116, v118
	s_waitcnt lgkmcnt(1)
	s_lshl_b32 s2, s19, 5
	s_waitcnt lgkmcnt(0)
	s_lshl_b32 s3, s19, 3
	s_and_b32 s2, s2, 0x60
	s_and_b32 s3, s3, 0x3e0
	v_cvt_pk_bf16_f32 v35, v120, v122
	v_or_b32_e32 v2, s2, v100
	s_and_b32 s2, 0xffff, s18
	s_add_i32 s3, s3, s2
	v_lshrrev_b32_e32 v2, 3, v2
	s_lshl_b32 s2, s3, 14
	v_or_b32_e32 v2, v2, v64
	s_add_u32 s2, s58, s2
	v_lshlrev_b32_e32 v2, 10, v2
	s_addc_u32 s3, s59, 0
	v_or_b32_e32 v124, v2, v68
	global_store_dwordx4 v124, v[32:35], s[2:3]
	v_bfe_u32 v108, v123, 16, 1
	v_add3_u32 v110, v123, v108, s33
	v_bfe_u32 v32, v109, 16, 1
	v_add3_u32 v32, v109, v32, s33
	v_bfe_u32 v33, v111, 16, 1
	v_lshrrev_b32_e32 v32, 16, v32
	v_add3_u32 v33, v111, v33, s33
	v_and_or_b32 v32, v33, s86, v32
	v_cvt_pk_bf16_f32 v33, v113, v115
	v_cvt_pk_bf16_f32 v34, v117, v119
	v_bfe_u32 v35, v121, 16, 1
	v_add3_u32 v35, v121, v35, s33
	v_lshrrev_b32_e32 v35, 16, v35
	ds_read2_b32 v[108:109], v67 offset0:16 offset1:24
	v_and_or_b32 v35, v110, s86, v35
	ds_read2_b32 v[110:111], v67 offset0:49 offset1:57
	ds_read2_b32 v[112:113], v67 offset0:82 offset1:90
	v_or_b32_e32 v2, v2, v69
	ds_read2_b32 v[114:115], v67 offset0:115 offset1:123
	global_store_dwordx4 v2, v[32:35], s[2:3]
	s_waitcnt lgkmcnt(3)
	v_bfe_u32 v2, v108, 16, 1
	v_add3_u32 v2, v108, v2, s33
	s_waitcnt lgkmcnt(2)
	v_bfe_u32 v32, v110, 16, 1
	ds_read2_b32 v[116:117], v67 offset0:148 offset1:156
	v_lshrrev_b32_e32 v2, 16, v2
	v_add3_u32 v32, v110, v32, s33
	ds_read2_b32 v[118:119], v67 offset0:181 offset1:189
	v_and_or_b32 v32, v32, s86, v2
	s_waitcnt lgkmcnt(3)
	s_waitcnt lgkmcnt(2)
	ds_read2_b32 v[120:121], v67 offset0:214 offset1:222
	ds_read2_b32 v[122:123], v67 offset0:247 offset1:255
	v_cvt_pk_bf16_f32 v33, v112, v114
	s_waitcnt lgkmcnt(3)
	s_waitcnt lgkmcnt(2)
	v_cvt_pk_bf16_f32 v34, v116, v118
	s_waitcnt lgkmcnt(1)
	v_bfe_u32 v2, v120, 16, 1
	v_add3_u32 v2, v120, v2, s33
	s_waitcnt lgkmcnt(0)
	v_bfe_u32 v35, v122, 16, 1
	v_lshrrev_b32_e32 v2, 16, v2
	v_add3_u32 v35, v122, v35, s33
	v_and_or_b32 v35, v35, s86, v2
	v_xor_b32_e32 v2, 32, v124
	v_lshl_add_u64 v[124:125], s[2:3], 0, v[2:3]
	global_store_dwordx4 v[124:125], v[32:35], off offset:512
	v_bfe_u32 v2, v111, 16, 1
	v_add3_u32 v2, v111, v2, s33
	v_bfe_u32 v32, v109, 16, 1
	v_add3_u32 v32, v109, v32, s33
	v_lshrrev_b32_e32 v32, 16, v32
	v_and_or_b32 v32, v2, s86, v32
	v_cvt_pk_bf16_f32 v33, v113, v115
	v_bfe_u32 v35, v121, 16, 1
	v_cvt_pk_bf16_f32 v34, v117, v119
	v_bfe_u32 v2, v123, 16, 1
	v_add3_u32 v35, v121, v35, s33
	v_add3_u32 v2, v123, v2, s33
	v_lshrrev_b32_e32 v35, 16, v35
	v_and_or_b32 v35, v2, s86, v35
	global_store_dwordx4 v[124:125], v[32:35], off offset:768
	s_waitcnt lgkmcnt(0)

; __device__ __forceinline__ void transpose_item(const float* W, int K, int N, bf16* WT, int mode, const float* gain, LAS float* scr, int item, int lane) {
;     const int nblk = N / 32, kb = item / nblk, nb = item % nblk, k0 = 64 * kb, n0 = 32 * nb;
; #pragma unroll
;     for (int i = 0; i < 32; ++i) { const int kk = 2 * i + (lane >> 5); float w = W[(size_t)(k0 + kk) * N + n0 + (lane & 31)]; if (gain) w *= gain[k0 + kk]; scr[kk * 33 + (lane & 31)] = w; }
.LBB0_257:
	s_andn2_b64 vcc, exec, s[2:3]
	s_cbranch_vccnz .LBB0_259
	s_add_i32 s2, s88, 0xf400
	s_bfe_u32 s2, s2, 0xb0005
	s_lshl_b32 s3, s2, 6
	s_and_b32 s18, s10, 0x3e0
	s_lshl_b32 s56, s18, 2
	v_or_b32_e32 v2, s3, v0
	v_lshl_add_u64 v[32:33], v[24:25], 0, s[56:57]
	v_lshlrev_b32_e32 v2, 12, v2
	v_lshl_add_u64 v[34:35], v[32:33], 0, v[2:3]
	v_or_b32_e32 v2, s3, v38
	v_lshlrev_b32_e32 v2, 12, v2
	global_load_dword v108, v[34:35], off
	v_lshl_add_u64 v[34:35], v[32:33], 0, v[2:3]
	v_or_b32_e32 v2, s3, v70
	v_lshlrev_b32_e32 v2, 12, v2
	global_load_dword v109, v[34:35], off
	v_lshl_add_u64 v[34:35], v[32:33], 0, v[2:3]
	v_or_b32_e32 v2, s3, v71
	v_lshlrev_b32_e32 v2, 12, v2
	global_load_dword v110, v[34:35], off
	v_lshl_add_u64 v[34:35], v[32:33], 0, v[2:3]
	v_or_b32_e32 v2, s3, v72
	v_lshlrev_b32_e32 v2, 12, v2
	global_load_dword v111, v[34:35], off
	v_lshl_add_u64 v[34:35], v[32:33], 0, v[2:3]
	v_or_b32_e32 v2, s3, v73
	v_lshlrev_b32_e32 v2, 12, v2
	global_load_dword v112, v[34:35], off
	v_lshl_add_u64 v[34:35], v[32:33], 0, v[2:3]
	v_or_b32_e32 v2, s3, v74
	v_lshlrev_b32_e32 v2, 12, v2
	global_load_dword v113, v[34:35], off
	v_lshl_add_u64 v[34:35], v[32:33], 0, v[2:3]
	v_or_b32_e32 v2, s3, v75
	v_lshlrev_b32_e32 v2, 12, v2
	global_load_dword v114, v[34:35], off
	v_lshl_add_u64 v[34:35], v[32:33], 0, v[2:3]
	v_or_b32_e32 v2, s3, v76
	v_lshlrev_b32_e32 v2, 12, v2
	global_load_dword v115, v[34:35], off
	v_lshl_add_u64 v[34:35], v[32:33], 0, v[2:3]
	v_or_b32_e32 v2, s3, v77
	v_lshlrev_b32_e32 v2, 12, v2
	global_load_dword v116, v[34:35], off
	v_lshl_add_u64 v[34:35], v[32:33], 0, v[2:3]
	v_or_b32_e32 v2, s3, v78
	v_lshlrev_b32_e32 v2, 12, v2
	global_load_dword v117, v[34:35], off
	v_lshl_add_u64 v[34:35], v[32:33], 0, v[2:3]
	v_or_b32_e32 v2, s3, v79
	v_lshlrev_b32_e32 v2, 12, v2
	global_load_dword v118, v[34:35], off
	v_lshl_add_u64 v[34:35], v[32:33], 0, v[2:3]
	v_or_b32_e32 v2, s3, v80
	v_lshlrev_b32_e32 v2, 12, v2
	global_load_dword v119, v[34:35], off
	v_lshl_add_u64 v[34:35], v[32:33], 0, v[2:3]
	v_or_b32_e32 v2, s3, v81
	v_lshlrev_b32_e32 v2, 12, v2
	global_load_dword v120, v[34:35], off
	v_lshl_add_u64 v[34:35], v[32:33], 0, v[2:3]
	v_or_b32_e32 v2, s3, v82
	v_lshlrev_b32_e32 v2, 12, v2
	global_load_dword v121, v[34:35], off
	v_lshl_add_u64 v[34:35], v[32:33], 0, v[2:3]
	v_or_b32_e32 v2, s3, v83
	v_lshlrev_b32_e32 v2, 12, v2
	global_load_dword v122, v[34:35], off
	v_lshl_add_u64 v[34:35], v[32:33], 0, v[2:3]
	v_or_b32_e32 v2, s3, v84
	v_lshlrev_b32_e32 v2, 12, v2
	global_load_dword v123, v[34:35], off
	v_lshl_add_u64 v[34:35], v[32:33], 0, v[2:3]
	v_or_b32_e32 v2, s3, v85
	v_lshlrev_b32_e32 v2, 12, v2
	global_load_dword v124, v[34:35], off
	v_lshl_add_u64 v[34:35], v[32:33], 0, v[2:3]
	v_or_b32_e32 v2, s3, v86
	v_lshlrev_b32_e32 v2, 12, v2
	global_load_dword v125, v[34:35], off
	v_lshl_add_u64 v[34:35], v[32:33], 0, v[2:3]
	v_or_b32_e32 v2, s3, v87
	v_lshlrev_b32_e32 v2, 12, v2
	global_load_dword v126, v[34:35], off
	v_lshl_add_u64 v[34:35], v[32:33], 0, v[2:3]
	v_or_b32_e32 v2, s3, v88
	v_lshlrev_b32_e32 v2, 12, v2
	global_load_dword v127, v[34:35], off
	v_lshl_add_u64 v[34:35], v[32:33], 0, v[2:3]
	v_or_b32_e32 v2, s3, v89
	v_lshlrev_b32_e32 v2, 12, v2
	global_load_dword v128, v[34:35], off
	v_lshl_add_u64 v[34:35], v[32:33], 0, v[2:3]
	v_or_b32_e32 v2, s3, v90
	v_lshlrev_b32_e32 v2, 12, v2
	global_load_dword v129, v[34:35], off
	v_lshl_add_u64 v[34:35], v[32:33], 0, v[2:3]
	v_or_b32_e32 v2, s3, v91
	v_lshlrev_b32_e32 v2, 12, v2
	global_load_dword v130, v[34:35], off
	v_lshl_add_u64 v[34:35], v[32:33], 0, v[2:3]
	v_or_b32_e32 v2, s3, v92
	v_lshlrev_b32_e32 v2, 12, v2
	global_load_dword v131, v[34:35], off
	v_lshl_add_u64 v[34:35], v[32:33], 0, v[2:3]
	v_or_b32_e32 v2, s3, v93
	v_lshlrev_b32_e32 v2, 12, v2
	global_load_dword v132, v[34:35], off
	v_lshl_add_u64 v[34:35], v[32:33], 0, v[2:3]
	v_or_b32_e32 v2, s3, v94
	v_lshlrev_b32_e32 v2, 12, v2
	global_load_dword v133, v[34:35], off
	v_lshl_add_u64 v[34:35], v[32:33], 0, v[2:3]
	v_or_b32_e32 v2, s3, v95
	v_lshlrev_b32_e32 v2, 12, v2
	global_load_dword v134, v[34:35], off
	v_lshl_add_u64 v[34:35], v[32:33], 0, v[2:3]
	v_or_b32_e32 v2, s3, v96
	v_lshlrev_b32_e32 v2, 12, v2
	global_load_dword v135, v[34:35], off
	v_lshl_add_u64 v[34:35], v[32:33], 0, v[2:3]
	v_or_b32_e32 v2, s3, v97
	v_lshlrev_b32_e32 v2, 12, v2
	global_load_dword v136, v[34:35], off
	v_lshl_add_u64 v[34:35], v[32:33], 0, v[2:3]
	v_or_b32_e32 v2, s3, v98
	v_lshlrev_b32_e32 v2, 12, v2
	global_load_dword v137, v[34:35], off
	v_lshl_add_u64 v[34:35], v[32:33], 0, v[2:3]
	v_or_b32_e32 v2, s3, v99
	v_lshlrev_b32_e32 v2, 12, v2
	v_lshl_add_u64 v[32:33], v[32:33], 0, v[2:3]
	global_load_dword v34, v[34:35], off
	s_and_b32 s3, s10, 0x60
	global_load_dword v2, v[32:33], off
	v_add_u32_e32 v32, v36, v37
	s_waitcnt vmcnt(30)
; #define GAS __attribute__((address_space(1)))
; #define LAS __attribute__((address_space(3)))
; #define LDS_WAIT() asm volatile("s_waitcnt lgkmcnt(0)" ::: "memory")
; __device__ __forceinline__ unsigned pk2(float lo, float hi) { return f2bf(lo) | (f2bf(hi) << 16); }
; __device__ __forceinline__ void transpose_item(const float* W, int K, int N, bf16* WT, int mode, const float* gain, LAS float* scr, int item, int lane) {
;     ...
;     for (int i = 0; i < 32; ++i) { const int kk = 2 * i + (lane >> 5); float w = W[(size_t)(k0 + kk) * N + n0 + (lane & 31)]; if (gain) w *= gain[k0 + kk]; scr[kk * 33 + (lane & 31)] = w; }
;     LDS_WAIT(); asm volatile("" ::: "memory");
;     const int c = lane & 7;
; #pragma unroll
;     for (int j = 0; j < 4; ++j) { const int n = (lane >> 3) + 8 * j; const LAS float* s = scr + (8 * c) * 33 + n;
;         v4u o; o.x = pk2(s[0 * 33], s[1 * 33]); o.y = pk2(s[2 * 33], s[3 * 33]); o.z = pk2(s[4 * 33], s[5 * 33]); o.w = pk2(s[6 * 33], s[7 * 33]);
;         const int p_ = dst_row(mode, n0 + n), pl_ = p_ & 127, x_ = pl_ & 31, R_ = (pl_ & ~31) + 16 * ((x_ >> 2) & 1) + 4 * (x_ >> 3) + (x_ & 3);
;         *(GAS v4u*)((GAS unsigned char*)WT + ((size_t)(p_ >> 7) * (K / 64) + (k0 >> 6)) * 16384 + pg8::lds_byte(R_, 8 * c)) = o; }
	ds_write2_b32 v32, v108, v109 offset1:66
	s_waitcnt vmcnt(28)
	ds_write2_b32 v32, v110, v111 offset0:132 offset1:198
	v_add_u32_e32 v32, 0x400, v32
	s_waitcnt vmcnt(26)
	ds_write2_b32 v32, v112, v113 offset0:8 offset1:74
	v_add_u32_e32 v32, v36, v44
	s_waitcnt vmcnt(24)
	ds_write2_b32 v32, v114, v115 offset1:66
	s_waitcnt vmcnt(22)
	ds_write2_b32 v32, v116, v117 offset0:132 offset1:198
	v_add_u32_e32 v32, 0x400, v32
	s_waitcnt vmcnt(20)
	ds_write2_b32 v32, v118, v119 offset0:8 offset1:74
	v_add_u32_e32 v32, v36, v50
	s_waitcnt vmcnt(18)
	ds_write2_b32 v32, v120, v121 offset1:66
	s_waitcnt vmcnt(16)
	ds_write2_b32 v32, v122, v123 offset0:132 offset1:198
	v_add_u32_e32 v32, 0x400, v32
	s_waitcnt vmcnt(14)
	ds_write2_b32 v32, v124, v125 offset0:8 offset1:74
	v_add_u32_e32 v32, v36, v56
	s_waitcnt vmcnt(12)
	ds_write2_b32 v32, v126, v127 offset1:66
	s_waitcnt vmcnt(10)
	ds_write2_b32 v32, v128, v129 offset0:132 offset1:198
	v_add_u32_e32 v32, 0x400, v32
	s_waitcnt vmcnt(8)
	ds_write2_b32 v32, v130, v131 offset0:8 offset1:74
	v_add_u32_e32 v32, v36, v62
	s_waitcnt vmcnt(6)
	ds_write2_b32 v32, v132, v133 offset1:66
	s_waitcnt vmcnt(4)
	ds_write2_b32 v32, v134, v135 offset0:132 offset1:198
	v_add_u32_e32 v32, 0x400, v32
	s_waitcnt vmcnt(2)
	ds_write2_b32 v32, v136, v137 offset0:8 offset1:74
	s_waitcnt vmcnt(0)
	ds_write2_b32 v32, v34, v2 offset0:140 offset1:206
	s_waitcnt lgkmcnt(0)
	ds_read2_b32 v[108:109], v67 offset1:8
	ds_read2_b32 v[110:111], v67 offset0:33 offset1:41
	ds_read2_b32 v[112:113], v67 offset0:66 offset1:74
	ds_read2_b32 v[114:115], v67 offset0:99 offset1:107
	ds_read2_b32 v[116:117], v67 offset0:132 offset1:140
	s_waitcnt lgkmcnt(4)
	s_waitcnt lgkmcnt(3)
	ds_read2_b32 v[118:119], v67 offset0:165 offset1:173
	v_cvt_pk_bf16_f32 v32, v108, v110
	s_waitcnt lgkmcnt(3)
	s_waitcnt lgkmcnt(2)
	ds_read2_b32 v[120:121], v67 offset0:198 offset1:206
	ds_read2_b32 v[122:123], v67 offset0:231 offset1:239
	v_cvt_pk_bf16_f32 v33, v112, v114
	s_waitcnt lgkmcnt(3)
	s_waitcnt lgkmcnt(2)
	v_cvt_pk_bf16_f32 v34, v116, v118
	s_waitcnt lgkmcnt(1)
	s_waitcnt lgkmcnt(0)
	v_cvt_pk_bf16_f32 v35, v120, v122
	v_or_b32_e32 v2, s3, v100
	s_and_b32 s3, s13, 0x70
	s_add_i32 s2, s2, s3
	v_lshrrev_b32_e32 v2, 3, v2
	s_lshl_b32 s2, s2, 14
	v_or_b32_e32 v2, v2, v64
	s_add_u32 s2, s62, s2
	v_lshlrev_b32_e32 v2, 10, v2
	s_addc_u32 s3, s89, 0
	v_or_b32_e32 v124, v2, v68
	global_store_dwordx4 v124, v[32:35], s[2:3]
	v_bfe_u32 v108, v123, 16, 1
	v_add3_u32 v110, v123, v108, s33
	v_bfe_u32 v32, v109, 16, 1
	v_add3_u32 v32, v109, v32, s33
	v_bfe_u32 v33, v111, 16, 1
	v_lshrrev_b32_e32 v32, 16, v32
	v_add3_u32 v33, v111, v33, s33
	v_and_or_b32 v32, v33, s86, v32
	v_cvt_pk_bf16_f32 v33, v113, v115
	v_cvt_pk_bf16_f32 v34, v117, v119
	v_bfe_u32 v35, v121, 16, 1
	v_add3_u32 v35, v121, v35, s33
	v_lshrrev_b32_e32 v35, 16, v35
	ds_read2_b32 v[108:109], v67 offset0:16 offset1:24
	v_and_or_b32 v35, v110, s86, v35
	ds_read2_b32 v[110:111], v67 offset0:49 offset1:57
	ds_read2_b32 v[112:113], v67 offset0:82 offset1:90
	v_or_b32_e32 v2, v2, v69
	ds_read2_b32 v[114:115], v67 offset0:115 offset1:123
	global_store_dwordx4 v2, v[32:35], s[2:3]
	s_waitcnt lgkmcnt(3)
	v_bfe_u32 v2, v108, 16, 1
	v_add3_u32 v2, v108, v2, s33
	s_waitcnt lgkmcnt(2)
	v_bfe_u32 v32, v110, 16, 1
	ds_read2_b32 v[116:117], v67 offset0:148 offset1:156
	v_lshrrev_b32_e32 v2, 16, v2
	v_add3_u32 v32, v110, v32, s33
	ds_read2_b32 v[118:119], v67 offset0:181 offset1:189
	v_and_or_b32 v32, v32, s86, v2
	s_waitcnt lgkmcnt(3)
	s_waitcnt lgkmcnt(2)
	ds_read2_b32 v[120:121], v67 offset0:214 offset1:222
	ds_read2_b32 v[122:123], v67 offset0:247 offset1:255
	v_cvt_pk_bf16_f32 v33, v112, v114
	s_waitcnt lgkmcnt(3)
	s_waitcnt lgkmcnt(2)
	v_cvt_pk_bf16_f32 v34, v116, v118
	s_waitcnt lgkmcnt(1)
	v_bfe_u32 v2, v120, 16, 1
	v_add3_u32 v2, v120, v2, s33
	s_waitcnt lgkmcnt(0)
	v_bfe_u32 v35, v122, 16, 1
	v_lshrrev_b32_e32 v2, 16, v2
	v_add3_u32 v35, v122, v35, s33
	v_and_or_b32 v35, v35, s86, v2
	v_xor_b32_e32 v2, 32, v124
	v_lshl_add_u64 v[124:125], s[2:3], 0, v[2:3]
	global_store_dwordx4 v[124:125], v[32:35], off offset:512
	v_bfe_u32 v2, v111, 16, 1
	v_add3_u32 v2, v111, v2, s33
	v_bfe_u32 v32, v109, 16, 1
	v_add3_u32 v32, v109, v32, s33
	v_lshrrev_b32_e32 v32, 16, v32
	v_and_or_b32 v32, v2, s86, v32
	v_cvt_pk_bf16_f32 v33, v113, v115
	v_bfe_u32 v35, v121, 16, 1
	v_cvt_pk_bf16_f32 v34, v117, v119
	v_bfe_u32 v2, v123, 16, 1
	v_add3_u32 v35, v121, v35, s33
	v_add3_u32 v2, v123, v2, s33
	v_lshrrev_b32_e32 v35, 16, v35
	v_and_or_b32 v35, v2, s86, v35
	global_store_dwordx4 v[124:125], v[32:35], off offset:768
	s_waitcnt lgkmcnt(0)

; #define GAS __attribute__((address_space(1)))
; #define LAS __attribute__((address_space(3)))
; __device__ __forceinline__ unsigned pk2(float lo, float hi) { return f2bf(lo) | (f2bf(hi) << 16); }
; __device__ __forceinline__ int dst_row(int mode, int n) {
;     ...
;     if (n >= 2048) return n;
;     { const int sec = n >> 10, c = n & 1023, j = c >> 6, i = c & 63; return sec * 1024 + 256 * (j >> 2) + 128 * (i >> 5) + 32 * (j & 3) + (i & 31); }
; __device__ __forceinline__ void transpose_item(const float* W, int K, int N, bf16* WT, int mode, const float* gain, LAS float* scr, int item, int lane) {
;     ...
;     for (int j = 0; j < 4; ++j) { const int n = (lane >> 3) + 8 * j; const LAS float* s = scr + (8 * c) * 33 + n;
;         v4u o; o.x = pk2(s[0 * 33], s[1 * 33]); o.y = pk2(s[2 * 33], s[3 * 33]); o.z = pk2(s[4 * 33], s[5 * 33]); o.w = pk2(s[6 * 33], s[7 * 33]);
;         const int p_ = dst_row(mode, n0 + n), pl_ = p_ & 127, x_ = pl_ & 31, R_ = (pl_ & ~31) + 16 * ((x_ >> 2) & 1) + 4 * (x_ >> 3) + (x_ & 3);
;         *(GAS v4u*)((GAS unsigned char*)WT + ((size_t)(p_ >> 7) * (K / 64) + (k0 >> 6)) * 16384 + pg8::lds_byte(R_, 8 * c)) = o; }
.LBB0_325:
	s_waitcnt vmcnt(0)
	ds_write_b32 v34, v32 offset:1848
	s_waitcnt lgkmcnt(0)
	ds_read2_b32 v[108:109], v67 offset1:8
	ds_read2_b32 v[110:111], v67 offset0:33 offset1:41
	ds_read2_b32 v[112:113], v67 offset0:66 offset1:74
	ds_read2_b32 v[114:115], v67 offset0:99 offset1:107
	ds_read2_b32 v[116:117], v67 offset0:132 offset1:140
	s_waitcnt lgkmcnt(4)
	s_waitcnt lgkmcnt(3)
	ds_read2_b32 v[118:119], v67 offset0:165 offset1:173
	v_cvt_pk_bf16_f32 v32, v108, v110
	s_waitcnt lgkmcnt(3)
	s_waitcnt lgkmcnt(2)
	ds_read2_b32 v[120:121], v67 offset0:198 offset1:206
	ds_read2_b32 v[122:123], v67 offset0:231 offset1:239
	v_cvt_pk_bf16_f32 v33, v112, v114
	s_waitcnt lgkmcnt(3)
	s_waitcnt lgkmcnt(2)
	s_lshl_b32 s21, s19, 4
	s_and_b32 s3, s56, 0x80
	s_and_b32 s21, s21, 0x60
	v_cvt_pk_bf16_f32 v34, v116, v118
	s_waitcnt lgkmcnt(1)
	v_bfe_u32 v2, v120, 16, 1
	s_lshl_b32 s2, s19, 5
	s_or_b32 s3, s21, s3
	v_add3_u32 v2, v120, v2, s33
	s_waitcnt lgkmcnt(0)
	v_bfe_u32 v35, v122, 16, 1
	v_lshrrev_b32_e32 v2, 16, v2
	v_add3_u32 v35, v122, v35, s33
	s_cmp_gt_u32 s19, 63
	v_bitop3_b32 v108, s2, v104, v63 bitop3:0xc8
	v_and_or_b32 v35, v35, s86, v2
	v_or_b32_e32 v2, s2, v63
	v_or_b32_e32 v108, s3, v108
	s_cselect_b64 vcc, -1, 0
	v_cndmask_b32_e32 v108, v108, v2, vcc
	v_and_b32_e32 v2, 0x60, v108
	v_lshlrev_b32_e32 v110, 2, v108
	v_and_or_b32 v110, v110, 16, v2
	v_lshrrev_b32_e32 v2, 3, v108
	v_and_b32_e32 v2, 0x1fff0, v2
	s_and_b32 s18, 0xffff, s18
	v_add_lshl_u32 v2, v2, s18, 14
	v_lshl_add_u64 v[124:125], s[4:5], 0, v[2:3]
	v_lshrrev_b32_e32 v2, 3, v110
	v_or_b32_e32 v2, v2, v64
	v_lshlrev_b32_e32 v108, 6, v108
	v_and_b32_e32 v108, 0xc0, v108
	v_lshlrev_b32_e32 v2, 10, v2
	v_or3_b32 v2, v2, v108, v65
	v_lshl_add_u64 v[124:125], v[124:125], 0, v[2:3]
	v_bfe_u32 v2, v109, 16, 1
	global_store_dwordx4 v[124:125], v[32:35], off
	v_add3_u32 v2, v109, v2, s33
	v_lshrrev_b32_e32 v2, 16, v2
	v_bfe_u32 v32, v111, 16, 1
	v_add3_u32 v32, v111, v32, s33
	v_and_or_b32 v32, v32, s86, v2
	v_cvt_pk_bf16_f32 v33, v113, v115
	v_cvt_pk_bf16_f32 v34, v117, v119
	v_bfe_u32 v2, v121, 16, 1
	v_add3_u32 v2, v121, v2, s33
	v_bfe_u32 v35, v123, 16, 1
	v_lshrrev_b32_e32 v2, 16, v2
	v_add3_u32 v35, v123, v35, s33
	v_bitop3_b32 v108, s2, v105, v101 bitop3:0xc8
	v_and_or_b32 v35, v35, s86, v2
	v_or_b32_e32 v2, s2, v101
	v_or_b32_e32 v108, s3, v108
	v_cndmask_b32_e32 v2, v108, v2, vcc
	v_and_b32_e32 v108, 0x60, v2
	v_lshlrev_b32_e32 v109, 2, v2
	v_and_or_b32 v110, v109, 16, v108
	v_lshrrev_b32_e32 v108, 1, v2
	v_and_b32_e32 v109, 3, v2
	v_lshrrev_b32_e32 v2, 3, v2
	v_and_b32_e32 v2, 0x1fff0, v2
	v_add_lshl_u32 v2, v2, s18, 14
	v_and_or_b32 v111, v108, 4, v109
	v_lshl_add_u64 v[108:109], s[4:5], 0, v[2:3]
	v_lshrrev_b32_e32 v2, 3, v110
	v_or_b32_e32 v2, v2, v64
	v_lshlrev_b32_e32 v112, 6, v111
	v_lshlrev_b32_e32 v2, 10, v2
	v_or3_b32 v2, v2, v112, v65
	ds_read2_b32 v[110:111], v67 offset0:16 offset1:24
	v_lshl_add_u64 v[108:109], v[108:109], 0, v[2:3]
	global_store_dwordx4 v[108:109], v[32:35], off
	ds_read2_b32 v[108:109], v67 offset0:49 offset1:57
	ds_read2_b32 v[112:113], v67 offset0:82 offset1:90
	ds_read2_b32 v[114:115], v67 offset0:115 offset1:123
	s_waitcnt lgkmcnt(3)
	v_bfe_u32 v2, v110, 16, 1
	v_add3_u32 v2, v110, v2, s33
	s_waitcnt lgkmcnt(2)
	v_bfe_u32 v32, v108, 16, 1
	ds_read2_b32 v[116:117], v67 offset0:148 offset1:156
	v_lshrrev_b32_e32 v2, 16, v2
	v_add3_u32 v32, v108, v32, s33
	ds_read2_b32 v[118:119], v67 offset0:181 offset1:189
	v_and_or_b32 v32, v32, s86, v2
	s_waitcnt lgkmcnt(3)
	s_waitcnt lgkmcnt(2)
	ds_read2_b32 v[120:121], v67 offset0:214 offset1:222
	ds_read2_b32 v[122:123], v67 offset0:247 offset1:255
	v_cvt_pk_bf16_f32 v33, v112, v114
	s_waitcnt lgkmcnt(3)
	s_waitcnt lgkmcnt(2)
	v_cvt_pk_bf16_f32 v34, v116, v118
	s_waitcnt lgkmcnt(1)
	v_bfe_u32 v2, v120, 16, 1
	v_add3_u32 v2, v120, v2, s33
	s_waitcnt lgkmcnt(0)
	v_bfe_u32 v35, v122, 16, 1
	v_lshrrev_b32_e32 v2, 16, v2
	v_add3_u32 v35, v122, v35, s33
	v_bitop3_b32 v108, s2, v106, v102 bitop3:0xc8
	v_and_or_b32 v35, v35, s86, v2
	v_or_b32_e32 v2, s2, v102
	v_or_b32_e32 v108, s3, v108
	v_cndmask_b32_e32 v2, v108, v2, vcc
	v_and_b32_e32 v108, 0x60, v2
	v_lshlrev_b32_e32 v110, 2, v2
	v_and_or_b32 v108, v110, 16, v108
	v_lshrrev_b32_e32 v110, 1, v2
	v_and_b32_e32 v110, 8, v110
	v_and_or_b32 v112, v2, 3, v110
	v_lshrrev_b32_e32 v2, 3, v2
	v_and_b32_e32 v2, 0x1fff0, v2
	v_add_lshl_u32 v2, v2, s18, 14
	v_lshl_add_u64 v[124:125], s[4:5], 0, v[2:3]
	v_lshrrev_b32_e32 v2, 3, v108
	v_or_b32_e32 v2, v2, v64
	v_lshl_or_b32 v108, v112, 6, v65
	v_lshlrev_b32_e32 v2, 10, v2
	v_lshlrev_b32_e32 v110, 2, v110
	v_bitop3_b32 v2, v108, v2, v110 bitop3:0xde
	v_lshl_add_u64 v[124:125], v[124:125], 0, v[2:3]
	global_store_dwordx4 v[124:125], v[32:35], off
	v_or_b32_e32 v2, s2, v103
	s_nop 0
	v_bitop3_b32 v32, s2, v107, v103 bitop3:0xc8
	v_or_b32_e32 v32, s3, v32
	v_cndmask_b32_e32 v110, v32, v2, vcc
	v_bfe_u32 v32, v111, 16, 1
	v_bfe_u32 v2, v109, 16, 1
	v_add3_u32 v32, v111, v32, s33
	v_add3_u32 v2, v109, v2, s33
	v_lshrrev_b32_e32 v32, 16, v32
	v_and_or_b32 v32, v2, s86, v32
	v_cvt_pk_bf16_f32 v33, v113, v115
	v_cvt_pk_bf16_f32 v34, v117, v119
	v_cvt_pk_bf16_f32 v35, v121, v123
	v_and_b32_e32 v2, 0x60, v110
	v_lshlrev_b32_e32 v108, 2, v110
	v_and_or_b32 v111, v108, 16, v2
	v_lshrrev_b32_e32 v2, 1, v110
	v_and_b32_e32 v108, 3, v110
	v_and_or_b32 v112, v2, 12, v108
	v_lshrrev_b32_e32 v2, 3, v110
	v_and_b32_e32 v2, 0x1fff0, v2
	v_add_lshl_u32 v2, v2, s18, 14
	v_lshl_add_u64 v[108:109], s[4:5], 0, v[2:3]
	v_lshrrev_b32_e32 v2, 3, v111
	v_or_b32_e32 v2, v2, v64
	v_lshlrev_b32_e32 v110, 1, v110
	v_lshl_or_b32 v111, v112, 6, v65
	v_lshlrev_b32_e32 v2, 10, v2
	v_and_b32_e32 v110, 32, v110
	v_bitop3_b32 v2, v111, v2, v110 bitop3:0xde
	v_lshl_add_u64 v[108:109], v[108:109], 0, v[2:3]
	global_store_dwordx4 v[108:109], v[32:35], off
	s_waitcnt lgkmcnt(0)

; __device__ __forceinline__ void transpose_item(const float* W, int K, int N, bf16* WT, int mode, const float* gain, LAS float* scr, int item, int lane) {
;     const int nblk = N / 32, kb = item / nblk, nb = item % nblk, k0 = 64 * kb, n0 = 32 * nb;
; #pragma unroll
;     for (int i = 0; i < 32; ++i) { const int kk = 2 * i + (lane >> 5); float w = W[(size_t)(k0 + kk) * N + n0 + (lane & 31)]; if (gain) w *= gain[k0 + kk]; scr[kk * 33 + (lane & 31)] = w; }
.LBB0_327:
	s_andn2_b64 vcc, exec, s[2:3]
	s_cbranch_vccnz .LBB0_329
	s_add_i32 s2, s88, 0xfc00
	s_bfe_u32 s2, s2, 0xb0005
	s_lshl_b32 s3, s2, 6
	s_and_b32 s18, s10, 0x3e0
	s_lshl_b32 s56, s18, 2
	v_or_b32_e32 v2, s3, v0
	v_lshl_add_u64 v[32:33], v[28:29], 0, s[56:57]
	v_lshlrev_b32_e32 v2, 12, v2
	v_lshl_add_u64 v[34:35], v[32:33], 0, v[2:3]
	v_or_b32_e32 v2, s3, v38
	v_lshlrev_b32_e32 v2, 12, v2
	global_load_dword v108, v[34:35], off
	v_lshl_add_u64 v[34:35], v[32:33], 0, v[2:3]
	v_or_b32_e32 v2, s3, v70
	v_lshlrev_b32_e32 v2, 12, v2
	global_load_dword v109, v[34:35], off
	v_lshl_add_u64 v[34:35], v[32:33], 0, v[2:3]
	v_or_b32_e32 v2, s3, v71
	v_lshlrev_b32_e32 v2, 12, v2
	global_load_dword v110, v[34:35], off
	v_lshl_add_u64 v[34:35], v[32:33], 0, v[2:3]
	v_or_b32_e32 v2, s3, v72
	v_lshlrev_b32_e32 v2, 12, v2
	global_load_dword v111, v[34:35], off
	v_lshl_add_u64 v[34:35], v[32:33], 0, v[2:3]
	v_or_b32_e32 v2, s3, v73
	v_lshlrev_b32_e32 v2, 12, v2
	global_load_dword v112, v[34:35], off
	v_lshl_add_u64 v[34:35], v[32:33], 0, v[2:3]
	v_or_b32_e32 v2, s3, v74
	v_lshlrev_b32_e32 v2, 12, v2
	global_load_dword v113, v[34:35], off
	v_lshl_add_u64 v[34:35], v[32:33], 0, v[2:3]
	v_or_b32_e32 v2, s3, v75
	v_lshlrev_b32_e32 v2, 12, v2
	global_load_dword v114, v[34:35], off
	v_lshl_add_u64 v[34:35], v[32:33], 0, v[2:3]
	v_or_b32_e32 v2, s3, v76
	v_lshlrev_b32_e32 v2, 12, v2
	global_load_dword v115, v[34:35], off
	v_lshl_add_u64 v[34:35], v[32:33], 0, v[2:3]
	v_or_b32_e32 v2, s3, v77
	v_lshlrev_b32_e32 v2, 12, v2
	global_load_dword v116, v[34:35], off
	v_lshl_add_u64 v[34:35], v[32:33], 0, v[2:3]
	v_or_b32_e32 v2, s3, v78
	v_lshlrev_b32_e32 v2, 12, v2
	global_load_dword v117, v[34:35], off
	v_lshl_add_u64 v[34:35], v[32:33], 0, v[2:3]
	v_or_b32_e32 v2, s3, v79
	v_lshlrev_b32_e32 v2, 12, v2
	global_load_dword v118, v[34:35], off
	v_lshl_add_u64 v[34:35], v[32:33], 0, v[2:3]
	v_or_b32_e32 v2, s3, v80
	v_lshlrev_b32_e32 v2, 12, v2
	global_load_dword v119, v[34:35], off
	v_lshl_add_u64 v[34:35], v[32:33], 0, v[2:3]
	v_or_b32_e32 v2, s3, v81
	v_lshlrev_b32_e32 v2, 12, v2
	global_load_dword v120, v[34:35], off
	v_lshl_add_u64 v[34:35], v[32:33], 0, v[2:3]
	v_or_b32_e32 v2, s3, v82
	v_lshlrev_b32_e32 v2, 12, v2
	global_load_dword v121, v[34:35], off
	v_lshl_add_u64 v[34:35], v[32:33], 0, v[2:3]
	v_or_b32_e32 v2, s3, v83
	v_lshlrev_b32_e32 v2, 12, v2
	global_load_dword v122, v[34:35], off
	v_lshl_add_u64 v[34:35], v[32:33], 0, v[2:3]
	v_or_b32_e32 v2, s3, v84
	v_lshlrev_b32_e32 v2, 12, v2
	global_load_dword v123, v[34:35], off
	v_lshl_add_u64 v[34:35], v[32:33], 0, v[2:3]
	v_or_b32_e32 v2, s3, v85
	v_lshlrev_b32_e32 v2, 12, v2
	global_load_dword v124, v[34:35], off
	v_lshl_add_u64 v[34:35], v[32:33], 0, v[2:3]
	v_or_b32_e32 v2, s3, v86
	v_lshlrev_b32_e32 v2, 12, v2
	global_load_dword v125, v[34:35], off
	v_lshl_add_u64 v[34:35], v[32:33], 0, v[2:3]
	v_or_b32_e32 v2, s3, v87
	v_lshlrev_b32_e32 v2, 12, v2
	global_load_dword v126, v[34:35], off
	v_lshl_add_u64 v[34:35], v[32:33], 0, v[2:3]
	v_or_b32_e32 v2, s3, v88
	v_lshlrev_b32_e32 v2, 12, v2
	global_load_dword v127, v[34:35], off
	v_lshl_add_u64 v[34:35], v[32:33], 0, v[2:3]
	v_or_b32_e32 v2, s3, v89
	v_lshlrev_b32_e32 v2, 12, v2
	global_load_dword v128, v[34:35], off
	v_lshl_add_u64 v[34:35], v[32:33], 0, v[2:3]
	v_or_b32_e32 v2, s3, v90
	v_lshlrev_b32_e32 v2, 12, v2
	global_load_dword v129, v[34:35], off
	v_lshl_add_u64 v[34:35], v[32:33], 0, v[2:3]
	v_or_b32_e32 v2, s3, v91
	v_lshlrev_b32_e32 v2, 12, v2
	global_load_dword v130, v[34:35], off
	v_lshl_add_u64 v[34:35], v[32:33], 0, v[2:3]
	v_or_b32_e32 v2, s3, v92
	v_lshlrev_b32_e32 v2, 12, v2
	global_load_dword v131, v[34:35], off
	v_lshl_add_u64 v[34:35], v[32:33], 0, v[2:3]
	v_or_b32_e32 v2, s3, v93
	v_lshlrev_b32_e32 v2, 12, v2
	global_load_dword v132, v[34:35], off
	v_lshl_add_u64 v[34:35], v[32:33], 0, v[2:3]
	v_or_b32_e32 v2, s3, v94
	v_lshlrev_b32_e32 v2, 12, v2
	global_load_dword v133, v[34:35], off
	v_lshl_add_u64 v[34:35], v[32:33], 0, v[2:3]
	v_or_b32_e32 v2, s3, v95
	v_lshlrev_b32_e32 v2, 12, v2
	global_load_dword v134, v[34:35], off
	v_lshl_add_u64 v[34:35], v[32:33], 0, v[2:3]
	v_or_b32_e32 v2, s3, v96
	v_lshlrev_b32_e32 v2, 12, v2
	global_load_dword v135, v[34:35], off
	v_lshl_add_u64 v[34:35], v[32:33], 0, v[2:3]
	v_or_b32_e32 v2, s3, v97
	v_lshlrev_b32_e32 v2, 12, v2
	global_load_dword v136, v[34:35], off
	v_lshl_add_u64 v[34:35], v[32:33], 0, v[2:3]
	v_or_b32_e32 v2, s3, v98
	v_lshlrev_b32_e32 v2, 12, v2
	global_load_dword v137, v[34:35], off
	v_lshl_add_u64 v[34:35], v[32:33], 0, v[2:3]
	v_or_b32_e32 v2, s3, v99
	v_lshlrev_b32_e32 v2, 12, v2
	v_lshl_add_u64 v[32:33], v[32:33], 0, v[2:3]
	global_load_dword v34, v[34:35], off
	s_and_b32 s3, s10, 0x60
	global_load_dword v2, v[32:33], off
	v_add_u32_e32 v32, v36, v37
	s_waitcnt vmcnt(30)
; #define GAS __attribute__((address_space(1)))
; #define LAS __attribute__((address_space(3)))
; #define LDS_WAIT() asm volatile("s_waitcnt lgkmcnt(0)" ::: "memory")
; __device__ __forceinline__ unsigned pk2(float lo, float hi) { return f2bf(lo) | (f2bf(hi) << 16); }
; __device__ __forceinline__ void transpose_item(const float* W, int K, int N, bf16* WT, int mode, const float* gain, LAS float* scr, int item, int lane) {
;     ...
;     for (int i = 0; i < 32; ++i) { const int kk = 2 * i + (lane >> 5); float w = W[(size_t)(k0 + kk) * N + n0 + (lane & 31)]; if (gain) w *= gain[k0 + kk]; scr[kk * 33 + (lane & 31)] = w; }
;     LDS_WAIT(); asm volatile("" ::: "memory");
;     const int c = lane & 7;
; #pragma unroll
;     for (int j = 0; j < 4; ++j) { const int n = (lane >> 3) + 8 * j; const LAS float* s = scr + (8 * c) * 33 + n;
;         v4u o; o.x = pk2(s[0 * 33], s[1 * 33]); o.y = pk2(s[2 * 33], s[3 * 33]); o.z = pk2(s[4 * 33], s[5 * 33]); o.w = pk2(s[6 * 33], s[7 * 33]);
;         const int p_ = dst_row(mode, n0 + n), pl_ = p_ & 127, x_ = pl_ & 31, R_ = (pl_ & ~31) + 16 * ((x_ >> 2) & 1) + 4 * (x_ >> 3) + (x_ & 3);
;         *(GAS v4u*)((GAS unsigned char*)WT + ((size_t)(p_ >> 7) * (K / 64) + (k0 >> 6)) * 16384 + pg8::lds_byte(R_, 8 * c)) = o; }
	ds_write2_b32 v32, v108, v109 offset1:66
	s_waitcnt vmcnt(28)
	ds_write2_b32 v32, v110, v111 offset0:132 offset1:198
	v_add_u32_e32 v32, 0x400, v32
	s_waitcnt vmcnt(26)
	ds_write2_b32 v32, v112, v113 offset0:8 offset1:74
	v_add_u32_e32 v32, v36, v44
	s_waitcnt vmcnt(24)
	ds_write2_b32 v32, v114, v115 offset1:66
	s_waitcnt vmcnt(22)
	ds_write2_b32 v32, v116, v117 offset0:132 offset1:198
	v_add_u32_e32 v32, 0x400, v32
	s_waitcnt vmcnt(20)
	ds_write2_b32 v32, v118, v119 offset0:8 offset1:74
	v_add_u32_e32 v32, v36, v50
	s_waitcnt vmcnt(18)
	ds_write2_b32 v32, v120, v121 offset1:66
	s_waitcnt vmcnt(16)
	ds_write2_b32 v32, v122, v123 offset0:132 offset1:198
	v_add_u32_e32 v32, 0x400, v32
	s_waitcnt vmcnt(14)
	ds_write2_b32 v32, v124, v125 offset0:8 offset1:74
	v_add_u32_e32 v32, v36, v56
	s_waitcnt vmcnt(12)
	ds_write2_b32 v32, v126, v127 offset1:66
	s_waitcnt vmcnt(10)
	ds_write2_b32 v32, v128, v129 offset0:132 offset1:198
	v_add_u32_e32 v32, 0x400, v32
	s_waitcnt vmcnt(8)
	ds_write2_b32 v32, v130, v131 offset0:8 offset1:74
	v_add_u32_e32 v32, v36, v62
	s_waitcnt vmcnt(6)
	ds_write2_b32 v32, v132, v133 offset1:66
	s_waitcnt vmcnt(4)
	ds_write2_b32 v32, v134, v135 offset0:132 offset1:198
	v_add_u32_e32 v32, 0x400, v32
	s_waitcnt vmcnt(2)
	ds_write2_b32 v32, v136, v137 offset0:8 offset1:74
	s_waitcnt vmcnt(0)
	ds_write2_b32 v32, v34, v2 offset0:140 offset1:206
	s_waitcnt lgkmcnt(0)
	ds_read2_b32 v[108:109], v67 offset1:8
	ds_read2_b32 v[110:111], v67 offset0:33 offset1:41
	ds_read2_b32 v[112:113], v67 offset0:66 offset1:74
	ds_read2_b32 v[114:115], v67 offset0:99 offset1:107
	ds_read2_b32 v[116:117], v67 offset0:132 offset1:140
	s_waitcnt lgkmcnt(4)
	s_waitcnt lgkmcnt(3)
	ds_read2_b32 v[118:119], v67 offset0:165 offset1:173
	v_cvt_pk_bf16_f32 v32, v108, v110
	s_waitcnt lgkmcnt(3)
	s_waitcnt lgkmcnt(2)
	ds_read2_b32 v[120:121], v67 offset0:198 offset1:206
	ds_read2_b32 v[122:123], v67 offset0:231 offset1:239
	v_cvt_pk_bf16_f32 v33, v112, v114
	s_waitcnt lgkmcnt(3)
	s_waitcnt lgkmcnt(2)
	v_cvt_pk_bf16_f32 v34, v116, v118
	s_waitcnt lgkmcnt(1)
	s_waitcnt lgkmcnt(0)
	v_cvt_pk_bf16_f32 v35, v120, v122
	v_or_b32_e32 v2, s3, v100
	s_and_b32 s3, s13, 0x70
	s_add_i32 s2, s2, s3
	v_lshrrev_b32_e32 v2, 3, v2
	s_lshl_b32 s2, s2, 14
	v_or_b32_e32 v2, v2, v64
	s_add_u32 s2, s90, s2
	v_lshlrev_b32_e32 v2, 10, v2
	s_addc_u32 s3, s91, 0
	v_or_b32_e32 v124, v2, v68
	global_store_dwordx4 v124, v[32:35], s[2:3]
	v_bfe_u32 v108, v123, 16, 1
	v_add3_u32 v110, v123, v108, s33
	v_bfe_u32 v32, v109, 16, 1
	v_add3_u32 v32, v109, v32, s33
	v_bfe_u32 v33, v111, 16, 1
	v_lshrrev_b32_e32 v32, 16, v32
	v_add3_u32 v33, v111, v33, s33
	v_and_or_b32 v32, v33, s86, v32
	v_cvt_pk_bf16_f32 v33, v113, v115
	v_cvt_pk_bf16_f32 v34, v117, v119
	v_bfe_u32 v35, v121, 16, 1
	v_add3_u32 v35, v121, v35, s33
	v_lshrrev_b32_e32 v35, 16, v35
	ds_read2_b32 v[108:109], v67 offset0:16 offset1:24
	v_and_or_b32 v35, v110, s86, v35
	ds_read2_b32 v[110:111], v67 offset0:49 offset1:57
	ds_read2_b32 v[112:113], v67 offset0:82 offset1:90
	v_or_b32_e32 v2, v2, v69
	ds_read2_b32 v[114:115], v67 offset0:115 offset1:123
	global_store_dwordx4 v2, v[32:35], s[2:3]
	s_waitcnt lgkmcnt(3)
	v_bfe_u32 v2, v108, 16, 1
	v_add3_u32 v2, v108, v2, s33
	s_waitcnt lgkmcnt(2)
	v_bfe_u32 v32, v110, 16, 1
	ds_read2_b32 v[116:117], v67 offset0:148 offset1:156
	v_lshrrev_b32_e32 v2, 16, v2
	v_add3_u32 v32, v110, v32, s33
	ds_read2_b32 v[118:119], v67 offset0:181 offset1:189
	v_and_or_b32 v32, v32, s86, v2
	s_waitcnt lgkmcnt(3)
	s_waitcnt lgkmcnt(2)
	ds_read2_b32 v[120:121], v67 offset0:214 offset1:222
	ds_read2_b32 v[122:123], v67 offset0:247 offset1:255
	v_cvt_pk_bf16_f32 v33, v112, v114
	s_waitcnt lgkmcnt(3)
	s_waitcnt lgkmcnt(2)
	v_cvt_pk_bf16_f32 v34, v116, v118
	s_waitcnt lgkmcnt(1)
	v_bfe_u32 v2, v120, 16, 1
	v_add3_u32 v2, v120, v2, s33
	s_waitcnt lgkmcnt(0)
	v_bfe_u32 v35, v122, 16, 1
	v_lshrrev_b32_e32 v2, 16, v2
	v_add3_u32 v35, v122, v35, s33
	v_and_or_b32 v35, v35, s86, v2
	v_xor_b32_e32 v2, 32, v124
	v_lshl_add_u64 v[124:125], s[2:3], 0, v[2:3]
	global_store_dwordx4 v[124:125], v[32:35], off offset:512
	v_bfe_u32 v2, v111, 16, 1
	v_add3_u32 v2, v111, v2, s33
	v_bfe_u32 v32, v109, 16, 1
	v_add3_u32 v32, v109, v32, s33
	v_lshrrev_b32_e32 v32, 16, v32
	v_and_or_b32 v32, v2, s86, v32
	v_cvt_pk_bf16_f32 v33, v113, v115
	v_bfe_u32 v35, v121, 16, 1
	v_cvt_pk_bf16_f32 v34, v117, v119
	v_bfe_u32 v2, v123, 16, 1
	v_add3_u32 v35, v121, v35, s33
	v_add3_u32 v2, v123, v2, s33
	v_lshrrev_b32_e32 v35, 16, v35
	v_and_or_b32 v35, v2, s86, v35
	global_store_dwordx4 v[124:125], v[32:35], off offset:768
	s_waitcnt lgkmcnt(0)

; #define GAS __attribute__((address_space(1)))
; __device__ __forceinline__ void p0_prologue(const Args& a, LAS unsigned char* lds, int vcu, int G, int wave, int lane) {
;     ...
;           f32x4 v[4][4]; float s[4];
; #pragma unroll
;           for (int r = 0; r < 4; ++r) { const GAS f32x4* xr = (const GAS f32x4*)(x + (size_t)(m0 + r) * D) + lane;
; #pragma unroll
;               for (int j = 0; j < 4; ++j) v[r][j] = xr[64 * j]; }
; #pragma unroll
;           for (int r = 0; r < 4; ++r) { float t = 0.f;
; #pragma unroll
;               for (int j = 0; j < 4; ++j) t += (v[r][j].x * v[r][j].x + v[r][j].y * v[r][j].y) + (v[r][j].z * v[r][j].z + v[r][j].w * v[r][j].w);
;               s[r] = wave_sum(t); }
.LBB0_398:
	v_add_co_u32_e32 v0, vcc, 0xffffd000, v70
	global_load_dwordx4 v[12:15], v[70:71], off offset:-3072
	global_load_dwordx4 v[4:7], v[70:71], off offset:-2048
	v_addc_co_u32_e32 v1, vcc, -1, v71, vcc
	global_load_dwordx4 v[60:63], v[0:1], off offset:-3072
	global_load_dwordx4 v[56:59], v[0:1], off offset:-2048
	global_load_dwordx4 v[52:55], v[0:1], off offset:-1024
	global_load_dwordx4 v[48:51], v[0:1], off
	v_add_co_u32_e32 v0, vcc, 0xffffe000, v70
	s_ashr_i32 s18, s6, 7
	s_nop 0
	v_addc_co_u32_e32 v1, vcc, -1, v71, vcc
	global_load_dwordx4 v[44:47], v[0:1], off offset:-3072
	global_load_dwordx4 v[40:43], v[0:1], off offset:-2048
	global_load_dwordx4 v[36:39], v[0:1], off offset:-1024
	global_load_dwordx4 v[32:35], v[0:1], off
	v_add_co_u32_e32 v0, vcc, 0xfffff000, v70
	s_ashr_i32 s19, s18, 31
	s_nop 0
	v_addc_co_u32_e32 v1, vcc, -1, v71, vcc
	global_load_dwordx4 v[28:31], v[0:1], off offset:-3072
	global_load_dwordx4 v[24:27], v[0:1], off offset:-2048
	global_load_dwordx4 v[20:23], v[0:1], off offset:-1024
	global_load_dwordx4 v[16:19], v[70:71], off offset:-4096
	global_load_dwordx4 v[8:11], v[70:71], off offset:-1024
	s_nop 0
	global_load_dwordx4 v[0:3], v[70:71], off
	s_lshr_b32 s21, s6, 3
	s_lshl_b64 s[18:19], s[18:19], 18
	s_add_u32 s24, s34, s18
	s_addc_u32 s25, s35, s19
	s_and_b32 s18, s13, 0x300
	s_waitcnt vmcnt(15)
	v_mul_f32_e32 v65, v13, v13
	s_waitcnt vmcnt(13)
	v_mul_f32_e32 v77, v61, v61
	s_waitcnt lgkmcnt(0)
	v_mul_f32_e32 v92, v63, v63
	s_waitcnt vmcnt(12)
	v_mul_f32_e32 v93, v57, v57
	v_mul_f32_e32 v94, v59, v59
	s_waitcnt vmcnt(11)
	v_mul_f32_e32 v95, v53, v53
	v_mul_f32_e32 v96, v55, v55
	v_fmac_f32_e32 v77, v60, v60
	v_fmac_f32_e32 v92, v62, v62
	v_fmac_f32_e32 v93, v56, v56
	v_fmac_f32_e32 v94, v58, v58
	s_waitcnt vmcnt(10)
	v_mul_f32_e32 v97, v49, v49
	v_mul_f32_e32 v98, v51, v51
	v_fmac_f32_e32 v95, v52, v52
	v_fmac_f32_e32 v96, v54, v54
	v_add_f32_e32 v77, v77, v92
	v_add_f32_e32 v92, v93, v94
	v_fmac_f32_e32 v97, v48, v48
	v_fmac_f32_e32 v98, v50, v50
	v_add_f32_e32 v93, v95, v96
	v_add_f32_e32 v77, v77, v92
	v_add_f32_e32 v94, v97, v98
	v_add_f32_e32 v77, v77, v93
	v_add_f32_e32 v77, v77, v94
	ds_bpermute_b32 v93, v84, v77
	v_mul_f32_e32 v73, v15, v15
	v_fmac_f32_e32 v65, v12, v12
	v_fmac_f32_e32 v73, v14, v14
	v_add_f32_e32 v65, v65, v73
	s_waitcnt lgkmcnt(0)
	v_add_f32_e32 v77, v77, v93
	s_waitcnt vmcnt(9)
	v_mul_f32_e32 v73, v45, v45
	v_mul_f32_e32 v99, v47, v47
	s_waitcnt vmcnt(8)
	v_mul_f32_e32 v100, v41, v41
	v_mul_f32_e32 v101, v43, v43
	ds_bpermute_b32 v93, v85, v77
	v_fmac_f32_e32 v73, v44, v44
	v_fmac_f32_e32 v99, v46, v46
	v_fmac_f32_e32 v100, v40, v40
	v_fmac_f32_e32 v101, v42, v42
	s_waitcnt vmcnt(5)
	v_mul_f32_e32 v95, v29, v29
	v_mul_f32_e32 v96, v31, v31
	s_waitcnt vmcnt(4)
	v_mul_f32_e32 v97, v25, v25
	v_mul_f32_e32 v98, v27, v27
	s_waitcnt vmcnt(3)
	v_mul_f32_e32 v106, v21, v21
	v_mul_f32_e32 v107, v23, v23
	v_add_f32_e32 v73, v73, v99
	v_add_f32_e32 v92, v100, v101
	v_fmac_f32_e32 v95, v28, v28
	v_fmac_f32_e32 v96, v30, v30
	v_fmac_f32_e32 v97, v24, v24
	v_fmac_f32_e32 v98, v26, v26
	s_waitcnt vmcnt(2)
	v_mul_f32_e32 v108, v17, v17
	v_mul_f32_e32 v109, v19, v19
	v_fmac_f32_e32 v106, v20, v20
	v_fmac_f32_e32 v107, v22, v22
	v_add_f32_e32 v73, v73, v92
	v_add_f32_e32 v92, v95, v96
	v_add_f32_e32 v94, v97, v98
	v_fmac_f32_e32 v108, v16, v16
	v_fmac_f32_e32 v109, v18, v18
	v_add_f32_e32 v95, v106, v107
	v_add_f32_e32 v92, v92, v94
	s_waitcnt lgkmcnt(0)
	v_add_f32_e32 v77, v77, v93
	v_add_f32_e32 v96, v108, v109
	v_add_f32_e32 v92, v92, v95
	v_mul_f32_e32 v81, v5, v5
	ds_bpermute_b32 v93, v86, v77
	v_add_f32_e32 v92, v92, v96
	v_mul_f32_e32 v96, v7, v7
	v_fmac_f32_e32 v81, v4, v4
	v_fmac_f32_e32 v96, v6, v6
	v_add_f32_e32 v81, v81, v96
	v_add_f32_e32 v65, v65, v81
	s_waitcnt vmcnt(1)
	v_mul_f32_e32 v81, v9, v9
	v_mul_f32_e32 v96, v11, v11
	v_fmac_f32_e32 v81, v8, v8
	v_fmac_f32_e32 v96, v10, v10
	s_waitcnt lgkmcnt(0)
	v_add_f32_e32 v77, v77, v93
	v_add_f32_e32 v81, v81, v96
	v_mul_f32_e32 v102, v37, v37
	v_mul_f32_e32 v103, v39, v39
	ds_bpermute_b32 v93, v87, v77
	v_add_f32_e32 v65, v65, v81
	s_waitcnt vmcnt(0)
	v_mul_f32_e32 v81, v1, v1
	v_mul_f32_e32 v96, v3, v3
	v_mul_f32_e32 v104, v33, v33
	v_mul_f32_e32 v105, v35, v35
	v_fmac_f32_e32 v102, v36, v36
	v_fmac_f32_e32 v103, v38, v38
	v_fmac_f32_e32 v81, v0, v0
	v_fmac_f32_e32 v96, v2, v2
	v_fmac_f32_e32 v104, v32, v32
	v_fmac_f32_e32 v105, v34, v34
	v_add_f32_e32 v99, v102, v103
	v_add_f32_e32 v81, v81, v96
	v_add_f32_e32 v100, v104, v105
	v_add_f32_e32 v73, v73, v99
	v_add_f32_e32 v65, v65, v81
	v_add_f32_e32 v94, v73, v100
	ds_bpermute_b32 v81, v84, v65
	s_waitcnt lgkmcnt(1)
	v_add_f32_e32 v73, v77, v93
	ds_bpermute_b32 v93, v84, v94
	ds_bpermute_b32 v95, v84, v92
	v_mov_b32_e32 v99, v67
	s_waitcnt lgkmcnt(2)
	v_add_f32_e32 v65, v65, v81
	ds_bpermute_b32 v81, v85, v65
	s_waitcnt lgkmcnt(2)
	v_add_f32_e32 v93, v94, v93
	s_waitcnt lgkmcnt(1)
	v_add_f32_e32 v92, v92, v95
	ds_bpermute_b32 v94, v85, v93
	ds_bpermute_b32 v95, v85, v92
	s_waitcnt lgkmcnt(2)
	v_add_f32_e32 v65, v65, v81
	ds_bpermute_b32 v81, v86, v65
	ds_bpermute_b32 v77, v88, v73
	s_waitcnt lgkmcnt(3)
	v_add_f32_e32 v93, v93, v94
	s_waitcnt lgkmcnt(2)
	v_add_f32_e32 v92, v92, v95
	ds_bpermute_b32 v94, v86, v93
	ds_bpermute_b32 v95, v86, v92
	s_waitcnt lgkmcnt(3)
	v_add_f32_e32 v65, v65, v81
	ds_bpermute_b32 v81, v87, v65
	s_waitcnt lgkmcnt(3)
	v_add_f32_e32 v73, v73, v77
	s_waitcnt lgkmcnt(2)
	v_add_f32_e32 v93, v93, v94
	s_waitcnt lgkmcnt(1)
	v_add_f32_e32 v92, v92, v95
	ds_bpermute_b32 v94, v87, v93
	ds_bpermute_b32 v95, v87, v92
	s_waitcnt lgkmcnt(2)
; __host__ __device__ __forceinline__ size_t tiled_off(int row, int col, int K) { return ((size_t)(row >> 7) * (K >> 6) + (col >> 6)) * 8192 + (lds_byte(row & 127, col & 63) >> 1); }
; #define GAS __attribute__((address_space(1)))
; __device__ __forceinline__ unsigned pk2(float lo, float hi) { return f2bf(lo) | (f2bf(hi) << 16); }
; __device__ __forceinline__ void p0_prologue(const Args& a, LAS unsigned char* lds, int vcu, int G, int wave, int lane) {
;     ...
;           for (int r = 0; r < 4; ++r) {
; #pragma unroll
;               for (int j = 0; j < 4; ++j) *(GAS unsigned long long*)(hb + pg8::tiled_off(m0 + r, 4 * lane + 256 * j, D)) = (unsigned long long)pk2(v[r][j].x, v[r][j].y) | ((unsigned long long)pk2(v[r][j].z, v[r][j].w) << 32);
;               if (lane < 16) ss[(size_t)(m0 + r) * 16 + lane] = lane == 0 ? s[r] : 0.f; } } }
	v_add_f32_e32 v65, v65, v81
	ds_bpermute_b32 v81, v88, v65
	ds_bpermute_b32 v77, v89, v73
	s_waitcnt lgkmcnt(3)
	v_add_f32_e32 v93, v93, v94
	s_waitcnt lgkmcnt(2)
	v_add_f32_e32 v92, v92, v95
	ds_bpermute_b32 v94, v88, v93
	ds_bpermute_b32 v95, v88, v92
	s_waitcnt lgkmcnt(3)
	v_add_f32_e32 v65, v65, v81
	v_and_or_b32 v81, s21, 14, v90
	s_waitcnt lgkmcnt(1)
	v_add_f32_e32 v96, v93, v94
	s_waitcnt lgkmcnt(0)
	v_add_f32_e32 v93, v92, v95
	v_lshlrev_b32_e32 v95, 10, v81
	v_or_b32_e32 v81, s18, v91
	s_lshr_b32 s18, s13, 4
	s_and_b32 s18, s18, 32
	v_bitop3_b32 v98, v81, v95, s18 bitop3:0xde
	v_bfe_u32 v81, v60, 16, 1
	v_add3_u32 v60, v60, v81, s7
	v_bfe_u32 v81, v61, 16, 1
	v_lshrrev_b32_e32 v60, 16, v60
	v_add3_u32 v61, v61, v81, s7
	v_and_or_b32 v60, v61, s9, v60
	v_lshl_add_u64 v[98:99], s[24:25], 0, v[98:99]
	v_cvt_pk_bf16_f32 v61, v62, v63
	v_lshl_add_u64 v[62:63], v[98:99], 0, v[66:67]
	global_store_dwordx2 v[62:63], v[60:61], off
	v_bfe_u32 v60, v56, 16, 1
	v_add3_u32 v56, v56, v60, s7
	v_bfe_u32 v60, v57, 16, 1
	v_lshrrev_b32_e32 v56, 16, v56
	v_add3_u32 v57, v57, v60, s7
	v_and_or_b32 v56, v57, s9, v56
	v_cvt_pk_bf16_f32 v57, v58, v59
	v_lshl_add_u64 v[58:59], v[98:99], 0, v[74:75]
	global_store_dwordx2 v[58:59], v[56:57], off
	v_bfe_u32 v56, v52, 16, 1
	v_add3_u32 v52, v52, v56, s7
	v_bfe_u32 v56, v53, 16, 1
	v_lshrrev_b32_e32 v52, 16, v52
	v_add3_u32 v53, v53, v56, s7
	v_and_or_b32 v52, v53, s9, v52
	v_cvt_pk_bf16_f32 v53, v54, v55
	v_lshl_add_u64 v[54:55], v[98:99], 0, v[78:79]
	global_store_dwordx2 v[54:55], v[52:53], off
	v_bfe_u32 v52, v48, 16, 1
	v_add3_u32 v48, v48, v52, s7
	v_bfe_u32 v52, v49, 16, 1
	ds_bpermute_b32 v97, v89, v96
	ds_bpermute_b32 v94, v89, v93
	ds_bpermute_b32 v92, v89, v65
	v_lshrrev_b32_e32 v48, 16, v48
	v_add3_u32 v49, v49, v52, s7
	v_and_or_b32 v48, v49, s9, v48
	v_cvt_pk_bf16_f32 v49, v50, v51
	v_lshl_add_u64 v[50:51], v[98:99], 0, v[82:83]
	global_store_dwordx2 v[50:51], v[48:49], off
	s_and_saveexec_b64 s[44:45], s[2:3]
	s_cbranch_execz .LBB0_400
	v_add_f32_e32 v48, v73, v77
	v_cndmask_b32_e64 v48, 0, v48, s[4:5]
	global_store_dword v[68:69], v48, off offset:-192
.LBB0_400:
	s_or_b64 exec, exec, s[44:45]
	v_bfe_u32 v50, v44, 16, 1
	s_add_i32 s18, s13, 64
	v_add3_u32 v44, v44, v50, s7
	v_bfe_u32 v50, v45, 16, 1
	s_and_b32 s19, s18, 0x340
	s_lshr_b32 s18, s18, 4
	v_lshrrev_b32_e32 v44, 16, v44
	v_add3_u32 v45, v45, v50, s7
	v_or_b32_e32 v48, s19, v91
	s_and_b32 s18, s18, 32
	v_and_or_b32 v44, v45, s9, v44
	v_bitop3_b32 v48, v48, v95, s18 bitop3:0xde
	v_mov_b32_e32 v49, v67
	v_lshl_add_u64 v[48:49], s[24:25], 0, v[48:49]
	v_cvt_pk_bf16_f32 v45, v46, v47
	v_lshl_add_u64 v[46:47], v[48:49], 0, v[66:67]
	global_store_dwordx2 v[46:47], v[44:45], off
	v_bfe_u32 v44, v40, 16, 1
	v_add3_u32 v40, v40, v44, s7
	v_bfe_u32 v44, v41, 16, 1
	v_lshrrev_b32_e32 v40, 16, v40
	v_add3_u32 v41, v41, v44, s7
	v_and_or_b32 v40, v41, s9, v40
	v_mov_b32_e32 v73, v67
	v_cvt_pk_bf16_f32 v41, v42, v43
	v_lshl_add_u64 v[42:43], v[48:49], 0, v[72:73]
	global_store_dwordx2 v[42:43], v[40:41], off
	v_bfe_u32 v40, v36, 16, 1
	v_add3_u32 v36, v36, v40, s7
	v_bfe_u32 v40, v37, 16, 1
	v_lshrrev_b32_e32 v36, 16, v36
	v_add3_u32 v37, v37, v40, s7
	v_and_or_b32 v36, v37, s9, v36
	v_mov_b32_e32 v77, v67
	v_cvt_pk_bf16_f32 v37, v38, v39
	v_lshl_add_u64 v[38:39], v[48:49], 0, v[76:77]
	global_store_dwordx2 v[38:39], v[36:37], off
	v_bfe_u32 v36, v32, 16, 1
	v_add3_u32 v32, v32, v36, s7
	v_bfe_u32 v36, v33, 16, 1
	v_lshrrev_b32_e32 v32, 16, v32
	v_add3_u32 v33, v33, v36, s7
	v_and_or_b32 v32, v33, s9, v32
	v_mov_b32_e32 v81, v67
	v_cvt_pk_bf16_f32 v33, v34, v35
	v_lshl_add_u64 v[34:35], v[48:49], 0, v[80:81]
	global_store_dwordx2 v[34:35], v[32:33], off
	s_and_saveexec_b64 s[44:45], s[2:3]
	s_cbranch_execz .LBB0_402
	s_waitcnt lgkmcnt(2)
	v_add_f32_e32 v32, v96, v97
	v_cndmask_b32_e64 v32, 0, v32, s[4:5]
	global_store_dword v[68:69], v32, off offset:-128
; __host__ __device__ __forceinline__ size_t tiled_off(int row, int col, int K) { return ((size_t)(row >> 7) * (K >> 6) + (col >> 6)) * 8192 + (lds_byte(row & 127, col & 63) >> 1); }
; #define GAS __attribute__((address_space(1)))
; __device__ __forceinline__ unsigned pk2(float lo, float hi) { return f2bf(lo) | (f2bf(hi) << 16); }
; __device__ __forceinline__ void p0_prologue(const Args& a, LAS unsigned char* lds, int vcu, int G, int wave, int lane) {
;     ...
;           for (int r = 0; r < 4; ++r) {
; #pragma unroll
;               for (int j = 0; j < 4; ++j) *(GAS unsigned long long*)(hb + pg8::tiled_off(m0 + r, 4 * lane + 256 * j, D)) = (unsigned long long)pk2(v[r][j].x, v[r][j].y) | ((unsigned long long)pk2(v[r][j].z, v[r][j].w) << 32);
;               if (lane < 16) ss[(size_t)(m0 + r) * 16 + lane] = lane == 0 ? s[r] : 0.f; } } }
.LBB0_402:
	s_or_b64 exec, exec, s[44:45]
	v_bfe_u32 v34, v28, 16, 1
	s_add_i32 s18, s13, 0x80
	v_add3_u32 v28, v28, v34, s7
	v_bfe_u32 v34, v29, 16, 1
	s_and_b32 s19, s18, 0x380
	s_lshr_b32 s18, s18, 4
	v_lshrrev_b32_e32 v28, 16, v28
	v_add3_u32 v29, v29, v34, s7
	v_or_b32_e32 v32, s19, v91
	s_and_b32 s18, s18, 32
	v_and_or_b32 v28, v29, s9, v28
	v_bitop3_b32 v32, v32, v95, s18 bitop3:0xde
	v_mov_b32_e32 v33, v67
	v_lshl_add_u64 v[32:33], s[24:25], 0, v[32:33]
	v_cvt_pk_bf16_f32 v29, v30, v31
	v_lshl_add_u64 v[30:31], v[32:33], 0, v[66:67]
	global_store_dwordx2 v[30:31], v[28:29], off
	v_bfe_u32 v28, v24, 16, 1
	v_add3_u32 v24, v24, v28, s7
	v_bfe_u32 v28, v25, 16, 1
	v_lshrrev_b32_e32 v24, 16, v24
	v_add3_u32 v25, v25, v28, s7
	v_and_or_b32 v24, v25, s9, v24
	v_cvt_pk_bf16_f32 v25, v26, v27
	v_lshl_add_u64 v[26:27], v[32:33], 0, v[72:73]
	global_store_dwordx2 v[26:27], v[24:25], off
	v_bfe_u32 v24, v20, 16, 1
	v_add3_u32 v20, v20, v24, s7
	v_bfe_u32 v24, v21, 16, 1
	v_lshrrev_b32_e32 v20, 16, v20
	v_add3_u32 v21, v21, v24, s7
	v_and_or_b32 v20, v21, s9, v20
	v_cvt_pk_bf16_f32 v21, v22, v23
	v_lshl_add_u64 v[22:23], v[32:33], 0, v[76:77]
	global_store_dwordx2 v[22:23], v[20:21], off
	v_bfe_u32 v20, v16, 16, 1
	v_add3_u32 v16, v16, v20, s7
	v_bfe_u32 v20, v17, 16, 1
	v_lshrrev_b32_e32 v16, 16, v16
	v_add3_u32 v17, v17, v20, s7
	v_and_or_b32 v16, v17, s9, v16
	v_cvt_pk_bf16_f32 v17, v18, v19
	v_lshl_add_u64 v[18:19], v[32:33], 0, v[80:81]
	global_store_dwordx2 v[18:19], v[16:17], off
	s_and_saveexec_b64 s[44:45], s[2:3]
	s_cbranch_execz .LBB0_404
	s_waitcnt lgkmcnt(1)
	v_add_f32_e32 v16, v93, v94
	v_cndmask_b32_e64 v16, 0, v16, s[4:5]
	global_store_dword v[68:69], v16, off offset:-64
.LBB0_404:
	s_or_b64 exec, exec, s[44:45]
	v_bfe_u32 v18, v12, 16, 1
	s_add_i32 s18, s13, 0xc0
	v_add3_u32 v12, v12, v18, s7
	v_bfe_u32 v18, v13, 16, 1
	s_and_b32 s19, s18, 0x3c0
	s_lshr_b32 s18, s18, 4
	v_lshrrev_b32_e32 v12, 16, v12
	v_add3_u32 v13, v13, v18, s7
	v_or_b32_e32 v16, s19, v91
	s_and_b32 s18, s18, 32
	v_and_or_b32 v12, v13, s9, v12
	v_bitop3_b32 v16, v16, v95, s18 bitop3:0xde
	v_mov_b32_e32 v17, v67
	v_lshl_add_u64 v[16:17], s[24:25], 0, v[16:17]
	v_cvt_pk_bf16_f32 v13, v14, v15
	v_lshl_add_u64 v[14:15], v[16:17], 0, v[66:67]
	global_store_dwordx2 v[14:15], v[12:13], off
	v_bfe_u32 v12, v4, 16, 1
	v_add3_u32 v4, v4, v12, s7
	v_bfe_u32 v12, v5, 16, 1
	v_lshrrev_b32_e32 v4, 16, v4
	v_add3_u32 v5, v5, v12, s7
	v_and_or_b32 v4, v5, s9, v4
	v_mov_b32_e32 v73, v67
	v_cvt_pk_bf16_f32 v5, v6, v7
	v_lshl_add_u64 v[6:7], v[16:17], 0, v[72:73]
	global_store_dwordx2 v[6:7], v[4:5], off
	v_cvt_pk_bf16_f32 v4, v8, v9
	v_mov_b32_e32 v77, v67
	v_cvt_pk_bf16_f32 v5, v10, v11
	v_lshl_add_u64 v[6:7], v[16:17], 0, v[76:77]
	global_store_dwordx2 v[6:7], v[4:5], off
	v_bfe_u32 v4, v0, 16, 1
	v_add3_u32 v0, v0, v4, s7
	v_bfe_u32 v4, v1, 16, 1
	v_lshrrev_b32_e32 v0, 16, v0
	v_add3_u32 v1, v1, v4, s7
	v_and_or_b32 v0, v1, s9, v0
	v_mov_b32_e32 v81, v67
	v_cvt_pk_bf16_f32 v1, v2, v3
	v_lshl_add_u64 v[2:3], v[16:17], 0, v[80:81]
	global_store_dwordx2 v[2:3], v[0:1], off
	s_and_saveexec_b64 s[24:25], s[2:3]
	s_cbranch_execz .LBB0_397
	s_waitcnt lgkmcnt(0)
	v_add_f32_e32 v0, v65, v92
	v_cndmask_b32_e64 v0, 0, v0, s[4:5]
	global_store_dword v[68:69], v0, off
	s_branch .LBB0_397

; __host__ __device__ __forceinline__ size_t tiled_off(int row, int col, int K) { return ((size_t)(row >> 7) * (K >> 6) + (col >> 6)) * 8192 + (lds_byte(row & 127, col & 63) >> 1); }
; __device__ __forceinline__ float fast_sigmoid(float x) { return __builtin_amdgcn_rcpf(1.0f + __builtin_amdgcn_exp2f(x * -1.4426950408889634f)); }
; __device__ __forceinline__ unsigned pk2(float lo, float hi) { return f2bf(lo) | (f2bf(hi) << 16); }
; __device__ __forceinline__ void conv_phase(const Args& a, LAS unsigned char* lds, int vcu, int G, int tid, int wave, int lane) {
;     ...
;         for (int i = 0; i < 32; ++i) { const f32x2 st = stat[i]; f32x2 y = (o[i] - st.x) * st.y * g2 + b2;
;             y.x = y.x * pg8::fast_sigmoid(y.x); y.y = y.y * pg8::fast_sigmoid(y.y);
;             *(unsigned*)(V2 + pg8::tiled_off(t0 + i, c0, D)) = pk2(y.x, y.y); }
.LBB0_554:
	s_or_b64 exec, exec, s[16:17]
	s_waitcnt lgkmcnt(0)
	s_barrier
	ds_read_b128 v[138:141], v1 offset:4096
	ds_read_b128 v[142:145], v1 offset:4112
	s_ashr_i32 s16, s22, 2
	s_ashr_i32 s17, s16, 31
	s_lshl_b64 s[16:17], s[16:17], 18
	s_waitcnt lgkmcnt(1)
	v_pk_add_f32 v[88:89], v[88:89], v[138:139] op_sel_hi:[1,0] neg_lo:[0,1] neg_hi:[0,1]
	s_nop 0
	v_pk_mul_f32 v[88:89], v[138:139], v[88:89] op_sel:[1,0]
	s_nop 0
	v_pk_fma_f32 v[88:89], v[66:67], v[88:89], v[68:69]
	s_nop 0
	v_mul_f32_e32 v0, 0xbfb8aa3b, v88
	v_exp_f32_e32 v0, v0
	v_mul_f32_e32 v138, 0xbfb8aa3b, v89
	v_exp_f32_e32 v146, v138
	v_lshl_add_u64 v[138:139], v[72:73], 0, s[16:17]
	v_add_f32_e32 v0, 1.0, v0
	v_rcp_f32_e32 v0, v0
	v_add_f32_e32 v146, 1.0, v146
	v_rcp_f32_e32 v154, v146
	s_lshr_b32 s16, s44, 3
	v_mul_f32_e32 v0, v88, v0
	ds_read_b128 v[146:149], v1 offset:4128
	ds_read_b128 v[150:153], v1 offset:4144
	v_mul_f32_e32 v88, v89, v154
	v_cvt_pk_bf16_f32 v154, v0, v88
	v_and_or_b32 v0, s16, 12, v189
	v_lshl_or_b32 v155, v0, 9, v190
	v_pk_add_f32 v[88:89], v[90:91], v[140:141] op_sel_hi:[1,0] neg_lo:[0,1] neg_hi:[0,1]
	v_mov_b32_e32 v0, v141
	v_pk_mul_f32 v[88:89], v[0:1], v[88:89] op_sel_hi:[0,1]
	v_pk_fma_f32 v[90:91], v[66:67], v[88:89], v[68:69]
	v_readlane_b32 s16, v255, 4
	v_mul_f32_e32 v0, 0xbfb8aa3b, v90
	v_exp_f32_e32 v88, v0
	v_mul_f32_e32 v0, 0xbfb8aa3b, v91
	v_exp_f32_e32 v89, v0
	v_lshlrev_b32_e32 v0, 1, v155
	v_add_f32_e32 v88, 1.0, v88
	v_rcp_f32_e32 v140, v88
	v_add_f32_e32 v88, 1.0, v89
	v_rcp_f32_e32 v141, v88
	v_lshl_add_u64 v[88:89], v[138:139], 0, v[0:1]
	v_mul_f32_e32 v0, v90, v140
	v_bfe_u32 v90, v0, 16, 1
	v_mul_f32_e32 v140, v91, v141
	v_add3_u32 v0, v0, v90, s21
	s_waitcnt lgkmcnt(2)
	v_pk_add_f32 v[90:91], v[98:99], v[142:143] op_sel_hi:[1,0] neg_lo:[0,1] neg_hi:[0,1]
	v_bfe_u32 v141, v140, 16, 1
	v_pk_mul_f32 v[90:91], v[142:143], v[90:91] op_sel:[1,0]
	v_lshrrev_b32_e32 v0, 16, v0
	v_pk_fma_f32 v[90:91], v[66:67], v[90:91], v[68:69]
	v_add3_u32 v140, v140, v141, s21
	v_mul_f32_e32 v98, 0xbfb8aa3b, v90
	v_exp_f32_e32 v98, v98
	v_mul_f32_e32 v99, 0xbfb8aa3b, v91
	v_exp_f32_e32 v99, v99
	v_and_or_b32 v0, v140, s19, v0
	v_add_f32_e32 v98, 1.0, v98
	v_rcp_f32_e32 v98, v98
	v_add_f32_e32 v99, 1.0, v99
	v_rcp_f32_e32 v99, v99
	global_store_dword v[88:89], v0, off offset:64
	v_mul_f32_e32 v0, v90, v98
	v_bfe_u32 v90, v0, 16, 1
	v_add3_u32 v0, v0, v90, s21
	v_mul_f32_e32 v98, v91, v99
	v_lshrrev_b32_e32 v99, 16, v0
	v_pk_add_f32 v[90:91], v[108:109], v[144:145] op_sel_hi:[1,0] neg_lo:[0,1] neg_hi:[0,1]
	v_mov_b32_e32 v0, v145
	v_pk_mul_f32 v[90:91], v[0:1], v[90:91] op_sel_hi:[0,1]
	v_pk_fma_f32 v[90:91], v[66:67], v[90:91], v[68:69]
	v_bfe_u32 v140, v98, 16, 1
	v_mul_f32_e32 v0, 0xbfb8aa3b, v90
	v_exp_f32_e32 v0, v0
	v_mul_f32_e32 v108, 0xbfb8aa3b, v91
	v_exp_f32_e32 v108, v108
	v_add3_u32 v98, v98, v140, s21
	v_add_f32_e32 v0, 1.0, v0
	v_rcp_f32_e32 v0, v0
	v_add_f32_e32 v108, 1.0, v108
	v_rcp_f32_e32 v108, v108
	v_and_or_b32 v98, v98, s19, v99
	v_mul_f32_e32 v0, v90, v0
	v_bfe_u32 v90, v0, 16, 1
	global_store_dword v[88:89], v98, off offset:128
	v_mul_f32_e32 v98, v91, v108
	v_add3_u32 v0, v0, v90, s21
	s_waitcnt lgkmcnt(1)
	v_pk_add_f32 v[90:91], v[118:119], v[146:147] op_sel_hi:[1,0] neg_lo:[0,1] neg_hi:[0,1]
	v_bfe_u32 v99, v98, 16, 1
	v_pk_mul_f32 v[90:91], v[146:147], v[90:91] op_sel:[1,0]
	v_add3_u32 v98, v98, v99, s21
	v_pk_fma_f32 v[90:91], v[66:67], v[90:91], v[68:69]
	v_lshrrev_b32_e32 v0, 16, v0
	v_mul_f32_e32 v108, 0xbfb8aa3b, v90
	v_exp_f32_e32 v108, v108
	v_mul_f32_e32 v109, 0xbfb8aa3b, v91
	v_exp_f32_e32 v109, v109
	v_and_or_b32 v0, v98, s19, v0
	v_add_f32_e32 v99, 1.0, v108
	v_rcp_f32_e32 v99, v99
	v_add_f32_e32 v108, 1.0, v109
	v_rcp_f32_e32 v108, v108
	global_store_dword v[88:89], v0, off offset:192
	v_mul_f32_e32 v0, v90, v99
	v_bfe_u32 v90, v0, 16, 1
	v_add3_u32 v0, v0, v90, s21
	v_mul_f32_e32 v98, v91, v108
	v_lshrrev_b32_e32 v99, 16, v0
	v_pk_add_f32 v[90:91], v[128:129], v[148:149] op_sel_hi:[1,0] neg_lo:[0,1] neg_hi:[0,1]
	v_mov_b32_e32 v0, v149
	v_pk_mul_f32 v[90:91], v[0:1], v[90:91] op_sel_hi:[0,1]
	v_pk_fma_f32 v[90:91], v[66:67], v[90:91], v[68:69]
	v_bfe_u32 v108, v98, 16, 1
	v_mul_f32_e32 v0, 0xbfb8aa3b, v90
	v_exp_f32_e32 v0, v0
	v_mul_f32_e32 v109, 0xbfb8aa3b, v91
	v_exp_f32_e32 v109, v109
	v_add3_u32 v98, v98, v108, s21
	v_add_f32_e32 v0, 1.0, v0
	v_rcp_f32_e32 v0, v0
	v_add_f32_e32 v108, 1.0, v109
	v_rcp_f32_e32 v108, v108
	v_and_or_b32 v98, v98, s19, v99
	v_mul_f32_e32 v0, v90, v0
	v_bfe_u32 v90, v0, 16, 1
	global_store_dword v[88:89], v98, off offset:256
	v_mul_f32_e32 v98, v91, v108
	v_add3_u32 v0, v0, v90, s21
	s_waitcnt lgkmcnt(0)
	v_pk_add_f32 v[90:91], v[134:135], v[150:151] op_sel_hi:[1,0] neg_lo:[0,1] neg_hi:[0,1]
	v_bfe_u32 v99, v98, 16, 1
	v_pk_mul_f32 v[90:91], v[150:151], v[90:91] op_sel:[1,0]
	v_add3_u32 v98, v98, v99, s21
	v_pk_fma_f32 v[90:91], v[66:67], v[90:91], v[68:69]
	v_lshrrev_b32_e32 v0, 16, v0
	v_mul_f32_e32 v108, 0xbfb8aa3b, v90
	v_exp_f32_e32 v108, v108
	v_mul_f32_e32 v109, 0xbfb8aa3b, v91
	v_exp_f32_e32 v109, v109
	v_and_or_b32 v0, v98, s19, v0
	v_add_f32_e32 v99, 1.0, v108
	v_rcp_f32_e32 v99, v99
	v_add_f32_e32 v108, 1.0, v109
	v_rcp_f32_e32 v108, v108
	global_store_dword v[88:89], v0, off offset:320
	v_mul_f32_e32 v0, v90, v99
	v_bfe_u32 v90, v0, 16, 1
	v_add3_u32 v0, v0, v90, s21
	v_mul_f32_e32 v98, v91, v108
	v_lshrrev_b32_e32 v99, 16, v0
	v_pk_add_f32 v[90:91], v[136:137], v[152:153] op_sel_hi:[1,0] neg_lo:[0,1] neg_hi:[0,1]
	v_mov_b32_e32 v0, v153
	v_pk_mul_f32 v[90:91], v[0:1], v[90:91] op_sel_hi:[0,1]
	v_pk_fma_f32 v[90:91], v[66:67], v[90:91], v[68:69]
	v_bfe_u32 v108, v98, 16, 1
	v_mul_f32_e32 v0, 0xbfb8aa3b, v90
	v_exp_f32_e32 v0, v0
	v_mul_f32_e32 v109, 0xbfb8aa3b, v91
	v_exp_f32_e32 v109, v109
	v_add3_u32 v98, v98, v108, s21
	v_add_f32_e32 v0, 1.0, v0
	v_rcp_f32_e32 v0, v0
	v_add_f32_e32 v108, 1.0, v109
	ds_read_b128 v[134:137], v1 offset:4160
	ds_read_b128 v[140:143], v1 offset:4176
	v_rcp_f32_e32 v108, v108
	v_mul_f32_e32 v0, v90, v0
	v_and_or_b32 v98, v98, s19, v99
	v_bfe_u32 v90, v0, 16, 1
	global_store_dword v[88:89], v98, off offset:384
	v_mul_f32_e32 v98, v91, v108
	v_add3_u32 v0, v0, v90, s21
	s_waitcnt lgkmcnt(1)
; __host__ __device__ __forceinline__ size_t tiled_off(int row, int col, int K) { return ((size_t)(row >> 7) * (K >> 6) + (col >> 6)) * 8192 + (lds_byte(row & 127, col & 63) >> 1); }
; __device__ __forceinline__ float fast_sigmoid(float x) { return __builtin_amdgcn_rcpf(1.0f + __builtin_amdgcn_exp2f(x * -1.4426950408889634f)); }
; __device__ __forceinline__ unsigned pk2(float lo, float hi) { return f2bf(lo) | (f2bf(hi) << 16); }
; __device__ __forceinline__ void conv_phase(const Args& a, LAS unsigned char* lds, int vcu, int G, int tid, int wave, int lane) {
;     ...
;         for (int i = 0; i < 32; ++i) { const f32x2 st = stat[i]; f32x2 y = (o[i] - st.x) * st.y * g2 + b2;
;             y.x = y.x * pg8::fast_sigmoid(y.x); y.y = y.y * pg8::fast_sigmoid(y.y);
;             *(unsigned*)(V2 + pg8::tiled_off(t0 + i, c0, D)) = pk2(y.x, y.y); }
	v_pk_add_f32 v[90:91], v[92:93], v[134:135] op_sel_hi:[1,0] neg_lo:[0,1] neg_hi:[0,1]
	v_bfe_u32 v99, v98, 16, 1
	v_pk_mul_f32 v[90:91], v[134:135], v[90:91] op_sel:[1,0]
	v_lshrrev_b32_e32 v0, 16, v0
	v_pk_fma_f32 v[90:91], v[66:67], v[90:91], v[68:69]
	v_add3_u32 v98, v98, v99, s21
	v_mul_f32_e32 v92, 0xbfb8aa3b, v90
	v_exp_f32_e32 v92, v92
	v_mul_f32_e32 v93, 0xbfb8aa3b, v91
	v_exp_f32_e32 v93, v93
	v_and_or_b32 v0, v98, s19, v0
	v_add_f32_e32 v92, 1.0, v92
	v_rcp_f32_e32 v92, v92
	v_add_f32_e32 v93, 1.0, v93
	v_rcp_f32_e32 v93, v93
	global_store_dword v[88:89], v0, off offset:448
	v_mul_f32_e32 v0, v90, v92
	global_store_dword v[88:89], v154, off
	v_mul_f32_e32 v90, v91, v93
	v_bfe_u32 v91, v0, 16, 1
	v_add3_u32 v0, v0, v91, s21
	v_bfe_u32 v91, v90, 16, 1
	v_lshrrev_b32_e32 v0, 16, v0
	v_add3_u32 v90, v90, v91, s21
	v_and_or_b32 v98, v90, s19, v0
	v_pk_add_f32 v[90:91], v[106:107], v[136:137] op_sel_hi:[1,0] neg_lo:[0,1] neg_hi:[0,1]
	v_mov_b32_e32 v0, v137
	v_pk_mul_f32 v[90:91], v[0:1], v[90:91] op_sel_hi:[0,1]
	v_pk_fma_f32 v[92:93], v[66:67], v[90:91], v[68:69]
	s_add_i32 s22, s22, s16
	v_mul_f32_e32 v0, 0xbfb8aa3b, v92
	v_exp_f32_e32 v90, v0
	v_mul_f32_e32 v0, 0xbfb8aa3b, v93
	v_exp_f32_e32 v91, v0
	v_xor_b32_e32 v0, 16, v155
	v_add_f32_e32 v90, 1.0, v90
	v_rcp_f32_e32 v99, v90
	v_add_f32_e32 v90, 1.0, v91
	v_rcp_f32_e32 v106, v90
	v_lshl_add_u64 v[90:91], v[0:1], 1, v[138:139]
	v_mul_f32_e32 v0, v92, v99
	v_bfe_u32 v92, v0, 16, 1
	global_store_dword v[90:91], v98, off offset:512
	v_mul_f32_e32 v98, v93, v106
	v_add3_u32 v0, v0, v92, s21
	s_waitcnt lgkmcnt(0)
	v_pk_add_f32 v[92:93], v[124:125], v[140:141] op_sel_hi:[1,0] neg_lo:[0,1] neg_hi:[0,1]
	v_bfe_u32 v99, v98, 16, 1
	v_pk_mul_f32 v[92:93], v[140:141], v[92:93] op_sel:[1,0]
	v_add3_u32 v98, v98, v99, s21
	v_pk_fma_f32 v[92:93], v[66:67], v[92:93], v[68:69]
	v_lshrrev_b32_e32 v0, 16, v0
	v_mul_f32_e32 v106, 0xbfb8aa3b, v92
	v_exp_f32_e32 v106, v106
	v_mul_f32_e32 v107, 0xbfb8aa3b, v93
	v_exp_f32_e32 v107, v107
	v_and_or_b32 v0, v98, s19, v0
	v_add_f32_e32 v99, 1.0, v106
	v_rcp_f32_e32 v99, v99
	v_add_f32_e32 v106, 1.0, v107
	v_rcp_f32_e32 v106, v106
	global_store_dword v[90:91], v0, off offset:576
	v_mul_f32_e32 v0, v92, v99
	v_bfe_u32 v92, v0, 16, 1
	v_add3_u32 v0, v0, v92, s21
	v_mul_f32_e32 v98, v93, v106
	v_lshrrev_b32_e32 v99, 16, v0
	v_pk_add_f32 v[92:93], v[132:133], v[142:143] op_sel_hi:[1,0] neg_lo:[0,1] neg_hi:[0,1]
	v_mov_b32_e32 v0, v143
	v_pk_mul_f32 v[92:93], v[0:1], v[92:93] op_sel_hi:[0,1]
	v_pk_fma_f32 v[92:93], v[66:67], v[92:93], v[68:69]
	v_bfe_u32 v106, v98, 16, 1
	v_mul_f32_e32 v0, 0xbfb8aa3b, v92
	v_mul_f32_e32 v107, 0xbfb8aa3b, v93
	v_exp_f32_e32 v0, v0
	v_exp_f32_e32 v107, v107
	v_add3_u32 v98, v98, v106, s21
	ds_read_b128 v[132:135], v1 offset:4208
	v_add_f32_e32 v0, 1.0, v0
	v_add_f32_e32 v106, 1.0, v107
	v_rcp_f32_e32 v0, v0
	v_rcp_f32_e32 v106, v106
	v_and_or_b32 v98, v98, s19, v99
	global_store_dword v[90:91], v98, off offset:640
	v_mul_f32_e32 v0, v92, v0
	v_mul_f32_e32 v92, v93, v106
	ds_read_b128 v[106:109], v1 offset:4192
	v_bfe_u32 v93, v0, 16, 1
	v_add3_u32 v0, v0, v93, s21
	v_bfe_u32 v93, v92, 16, 1
	v_add3_u32 v92, v92, v93, s21
	s_waitcnt lgkmcnt(0)
	v_pk_add_f32 v[84:85], v[84:85], v[106:107] op_sel_hi:[1,0] neg_lo:[0,1] neg_hi:[0,1]
	v_lshrrev_b32_e32 v0, 16, v0
	v_pk_mul_f32 v[84:85], v[106:107], v[84:85] op_sel:[1,0]
	v_and_or_b32 v0, v92, s19, v0
	v_pk_fma_f32 v[84:85], v[66:67], v[84:85], v[68:69]
	global_store_dword v[90:91], v0, off offset:704
	v_mul_f32_e32 v98, 0xbfb8aa3b, v84
	v_exp_f32_e32 v98, v98
	v_mul_f32_e32 v99, 0xbfb8aa3b, v85
	v_exp_f32_e32 v99, v99
	s_add_i32 s44, s44, s18
	v_add_f32_e32 v93, 1.0, v98
	v_rcp_f32_e32 v93, v93
	v_add_f32_e32 v98, 1.0, v99
	v_rcp_f32_e32 v98, v98
	s_cmpk_lt_i32 s22, 0x400
	v_mul_f32_e32 v0, v84, v93
	v_bfe_u32 v84, v0, 16, 1
	v_add3_u32 v0, v0, v84, s21
	v_mul_f32_e32 v92, v85, v98
	v_lshrrev_b32_e32 v93, 16, v0
	v_pk_add_f32 v[84:85], v[102:103], v[108:109] op_sel_hi:[1,0] neg_lo:[0,1] neg_hi:[0,1]
	v_mov_b32_e32 v0, v109
	v_pk_mul_f32 v[84:85], v[0:1], v[84:85] op_sel_hi:[0,1]
	v_pk_fma_f32 v[84:85], v[66:67], v[84:85], v[68:69]
	v_bfe_u32 v98, v92, 16, 1
	v_mul_f32_e32 v0, 0xbfb8aa3b, v84
	v_exp_f32_e32 v0, v0
	v_mul_f32_e32 v99, 0xbfb8aa3b, v85
	v_exp_f32_e32 v99, v99
	v_add3_u32 v92, v92, v98, s21
	v_add_f32_e32 v0, 1.0, v0
	v_rcp_f32_e32 v0, v0
	v_add_f32_e32 v98, 1.0, v99
	v_rcp_f32_e32 v98, v98
	v_and_or_b32 v92, v92, s19, v93
	v_mul_f32_e32 v0, v84, v0
	v_bfe_u32 v84, v0, 16, 1
	global_store_dword v[90:91], v92, off offset:768
	v_mul_f32_e32 v92, v85, v98
	v_add3_u32 v0, v0, v84, s21
	v_pk_add_f32 v[84:85], v[120:121], v[132:133] op_sel_hi:[1,0] neg_lo:[0,1] neg_hi:[0,1]
	v_bfe_u32 v93, v92, 16, 1
	v_pk_mul_f32 v[84:85], v[132:133], v[84:85] op_sel:[1,0]
	v_add3_u32 v92, v92, v93, s21
	v_pk_fma_f32 v[84:85], v[66:67], v[84:85], v[68:69]
	v_lshrrev_b32_e32 v0, 16, v0
	v_mul_f32_e32 v98, 0xbfb8aa3b, v84
	v_exp_f32_e32 v98, v98
	v_mul_f32_e32 v99, 0xbfb8aa3b, v85
	v_exp_f32_e32 v99, v99
	v_and_or_b32 v0, v92, s19, v0
	v_add_f32_e32 v93, 1.0, v98
	v_rcp_f32_e32 v93, v93
	v_add_f32_e32 v98, 1.0, v99
	v_rcp_f32_e32 v98, v98
	global_store_dword v[90:91], v0, off offset:832
	v_mul_f32_e32 v0, v84, v93
	v_bfe_u32 v84, v0, 16, 1
	v_add3_u32 v0, v0, v84, s21
	v_mul_f32_e32 v92, v85, v98
	v_lshrrev_b32_e32 v93, 16, v0
	v_pk_add_f32 v[84:85], v[130:131], v[134:135] op_sel_hi:[1,0] neg_lo:[0,1] neg_hi:[0,1]
	v_mov_b32_e32 v0, v135
	v_pk_mul_f32 v[84:85], v[0:1], v[84:85] op_sel_hi:[0,1]
	v_pk_fma_f32 v[84:85], v[66:67], v[84:85], v[68:69]
	ds_read_b128 v[106:109], v1 offset:4224
	ds_read_b128 v[118:121], v1 offset:4240
	v_mul_f32_e32 v0, 0xbfb8aa3b, v84
	v_exp_f32_e32 v0, v0
	v_mul_f32_e32 v99, 0xbfb8aa3b, v85
	v_exp_f32_e32 v99, v99
	v_bfe_u32 v98, v92, 16, 1
	v_add_f32_e32 v0, 1.0, v0
	s_waitcnt lgkmcnt(1)
; __host__ __device__ __forceinline__ size_t tiled_off(int row, int col, int K) { return ((size_t)(row >> 7) * (K >> 6) + (col >> 6)) * 8192 + (lds_byte(row & 127, col & 63) >> 1); }
; __device__ __forceinline__ float fast_sigmoid(float x) { return __builtin_amdgcn_rcpf(1.0f + __builtin_amdgcn_exp2f(x * -1.4426950408889634f)); }
; __device__ __forceinline__ unsigned pk2(float lo, float hi) { return f2bf(lo) | (f2bf(hi) << 16); }
; __device__ __forceinline__ void conv_phase(const Args& a, LAS unsigned char* lds, int vcu, int G, int tid, int wave, int lane) {
;     ...
;         for (int i = 0; i < 32; ++i) { const f32x2 st = stat[i]; f32x2 y = (o[i] - st.x) * st.y * g2 + b2;
;             y.x = y.x * pg8::fast_sigmoid(y.x); y.y = y.y * pg8::fast_sigmoid(y.y);
;             *(unsigned*)(V2 + pg8::tiled_off(t0 + i, c0, D)) = pk2(y.x, y.y); }
	v_pk_add_f32 v[80:81], v[80:81], v[106:107] op_sel_hi:[1,0] neg_lo:[0,1] neg_hi:[0,1]
	v_add3_u32 v92, v92, v98, s21
	v_rcp_f32_e32 v0, v0
	v_add_f32_e32 v98, 1.0, v99
	v_pk_mul_f32 v[80:81], v[106:107], v[80:81] op_sel:[1,0]
	v_rcp_f32_e32 v98, v98
	v_and_or_b32 v92, v92, s19, v93
	v_pk_fma_f32 v[80:81], v[66:67], v[80:81], v[68:69]
	global_store_dword v[90:91], v92, off offset:896
	v_mul_f32_e32 v92, 0xbfb8aa3b, v80
	v_exp_f32_e32 v92, v92
	v_mul_f32_e32 v0, v84, v0
	v_mul_f32_e32 v84, v85, v98
	v_bfe_u32 v85, v0, 16, 1
	v_mul_f32_e32 v93, 0xbfb8aa3b, v81
	v_add3_u32 v0, v0, v85, s21
	v_bfe_u32 v85, v84, 16, 1
	v_exp_f32_e32 v93, v93
	v_add3_u32 v84, v84, v85, s21
	v_add_f32_e32 v85, 1.0, v92
	v_rcp_f32_e32 v85, v85
	v_lshrrev_b32_e32 v0, 16, v0
	v_add_f32_e32 v92, 1.0, v93
	v_rcp_f32_e32 v92, v92
	v_and_or_b32 v0, v84, s19, v0
	global_store_dword v[90:91], v0, off offset:960
	v_mul_f32_e32 v0, v80, v85
	v_bfe_u32 v80, v0, 16, 1
	v_add3_u32 v0, v0, v80, s21
	v_mul_f32_e32 v84, v81, v92
	v_lshrrev_b32_e32 v85, 16, v0
	v_pk_add_f32 v[80:81], v[96:97], v[108:109] op_sel_hi:[1,0] neg_lo:[0,1] neg_hi:[0,1]
	v_mov_b32_e32 v0, v109
	v_pk_mul_f32 v[80:81], v[0:1], v[80:81] op_sel_hi:[0,1]
	v_pk_fma_f32 v[80:81], v[66:67], v[80:81], v[68:69]
	v_bfe_u32 v92, v84, 16, 1
	v_mul_f32_e32 v0, 0xbfb8aa3b, v80
	v_exp_f32_e32 v0, v0
	v_mul_f32_e32 v93, 0xbfb8aa3b, v81
	v_exp_f32_e32 v93, v93
	v_add3_u32 v84, v84, v92, s21
	v_add_f32_e32 v0, 1.0, v0
	v_rcp_f32_e32 v0, v0
	v_add_f32_e32 v92, 1.0, v93
	v_rcp_f32_e32 v92, v92
	v_and_or_b32 v84, v84, s19, v85
	v_mul_f32_e32 v0, v80, v0
	v_bfe_u32 v80, v0, 16, 1
	global_store_dword v[88:89], v84, off offset:2048
	v_mul_f32_e32 v84, v81, v92
	v_add3_u32 v0, v0, v80, s21
	s_waitcnt lgkmcnt(0)
	v_pk_add_f32 v[80:81], v[114:115], v[118:119] op_sel_hi:[1,0] neg_lo:[0,1] neg_hi:[0,1]
	v_bfe_u32 v85, v84, 16, 1
	v_pk_mul_f32 v[80:81], v[118:119], v[80:81] op_sel:[1,0]
	v_add3_u32 v84, v84, v85, s21
	v_pk_fma_f32 v[80:81], v[66:67], v[80:81], v[68:69]
	v_lshrrev_b32_e32 v0, 16, v0
	v_mul_f32_e32 v92, 0xbfb8aa3b, v80
	v_exp_f32_e32 v92, v92
	v_mul_f32_e32 v93, 0xbfb8aa3b, v81
	v_exp_f32_e32 v93, v93
	v_and_or_b32 v0, v84, s19, v0
	v_add_f32_e32 v85, 1.0, v92
	v_rcp_f32_e32 v85, v85
	v_add_f32_e32 v92, 1.0, v93
	v_rcp_f32_e32 v92, v92
	global_store_dword v[88:89], v0, off offset:2112
	v_mul_f32_e32 v0, v80, v85
	v_bfe_u32 v80, v0, 16, 1
	v_add3_u32 v0, v0, v80, s21
	v_mul_f32_e32 v84, v81, v92
	v_lshrrev_b32_e32 v85, 16, v0
	v_pk_add_f32 v[80:81], v[126:127], v[120:121] op_sel_hi:[1,0] neg_lo:[0,1] neg_hi:[0,1]
	v_mov_b32_e32 v0, v121
	v_pk_mul_f32 v[80:81], v[0:1], v[80:81] op_sel_hi:[0,1]
	v_pk_fma_f32 v[80:81], v[66:67], v[80:81], v[68:69]
	ds_read_b128 v[96:99], v1 offset:4256
	ds_read_b128 v[106:109], v1 offset:4272
	v_mul_f32_e32 v0, 0xbfb8aa3b, v80
	v_exp_f32_e32 v0, v0
	v_mul_f32_e32 v93, 0xbfb8aa3b, v81
	v_exp_f32_e32 v93, v93
	v_bfe_u32 v92, v84, 16, 1
	v_add_f32_e32 v0, 1.0, v0
	s_waitcnt lgkmcnt(1)
	v_pk_add_f32 v[78:79], v[78:79], v[96:97] op_sel_hi:[1,0] neg_lo:[0,1] neg_hi:[0,1]
	v_add3_u32 v84, v84, v92, s21
	v_rcp_f32_e32 v0, v0
	v_add_f32_e32 v92, 1.0, v93
	v_pk_mul_f32 v[78:79], v[96:97], v[78:79] op_sel:[1,0]
	v_rcp_f32_e32 v92, v92
	v_and_or_b32 v84, v84, s19, v85
	v_pk_fma_f32 v[78:79], v[66:67], v[78:79], v[68:69]
	global_store_dword v[88:89], v84, off offset:2176
	v_mul_f32_e32 v84, 0xbfb8aa3b, v78
	v_exp_f32_e32 v84, v84
	v_mul_f32_e32 v0, v80, v0
	v_mul_f32_e32 v80, v81, v92
	v_bfe_u32 v81, v0, 16, 1
	v_mul_f32_e32 v85, 0xbfb8aa3b, v79
	v_add3_u32 v0, v0, v81, s21
	v_bfe_u32 v81, v80, 16, 1
	v_exp_f32_e32 v85, v85
	v_add3_u32 v80, v80, v81, s21
	v_add_f32_e32 v81, 1.0, v84
	v_rcp_f32_e32 v81, v81
	v_lshrrev_b32_e32 v0, 16, v0
	v_add_f32_e32 v84, 1.0, v85
	v_rcp_f32_e32 v84, v84
	v_and_or_b32 v0, v80, s19, v0
	global_store_dword v[88:89], v0, off offset:2240
	v_mul_f32_e32 v0, v78, v81
	v_bfe_u32 v78, v0, 16, 1
	v_add3_u32 v0, v0, v78, s21
	v_mul_f32_e32 v80, v79, v84
	v_lshrrev_b32_e32 v81, 16, v0
	v_pk_add_f32 v[78:79], v[94:95], v[98:99] op_sel_hi:[1,0] neg_lo:[0,1] neg_hi:[0,1]
	v_mov_b32_e32 v0, v99
	v_pk_mul_f32 v[78:79], v[0:1], v[78:79] op_sel_hi:[0,1]
	v_pk_fma_f32 v[78:79], v[66:67], v[78:79], v[68:69]
	v_bfe_u32 v84, v80, 16, 1
	v_mul_f32_e32 v0, 0xbfb8aa3b, v78
	v_exp_f32_e32 v0, v0
	v_mul_f32_e32 v85, 0xbfb8aa3b, v79
	v_exp_f32_e32 v85, v85
	v_add3_u32 v80, v80, v84, s21
	v_add_f32_e32 v0, 1.0, v0
	v_rcp_f32_e32 v0, v0
	v_add_f32_e32 v84, 1.0, v85
	v_rcp_f32_e32 v84, v84
	v_and_or_b32 v80, v80, s19, v81
	v_mul_f32_e32 v0, v78, v0
	v_bfe_u32 v78, v0, 16, 1
	global_store_dword v[88:89], v80, off offset:2304
	v_mul_f32_e32 v80, v79, v84
	v_add3_u32 v0, v0, v78, s21
	s_waitcnt lgkmcnt(0)
	v_pk_add_f32 v[78:79], v[110:111], v[106:107] op_sel_hi:[1,0] neg_lo:[0,1] neg_hi:[0,1]
	v_bfe_u32 v81, v80, 16, 1
	v_pk_mul_f32 v[78:79], v[106:107], v[78:79] op_sel:[1,0]
	v_add3_u32 v80, v80, v81, s21
	v_pk_fma_f32 v[78:79], v[66:67], v[78:79], v[68:69]
	v_lshrrev_b32_e32 v0, 16, v0
	v_mul_f32_e32 v84, 0xbfb8aa3b, v78
	v_exp_f32_e32 v84, v84
	v_mul_f32_e32 v85, 0xbfb8aa3b, v79
	v_exp_f32_e32 v85, v85
	v_and_or_b32 v0, v80, s19, v0
	v_add_f32_e32 v81, 1.0, v84
	v_rcp_f32_e32 v81, v81
	v_add_f32_e32 v84, 1.0, v85
	v_rcp_f32_e32 v84, v84
	global_store_dword v[88:89], v0, off offset:2368
	v_mul_f32_e32 v0, v78, v81
	v_bfe_u32 v78, v0, 16, 1
	v_add3_u32 v0, v0, v78, s21
	v_mul_f32_e32 v80, v79, v84
	v_lshrrev_b32_e32 v81, 16, v0
	v_pk_add_f32 v[78:79], v[122:123], v[108:109] op_sel_hi:[1,0] neg_lo:[0,1] neg_hi:[0,1]
	v_mov_b32_e32 v0, v109
	v_pk_mul_f32 v[78:79], v[0:1], v[78:79] op_sel_hi:[0,1]
	v_pk_fma_f32 v[78:79], v[66:67], v[78:79], v[68:69]
	v_bfe_u32 v84, v80, 16, 1
	v_mul_f32_e32 v0, 0xbfb8aa3b, v78
	v_mul_f32_e32 v85, 0xbfb8aa3b, v79
	v_exp_f32_e32 v0, v0
	v_exp_f32_e32 v85, v85
	v_add3_u32 v80, v80, v84, s21
	v_and_or_b32 v80, v80, s19, v81
	v_add_f32_e32 v0, 1.0, v0
	v_add_f32_e32 v84, 1.0, v85
	v_rcp_f32_e32 v0, v0
	v_rcp_f32_e32 v84, v84
	global_store_dword v[88:89], v80, off offset:2432
	ds_read_b128 v[92:95], v1 offset:4304
	v_mul_f32_e32 v0, v78, v0
	v_mul_f32_e32 v84, v79, v84
	ds_read_b128 v[78:81], v1 offset:4288
	v_bfe_u32 v85, v0, 16, 1
	v_add3_u32 v0, v0, v85, s21
	v_bfe_u32 v85, v84, 16, 1
	v_lshrrev_b32_e32 v0, 16, v0
	s_waitcnt lgkmcnt(0)
; __host__ __device__ __forceinline__ size_t tiled_off(int row, int col, int K) { return ((size_t)(row >> 7) * (K >> 6) + (col >> 6)) * 8192 + (lds_byte(row & 127, col & 63) >> 1); }
; __device__ __forceinline__ float fast_sigmoid(float x) { return __builtin_amdgcn_rcpf(1.0f + __builtin_amdgcn_exp2f(x * -1.4426950408889634f)); }
; __device__ __forceinline__ unsigned pk2(float lo, float hi) { return f2bf(lo) | (f2bf(hi) << 16); }
; __device__ __forceinline__ void conv_phase(const Args& a, LAS unsigned char* lds, int vcu, int G, int tid, int wave, int lane) {
;     ...
;     for (int ch = vcu; ch < M / 32; ch += G) {
;     ...
;         for (int i = 0; i < 32; ++i) { const f32x2 st = stat[i]; f32x2 y = (o[i] - st.x) * st.y * g2 + b2;
;             y.x = y.x * pg8::fast_sigmoid(y.x); y.y = y.y * pg8::fast_sigmoid(y.y);
;             *(unsigned*)(V2 + pg8::tiled_off(t0 + i, c0, D)) = pk2(y.x, y.y); }
;         __syncthreads();
	v_pk_add_f32 v[76:77], v[76:77], v[78:79] op_sel_hi:[1,0] neg_lo:[0,1] neg_hi:[0,1]
	v_add3_u32 v84, v84, v85, s21
	v_pk_mul_f32 v[76:77], v[78:79], v[76:77] op_sel:[1,0]
	v_and_or_b32 v0, v84, s19, v0
	v_pk_fma_f32 v[76:77], v[66:67], v[76:77], v[68:69]
	global_store_dword v[88:89], v0, off offset:2496
	v_mul_f32_e32 v78, 0xbfb8aa3b, v76
	v_exp_f32_e32 v78, v78
	v_mul_f32_e32 v79, 0xbfb8aa3b, v77
	v_exp_f32_e32 v79, v79
	v_readlane_b32 s17, v255, 5
	v_add_f32_e32 v78, 1.0, v78
	v_rcp_f32_e32 v78, v78
	v_add_f32_e32 v79, 1.0, v79
	v_rcp_f32_e32 v79, v79
	v_mul_f32_e32 v0, v76, v78
	v_bfe_u32 v76, v0, 16, 1
	v_add3_u32 v0, v0, v76, s21
	v_mul_f32_e32 v78, v77, v79
	v_lshrrev_b32_e32 v79, 16, v0
	v_pk_add_f32 v[76:77], v[86:87], v[80:81] op_sel_hi:[1,0] neg_lo:[0,1] neg_hi:[0,1]
	v_mov_b32_e32 v0, v81
	v_pk_mul_f32 v[76:77], v[0:1], v[76:77] op_sel_hi:[0,1]
	v_pk_fma_f32 v[76:77], v[66:67], v[76:77], v[68:69]
	v_bfe_u32 v84, v78, 16, 1
	v_mul_f32_e32 v0, 0xbfb8aa3b, v76
	v_exp_f32_e32 v0, v0
	v_mul_f32_e32 v80, 0xbfb8aa3b, v77
	v_exp_f32_e32 v80, v80
	v_add3_u32 v78, v78, v84, s21
	v_add_f32_e32 v0, 1.0, v0
	v_rcp_f32_e32 v0, v0
	v_add_f32_e32 v80, 1.0, v80
	v_rcp_f32_e32 v80, v80
	v_and_or_b32 v78, v78, s19, v79
	v_mul_f32_e32 v0, v76, v0
	v_bfe_u32 v76, v0, 16, 1
	global_store_dword v[90:91], v78, off offset:2560
	v_mul_f32_e32 v78, v77, v80
	v_add3_u32 v0, v0, v76, s21
	v_pk_add_f32 v[76:77], v[104:105], v[92:93] op_sel_hi:[1,0] neg_lo:[0,1] neg_hi:[0,1]
	v_bfe_u32 v79, v78, 16, 1
	v_pk_mul_f32 v[76:77], v[92:93], v[76:77] op_sel:[1,0]
	v_add3_u32 v78, v78, v79, s21
	v_pk_fma_f32 v[76:77], v[66:67], v[76:77], v[68:69]
	v_lshrrev_b32_e32 v0, 16, v0
	v_mul_f32_e32 v80, 0xbfb8aa3b, v76
	v_exp_f32_e32 v80, v80
	v_mul_f32_e32 v81, 0xbfb8aa3b, v77
	v_exp_f32_e32 v81, v81
	v_and_or_b32 v0, v78, s19, v0
	v_add_f32_e32 v79, 1.0, v80
	v_rcp_f32_e32 v79, v79
	v_add_f32_e32 v80, 1.0, v81
	v_rcp_f32_e32 v80, v80
	global_store_dword v[90:91], v0, off offset:2624
	v_mul_f32_e32 v0, v76, v79
	v_bfe_u32 v76, v0, 16, 1
	v_add3_u32 v0, v0, v76, s21
	v_mul_f32_e32 v78, v77, v80
	v_lshrrev_b32_e32 v79, 16, v0
	v_pk_add_f32 v[76:77], v[116:117], v[94:95] op_sel_hi:[1,0] neg_lo:[0,1] neg_hi:[0,1]
	v_mov_b32_e32 v0, v95
	v_pk_mul_f32 v[76:77], v[0:1], v[76:77] op_sel_hi:[0,1]
	v_pk_fma_f32 v[76:77], v[66:67], v[76:77], v[68:69]
	v_bfe_u32 v80, v78, 16, 1
	v_mul_f32_e32 v0, 0xbfb8aa3b, v76
	v_mul_f32_e32 v81, 0xbfb8aa3b, v77
	v_exp_f32_e32 v0, v0
	v_exp_f32_e32 v81, v81
	v_add3_u32 v78, v78, v80, s21
	v_and_or_b32 v78, v78, s19, v79
	v_add_f32_e32 v0, 1.0, v0
	v_add_f32_e32 v80, 1.0, v81
	v_rcp_f32_e32 v0, v0
	v_rcp_f32_e32 v80, v80
	global_store_dword v[90:91], v78, off offset:2688
	ds_read_b128 v[84:87], v1 offset:4336
	v_mul_f32_e32 v0, v76, v0
	v_mul_f32_e32 v80, v77, v80
	ds_read_b128 v[76:79], v1 offset:4320
	v_bfe_u32 v81, v0, 16, 1
	v_add3_u32 v0, v0, v81, s21
	v_bfe_u32 v81, v80, 16, 1
	v_lshrrev_b32_e32 v0, 16, v0
	s_waitcnt lgkmcnt(0)
	v_pk_add_f32 v[74:75], v[74:75], v[76:77] op_sel_hi:[1,0] neg_lo:[0,1] neg_hi:[0,1]
	v_add3_u32 v80, v80, v81, s21
	v_pk_mul_f32 v[74:75], v[76:77], v[74:75] op_sel:[1,0]
	v_and_or_b32 v0, v80, s19, v0
	v_pk_fma_f32 v[74:75], v[66:67], v[74:75], v[68:69]
	global_store_dword v[90:91], v0, off offset:2752
	v_mul_f32_e32 v76, 0xbfb8aa3b, v74
	v_exp_f32_e32 v76, v76
	v_mul_f32_e32 v77, 0xbfb8aa3b, v75
	v_exp_f32_e32 v77, v77
	v_add_f32_e32 v76, 1.0, v76
	v_rcp_f32_e32 v76, v76
	v_add_f32_e32 v77, 1.0, v77
	v_rcp_f32_e32 v77, v77
	v_mul_f32_e32 v0, v74, v76
	v_bfe_u32 v74, v0, 16, 1
	v_add3_u32 v0, v0, v74, s21
	v_mul_f32_e32 v76, v75, v77
	v_lshrrev_b32_e32 v77, 16, v0
	v_pk_add_f32 v[74:75], v[82:83], v[78:79] op_sel_hi:[1,0] neg_lo:[0,1] neg_hi:[0,1]
	v_mov_b32_e32 v0, v79
	v_pk_mul_f32 v[74:75], v[0:1], v[74:75] op_sel_hi:[0,1]
	v_pk_fma_f32 v[74:75], v[66:67], v[74:75], v[68:69]
	v_bfe_u32 v80, v76, 16, 1
	v_mul_f32_e32 v0, 0xbfb8aa3b, v74
	v_exp_f32_e32 v0, v0
	v_mul_f32_e32 v78, 0xbfb8aa3b, v75
	v_exp_f32_e32 v78, v78
	v_add3_u32 v76, v76, v80, s21
	v_add_f32_e32 v0, 1.0, v0
	v_rcp_f32_e32 v0, v0
	v_add_f32_e32 v78, 1.0, v78
	v_rcp_f32_e32 v78, v78
	v_and_or_b32 v76, v76, s19, v77
	v_mul_f32_e32 v0, v74, v0
	v_bfe_u32 v74, v0, 16, 1
	global_store_dword v[90:91], v76, off offset:2816
	v_mul_f32_e32 v76, v75, v78
	v_add3_u32 v0, v0, v74, s21
	v_pk_add_f32 v[74:75], v[100:101], v[84:85] op_sel_hi:[1,0] neg_lo:[0,1] neg_hi:[0,1]
	v_bfe_u32 v77, v76, 16, 1
	v_pk_mul_f32 v[74:75], v[84:85], v[74:75] op_sel:[1,0]
	v_add3_u32 v76, v76, v77, s21
	v_pk_fma_f32 v[74:75], v[66:67], v[74:75], v[68:69]
	v_lshrrev_b32_e32 v0, 16, v0
	v_mul_f32_e32 v78, 0xbfb8aa3b, v74
	v_exp_f32_e32 v78, v78
	v_mul_f32_e32 v79, 0xbfb8aa3b, v75
	v_exp_f32_e32 v79, v79
	v_and_or_b32 v0, v76, s19, v0
	v_add_f32_e32 v77, 1.0, v78
	v_rcp_f32_e32 v77, v77
	v_add_f32_e32 v78, 1.0, v79
	v_rcp_f32_e32 v78, v78
	global_store_dword v[90:91], v0, off offset:2880
	v_mul_f32_e32 v0, v74, v77
	v_bfe_u32 v74, v0, 16, 1
	v_add3_u32 v0, v0, v74, s21
	v_mul_f32_e32 v76, v75, v78
	v_lshrrev_b32_e32 v77, 16, v0
	v_pk_add_f32 v[74:75], v[112:113], v[86:87] op_sel_hi:[1,0] neg_lo:[0,1] neg_hi:[0,1]
	v_mov_b32_e32 v0, v87
	v_pk_mul_f32 v[74:75], v[0:1], v[74:75] op_sel_hi:[0,1]
	v_pk_fma_f32 v[74:75], v[66:67], v[74:75], v[68:69]
	v_bfe_u32 v78, v76, 16, 1
	v_mul_f32_e32 v0, 0xbfb8aa3b, v74
	v_exp_f32_e32 v0, v0
	v_mul_f32_e32 v79, 0xbfb8aa3b, v75
	v_exp_f32_e32 v79, v79
	v_add3_u32 v76, v76, v78, s21
	v_add_f32_e32 v0, 1.0, v0
	v_rcp_f32_e32 v0, v0
	v_add_f32_e32 v78, 1.0, v79
	v_rcp_f32_e32 v78, v78
	v_and_or_b32 v76, v76, s19, v77
	v_mul_f32_e32 v0, v74, v0
	global_store_dword v[90:91], v76, off offset:2944
	v_mul_f32_e32 v74, v75, v78
	v_bfe_u32 v75, v0, 16, 1
	v_add3_u32 v0, v0, v75, s21
	v_bfe_u32 v75, v74, 16, 1
	v_lshrrev_b32_e32 v0, 16, v0
	v_add3_u32 v74, v74, v75, s21
	v_and_or_b32 v0, v74, s19, v0
	global_store_dword v[90:91], v0, off offset:3008
	s_barrier
	s_cbranch_scc0 .LBB0_619
